# compiler prep_conv bodies removed (unreachable), otherwise as the previous version
# baseline (speedup 1.0000x reference)
.Lgm_f1_cnt:
	s_add_u32 s30, s30, 16
	s_add_u32 s4, s4, s52
	s_cmp_lt_u32 s4, s54
	s_cbranch_scc1 .Lgm_f1_cnt
	s_add_u32 s48, s96, 0x2e24000
	s_addc_u32 s49, s97, 0
	s_mul_i32 s4, s36, 0x800000
	s_add_u32 s50, s96, 0xd80000
	s_addc_u32 s51, s97, 0
	s_add_u32 s50, s50, s4
	s_addc_u32 s51, s51, 0
	v_and_b32_e32 v0, 63, v206
	v_lshrrev_b32_e32 v1, 6, v206
	s_mov_b32 s31, 0
	v_readfirstlane_b32 s42, v1
	s_nop 0
	s_cmp_ge_u32 s42, 4
	s_cbranch_scc1 .Lgm_f1_compute
	v_lshrrev_b32_e32 v3, 3, v0
	v_and_b32_e32 v4, 7, v0
	v_xor_b32_e32 v4, v4, v3
	v_lshl_add_u32 v3, v1, 3, v3
	v_lshlrev_b32_e32 v3, 11, v3
	v_lshl_add_u32 v180, v4, 4, v3
	v_add_u32_e32 v181, 0x10000, v180
	v_add_u32_e32 v182, 0x20000, v180
	v_add_u32_e32 v183, 0x30000, v180
	v_add_u32_e32 v184, 0x40000, v180
	v_add_u32_e32 v185, 0x50000, v180
	s_lshl_b32 s42, s42, 10
	s_mov_b32 s38, s53
	s_mov_b32 s39, 0
	s_mov_b32 s41, s42
	s_and_b32 s4, s38, 31
	s_lshr_b32 s5, s38, 5
	s_mul_i32 s4, s4, 0x60000
	s_add_u32 s44, s48, s4
	s_addc_u32 s45, s49, 0
	s_mul_i32 s4, s5, 0x40000
	s_add_u32 s46, s50, s4
	s_addc_u32 s47, s51, 0
	s_add_u32 m0, s41, 0x0
	s_nop 0
	global_load_lds_dwordx4 v180, s[44:45]
	s_add_u32 m0, s41, 0x1000
	s_nop 0
	global_load_lds_dwordx4 v181, s[44:45]
	s_add_u32 m0, s41, 0x2000
	s_nop 0
	global_load_lds_dwordx4 v182, s[44:45]
	s_add_u32 m0, s41, 0x3000
	s_nop 0
	global_load_lds_dwordx4 v183, s[44:45]
	s_add_u32 m0, s41, 0x4000
	s_nop 0
	global_load_lds_dwordx4 v184, s[44:45]
	s_add_u32 m0, s41, 0x5000
	s_nop 0
	global_load_lds_dwordx4 v185, s[44:45]
	s_add_u32 m0, s41, 0x6000
	s_nop 0
	global_load_lds_dwordx4 v180, s[46:47]
	s_add_u32 m0, s41, 0x7000
	s_nop 0
	global_load_lds_dwordx4 v181, s[46:47]
	s_add_u32 m0, s41, 0x8000
	s_nop 0
	global_load_lds_dwordx4 v182, s[46:47]
	s_add_u32 m0, s41, 0x9000
	s_nop 0
	global_load_lds_dwordx4 v183, s[46:47]
	s_add_u32 s39, s39, 1
	s_add_u32 s44, s44, 0x80
	s_addc_u32 s45, s45, 0
	s_add_u32 s46, s46, 0x80
	s_addc_u32 s47, s47, 0
	s_cmp_lt_u32 s39, 16
	s_cbranch_scc1 .Lgm_f1_dadv1
	s_mov_b32 s39, 0
	s_add_u32 s4, s38, s52
	s_cmp_lt_u32 s4, s54
	s_cselect_b32 s38, s4, s38
	s_and_b32 s4, s38, 31
	s_lshr_b32 s5, s38, 5
	s_mul_i32 s4, s4, 0x60000
	s_add_u32 s44, s48, s4
	s_addc_u32 s45, s49, 0
	s_mul_i32 s4, s5, 0x40000
	s_add_u32 s46, s50, s4
	s_addc_u32 s47, s51, 0
.Lgm_f1_dadv1:
	s_add_u32 s41, s41, 0xa000
	s_sub_u32 s4, s41, 0x1e000
	s_cmp_ge_u32 s41, 0x1e000
	s_cselect_b32 s41, s4, s41
	s_add_u32 m0, s41, 0x0
	s_nop 0
	global_load_lds_dwordx4 v180, s[44:45]
	s_add_u32 m0, s41, 0x1000
	s_nop 0
	global_load_lds_dwordx4 v181, s[44:45]
	s_add_u32 m0, s41, 0x2000
	s_nop 0
	global_load_lds_dwordx4 v182, s[44:45]
	s_add_u32 m0, s41, 0x3000
	s_nop 0
	global_load_lds_dwordx4 v183, s[44:45]
	s_add_u32 m0, s41, 0x4000
	s_nop 0
	global_load_lds_dwordx4 v184, s[44:45]
	s_add_u32 m0, s41, 0x5000
	s_nop 0
	global_load_lds_dwordx4 v185, s[44:45]
	s_add_u32 m0, s41, 0x6000
	s_nop 0
	global_load_lds_dwordx4 v180, s[46:47]
	s_add_u32 m0, s41, 0x7000
	s_nop 0
	global_load_lds_dwordx4 v181, s[46:47]
	s_add_u32 m0, s41, 0x8000
	s_nop 0
	global_load_lds_dwordx4 v182, s[46:47]
	s_add_u32 m0, s41, 0x9000
	s_nop 0
	global_load_lds_dwordx4 v183, s[46:47]
	s_add_u32 s39, s39, 1
	s_add_u32 s44, s44, 0x80
	s_addc_u32 s45, s45, 0
	s_add_u32 s46, s46, 0x80
	s_addc_u32 s47, s47, 0
	s_cmp_lt_u32 s39, 16
	s_cbranch_scc1 .Lgm_f1_dadv2
	s_mov_b32 s39, 0
	s_add_u32 s4, s38, s52
	s_cmp_lt_u32 s4, s54
	s_cselect_b32 s38, s4, s38
	s_and_b32 s4, s38, 31
	s_lshr_b32 s5, s38, 5
	s_mul_i32 s4, s4, 0x60000
	s_add_u32 s44, s48, s4
	s_addc_u32 s45, s49, 0
	s_mul_i32 s4, s5, 0x40000
	s_add_u32 s46, s50, s4
	s_addc_u32 s47, s51, 0

.Lgm_f1_ld_loop:
	s_barrier
	s_add_u32 m0, s41, 0x0
	s_nop 0
	global_load_lds_dwordx4 v180, s[44:45]
	s_add_u32 m0, s41, 0x1000
	s_nop 0
	global_load_lds_dwordx4 v181, s[44:45]
	s_add_u32 m0, s41, 0x2000
	s_nop 0
	global_load_lds_dwordx4 v182, s[44:45]
	s_add_u32 m0, s41, 0x3000
	s_nop 0
	global_load_lds_dwordx4 v183, s[44:45]
	s_add_u32 m0, s41, 0x4000
	s_nop 0
	global_load_lds_dwordx4 v184, s[44:45]
	s_add_u32 m0, s41, 0x5000
	s_nop 0
	global_load_lds_dwordx4 v185, s[44:45]
	s_add_u32 m0, s41, 0x6000
	s_nop 0
	global_load_lds_dwordx4 v180, s[46:47]
	s_add_u32 m0, s41, 0x7000
	s_nop 0
	global_load_lds_dwordx4 v181, s[46:47]
	s_add_u32 m0, s41, 0x8000
	s_nop 0
	global_load_lds_dwordx4 v182, s[46:47]
	s_add_u32 m0, s41, 0x9000
	s_nop 0
	global_load_lds_dwordx4 v183, s[46:47]
	s_add_u32 s39, s39, 1
	s_add_u32 s44, s44, 0x80
	s_addc_u32 s45, s45, 0
	s_add_u32 s46, s46, 0x80
	s_addc_u32 s47, s47, 0
	s_cmp_lt_u32 s39, 16
	s_cbranch_scc1 .Lgm_f1_dadv3
	s_mov_b32 s39, 0
	s_add_u32 s4, s38, s52
	s_cmp_lt_u32 s4, s54
	s_cselect_b32 s38, s4, s38
	s_and_b32 s4, s38, 31
	s_lshr_b32 s5, s38, 5
	s_mul_i32 s4, s4, 0x60000
	s_add_u32 s44, s48, s4
	s_addc_u32 s45, s49, 0
	s_mul_i32 s4, s5, 0x40000
	s_add_u32 s46, s50, s4
	s_addc_u32 s47, s51, 0

.Lgm_f1_join:
	s_waitcnt lgkmcnt(13)
	v_mfma_f32_16x16x32_bf16 v[4:7], v[100:103], v[124:127], v[4:7]
	v_mfma_f32_16x16x32_bf16 v[20:23], v[104:107], v[124:127], v[20:23]
	v_mfma_f32_16x16x32_bf16 v[36:39], v[108:111], v[124:127], v[36:39]
	v_mfma_f32_16x16x32_bf16 v[52:55], v[112:115], v[124:127], v[52:55]
	v_mfma_f32_16x16x32_bf16 v[68:71], v[116:119], v[124:127], v[68:71]
	v_mfma_f32_16x16x32_bf16 v[84:87], v[120:123], v[124:127], v[84:87]
	s_waitcnt lgkmcnt(12)
	v_mfma_f32_16x16x32_bf16 v[8:11], v[100:103], v[128:131], v[8:11]
	v_mfma_f32_16x16x32_bf16 v[24:27], v[104:107], v[128:131], v[24:27]
	v_mfma_f32_16x16x32_bf16 v[40:43], v[108:111], v[128:131], v[40:43]
	v_mfma_f32_16x16x32_bf16 v[56:59], v[112:115], v[128:131], v[56:59]
	v_mfma_f32_16x16x32_bf16 v[72:75], v[116:119], v[128:131], v[72:75]
	v_mfma_f32_16x16x32_bf16 v[88:91], v[120:123], v[128:131], v[88:91]
	s_waitcnt lgkmcnt(11)
	v_mfma_f32_16x16x32_bf16 v[12:15], v[100:103], v[132:135], v[12:15]
	v_mfma_f32_16x16x32_bf16 v[28:31], v[104:107], v[132:135], v[28:31]
	v_mfma_f32_16x16x32_bf16 v[44:47], v[108:111], v[132:135], v[44:47]
	v_mfma_f32_16x16x32_bf16 v[60:63], v[112:115], v[132:135], v[60:63]
	v_mfma_f32_16x16x32_bf16 v[76:79], v[116:119], v[132:135], v[76:79]
	v_mfma_f32_16x16x32_bf16 v[92:95], v[120:123], v[132:135], v[92:95]
	s_waitcnt lgkmcnt(10)
	v_mfma_f32_16x16x32_bf16 v[16:19], v[100:103], v[136:139], v[16:19]
	v_mfma_f32_16x16x32_bf16 v[32:35], v[104:107], v[136:139], v[32:35]
	v_mfma_f32_16x16x32_bf16 v[48:51], v[108:111], v[136:139], v[48:51]
	v_mfma_f32_16x16x32_bf16 v[64:67], v[112:115], v[136:139], v[64:67]
	v_mfma_f32_16x16x32_bf16 v[80:83], v[116:119], v[136:139], v[80:83]
	v_mfma_f32_16x16x32_bf16 v[96:99], v[120:123], v[136:139], v[96:99]
	s_waitcnt lgkmcnt(0)
	s_add_u32 s34, s34, 1
	s_add_u32 s31, s31, 1
	s_cmp_lt_u32 s34, 16
	s_cbranch_scc1 .Lgm_f1_rot
	v_mfma_f32_16x16x32_bf16 v[4:7], v[140:143], v[164:167], v[4:7]
	v_mfma_f32_16x16x32_bf16 v[20:23], v[144:147], v[164:167], v[20:23]
	v_mfma_f32_16x16x32_bf16 v[36:39], v[148:151], v[164:167], v[36:39]
	v_mfma_f32_16x16x32_bf16 v[52:55], v[152:155], v[164:167], v[52:55]
	v_mfma_f32_16x16x32_bf16 v[68:71], v[156:159], v[164:167], v[68:71]
	v_mfma_f32_16x16x32_bf16 v[84:87], v[160:163], v[164:167], v[84:87]
	v_mfma_f32_16x16x32_bf16 v[8:11], v[140:143], v[168:171], v[8:11]
	v_mfma_f32_16x16x32_bf16 v[24:27], v[144:147], v[168:171], v[24:27]
	v_mfma_f32_16x16x32_bf16 v[40:43], v[148:151], v[168:171], v[40:43]
	v_mfma_f32_16x16x32_bf16 v[56:59], v[152:155], v[168:171], v[56:59]
	v_mfma_f32_16x16x32_bf16 v[72:75], v[156:159], v[168:171], v[72:75]
	v_mfma_f32_16x16x32_bf16 v[88:91], v[160:163], v[168:171], v[88:91]
	v_mfma_f32_16x16x32_bf16 v[12:15], v[140:143], v[172:175], v[12:15]
	v_mfma_f32_16x16x32_bf16 v[28:31], v[144:147], v[172:175], v[28:31]
	v_mfma_f32_16x16x32_bf16 v[44:47], v[148:151], v[172:175], v[44:47]
	v_mfma_f32_16x16x32_bf16 v[60:63], v[152:155], v[172:175], v[60:63]
	v_mfma_f32_16x16x32_bf16 v[76:79], v[156:159], v[172:175], v[76:79]
	v_mfma_f32_16x16x32_bf16 v[92:95], v[160:163], v[172:175], v[92:95]
	v_mfma_f32_16x16x32_bf16 v[16:19], v[140:143], v[176:179], v[16:19]
	v_mfma_f32_16x16x32_bf16 v[32:35], v[144:147], v[176:179], v[32:35]
	v_mfma_f32_16x16x32_bf16 v[48:51], v[148:151], v[176:179], v[48:51]
	v_mfma_f32_16x16x32_bf16 v[64:67], v[152:155], v[176:179], v[64:67]
	v_mfma_f32_16x16x32_bf16 v[80:83], v[156:159], v[176:179], v[80:83]
	v_mfma_f32_16x16x32_bf16 v[96:99], v[160:163], v[176:179], v[96:99]
	s_and_b32 s6, s35, 31
	s_lshr_b32 s7, s35, 5
	s_mul_i32 s6, s6, 192
	s_lshl_b32 s7, s7, 7
	s_nop 7
	s_mul_i32 s4, s6, 0x2000
	s_lshl_b32 s5, s7, 1
	s_add_u32 s4, s4, s5
	v_add_u32_e32 v197, s4, v205
	ds_write_b32 v203, v4 offset:0
	ds_write_b32 v203, v5 offset:272
	ds_write_b32 v203, v6 offset:544
	ds_write_b32 v203, v7 offset:816
	ds_write_b32 v203, v8 offset:64
	ds_write_b32 v203, v9 offset:336
	ds_write_b32 v203, v10 offset:608
	ds_write_b32 v203, v11 offset:880
	ds_write_b32 v203, v12 offset:128
	ds_write_b32 v203, v13 offset:400
	ds_write_b32 v203, v14 offset:672
	ds_write_b32 v203, v15 offset:944
	ds_write_b32 v203, v16 offset:192
	ds_write_b32 v203, v17 offset:464
	ds_write_b32 v203, v18 offset:736
	ds_write_b32 v203, v19 offset:1008
	s_waitcnt lgkmcnt(0)
	ds_read_b128 v[156:159], v204 offset:0
	ds_read_b128 v[160:163], v204 offset:1088
	ds_read_b128 v[164:167], v204 offset:2176
	ds_read_b128 v[168:171], v204 offset:3264
	s_waitcnt lgkmcnt(3)
	v_max_f32_e32 v156, 0, v156
	v_max_f32_e32 v157, 0, v157
	v_max_f32_e32 v158, 0, v158
	v_max_f32_e32 v159, 0, v159
	v_mul_f32_e32 v156, v156, v156
	v_mul_f32_e32 v157, v157, v157
	v_mul_f32_e32 v158, v158, v158
	v_mul_f32_e32 v159, v159, v159
	v_cvt_pk_bf16_f32 v176, v156, v157
	v_cvt_pk_bf16_f32 v177, v158, v159
	global_store_dwordx2 v197, v[176:177], s[56:57] sc0 sc1
	v_add_u32_e32 v197, 0x8000, v197
	s_waitcnt lgkmcnt(2)
	v_max_f32_e32 v160, 0, v160
	v_max_f32_e32 v161, 0, v161
	v_max_f32_e32 v162, 0, v162
	v_max_f32_e32 v163, 0, v163
	v_mul_f32_e32 v160, v160, v160
	v_mul_f32_e32 v161, v161, v161
	v_mul_f32_e32 v162, v162, v162
	v_mul_f32_e32 v163, v163, v163
	v_cvt_pk_bf16_f32 v178, v160, v161
	v_cvt_pk_bf16_f32 v179, v162, v163
	global_store_dwordx2 v197, v[178:179], s[56:57] sc0 sc1
	v_add_u32_e32 v197, 0x8000, v197
	s_waitcnt lgkmcnt(1)
	v_max_f32_e32 v164, 0, v164
	v_max_f32_e32 v165, 0, v165
	v_max_f32_e32 v166, 0, v166
	v_max_f32_e32 v167, 0, v167
	v_mul_f32_e32 v164, v164, v164
	v_mul_f32_e32 v165, v165, v165
	v_mul_f32_e32 v166, v166, v166
	v_mul_f32_e32 v167, v167, v167
	v_cvt_pk_bf16_f32 v176, v164, v165
	v_cvt_pk_bf16_f32 v177, v166, v167
	global_store_dwordx2 v197, v[176:177], s[56:57] sc0 sc1
	v_add_u32_e32 v197, 0x8000, v197
	s_waitcnt lgkmcnt(0)
	v_max_f32_e32 v168, 0, v168
	v_max_f32_e32 v169, 0, v169
	v_max_f32_e32 v170, 0, v170
	v_max_f32_e32 v171, 0, v171
	v_mul_f32_e32 v168, v168, v168
	v_mul_f32_e32 v169, v169, v169
	v_mul_f32_e32 v170, v170, v170
	v_mul_f32_e32 v171, v171, v171
	v_cvt_pk_bf16_f32 v178, v168, v169
	v_cvt_pk_bf16_f32 v179, v170, v171
	global_store_dwordx2 v197, v[178:179], s[56:57] sc0 sc1
	v_add_u32_e32 v197, 0x8000, v197
	ds_write_b32 v203, v20 offset:0
	ds_write_b32 v203, v21 offset:272
	ds_write_b32 v203, v22 offset:544
	ds_write_b32 v203, v23 offset:816
	ds_write_b32 v203, v24 offset:64
	ds_write_b32 v203, v25 offset:336
	ds_write_b32 v203, v26 offset:608
	ds_write_b32 v203, v27 offset:880
	ds_write_b32 v203, v28 offset:128
	ds_write_b32 v203, v29 offset:400
	ds_write_b32 v203, v30 offset:672
	ds_write_b32 v203, v31 offset:944
	ds_write_b32 v203, v32 offset:192
	ds_write_b32 v203, v33 offset:464
	ds_write_b32 v203, v34 offset:736
	ds_write_b32 v203, v35 offset:1008
	s_waitcnt lgkmcnt(0)
	ds_read_b128 v[156:159], v204 offset:0
	ds_read_b128 v[160:163], v204 offset:1088
	ds_read_b128 v[164:167], v204 offset:2176
	ds_read_b128 v[168:171], v204 offset:3264
	s_waitcnt lgkmcnt(3)
	v_max_f32_e32 v156, 0, v156
	v_max_f32_e32 v157, 0, v157
	v_max_f32_e32 v158, 0, v158
	v_max_f32_e32 v159, 0, v159
	v_mul_f32_e32 v156, v156, v156
	v_mul_f32_e32 v157, v157, v157
	v_mul_f32_e32 v158, v158, v158
	v_mul_f32_e32 v159, v159, v159
	v_cvt_pk_bf16_f32 v176, v156, v157
	v_cvt_pk_bf16_f32 v177, v158, v159
	global_store_dwordx2 v197, v[176:177], s[56:57] sc0 sc1
	v_add_u32_e32 v197, 0x8000, v197
	s_waitcnt lgkmcnt(2)
	v_max_f32_e32 v160, 0, v160
	v_max_f32_e32 v161, 0, v161
	v_max_f32_e32 v162, 0, v162
	v_max_f32_e32 v163, 0, v163
	v_mul_f32_e32 v160, v160, v160
	v_mul_f32_e32 v161, v161, v161
	v_mul_f32_e32 v162, v162, v162
	v_mul_f32_e32 v163, v163, v163
	v_cvt_pk_bf16_f32 v178, v160, v161
	v_cvt_pk_bf16_f32 v179, v162, v163
	global_store_dwordx2 v197, v[178:179], s[56:57] sc0 sc1
	v_add_u32_e32 v197, 0x8000, v197
	s_waitcnt lgkmcnt(1)
	v_max_f32_e32 v164, 0, v164
	v_max_f32_e32 v165, 0, v165
	v_max_f32_e32 v166, 0, v166
	v_max_f32_e32 v167, 0, v167
	v_mul_f32_e32 v164, v164, v164
	v_mul_f32_e32 v165, v165, v165
	v_mul_f32_e32 v166, v166, v166
	v_mul_f32_e32 v167, v167, v167
	v_cvt_pk_bf16_f32 v176, v164, v165
	v_cvt_pk_bf16_f32 v177, v166, v167
	global_store_dwordx2 v197, v[176:177], s[56:57] sc0 sc1
	v_add_u32_e32 v197, 0x8000, v197
	s_waitcnt lgkmcnt(0)
	v_max_f32_e32 v168, 0, v168
	v_max_f32_e32 v169, 0, v169
	v_max_f32_e32 v170, 0, v170
	v_max_f32_e32 v171, 0, v171
	v_mul_f32_e32 v168, v168, v168
	v_mul_f32_e32 v169, v169, v169
	v_mul_f32_e32 v170, v170, v170
	v_mul_f32_e32 v171, v171, v171
	v_cvt_pk_bf16_f32 v178, v168, v169
	v_cvt_pk_bf16_f32 v179, v170, v171
	global_store_dwordx2 v197, v[178:179], s[56:57] sc0 sc1
	v_add_u32_e32 v197, 0x8000, v197
	ds_write_b32 v203, v36 offset:0
	ds_write_b32 v203, v37 offset:272
	ds_write_b32 v203, v38 offset:544
	ds_write_b32 v203, v39 offset:816
	ds_write_b32 v203, v40 offset:64
	ds_write_b32 v203, v41 offset:336
	ds_write_b32 v203, v42 offset:608
	ds_write_b32 v203, v43 offset:880
	ds_write_b32 v203, v44 offset:128
	ds_write_b32 v203, v45 offset:400
	ds_write_b32 v203, v46 offset:672
	ds_write_b32 v203, v47 offset:944
	ds_write_b32 v203, v48 offset:192
	ds_write_b32 v203, v49 offset:464
	ds_write_b32 v203, v50 offset:736
	ds_write_b32 v203, v51 offset:1008
	s_waitcnt lgkmcnt(0)
	ds_read_b128 v[156:159], v204 offset:0
	ds_read_b128 v[160:163], v204 offset:1088
	ds_read_b128 v[164:167], v204 offset:2176
	ds_read_b128 v[168:171], v204 offset:3264
	s_waitcnt lgkmcnt(3)
	v_max_f32_e32 v156, 0, v156
	v_max_f32_e32 v157, 0, v157
	v_max_f32_e32 v158, 0, v158
	v_max_f32_e32 v159, 0, v159
	v_mul_f32_e32 v156, v156, v156
	v_mul_f32_e32 v157, v157, v157
	v_mul_f32_e32 v158, v158, v158
	v_mul_f32_e32 v159, v159, v159
	v_cvt_pk_bf16_f32 v176, v156, v157
	v_cvt_pk_bf16_f32 v177, v158, v159
	global_store_dwordx2 v197, v[176:177], s[56:57] sc0 sc1
	v_add_u32_e32 v197, 0x8000, v197
	s_waitcnt lgkmcnt(2)
	v_max_f32_e32 v160, 0, v160
	v_max_f32_e32 v161, 0, v161
	v_max_f32_e32 v162, 0, v162
	v_max_f32_e32 v163, 0, v163
	v_mul_f32_e32 v160, v160, v160
	v_mul_f32_e32 v161, v161, v161
	v_mul_f32_e32 v162, v162, v162
	v_mul_f32_e32 v163, v163, v163
	v_cvt_pk_bf16_f32 v178, v160, v161
	v_cvt_pk_bf16_f32 v179, v162, v163
	global_store_dwordx2 v197, v[178:179], s[56:57] sc0 sc1
	v_add_u32_e32 v197, 0x8000, v197
	s_waitcnt lgkmcnt(1)
	v_max_f32_e32 v164, 0, v164
	v_max_f32_e32 v165, 0, v165
	v_max_f32_e32 v166, 0, v166
	v_max_f32_e32 v167, 0, v167
	v_mul_f32_e32 v164, v164, v164
	v_mul_f32_e32 v165, v165, v165
	v_mul_f32_e32 v166, v166, v166
	v_mul_f32_e32 v167, v167, v167
	v_cvt_pk_bf16_f32 v176, v164, v165
	v_cvt_pk_bf16_f32 v177, v166, v167
	global_store_dwordx2 v197, v[176:177], s[56:57] sc0 sc1
	v_add_u32_e32 v197, 0x8000, v197
	s_waitcnt lgkmcnt(0)
	v_max_f32_e32 v168, 0, v168
	v_max_f32_e32 v169, 0, v169
	v_max_f32_e32 v170, 0, v170
	v_max_f32_e32 v171, 0, v171
	v_mul_f32_e32 v168, v168, v168
	v_mul_f32_e32 v169, v169, v169
	v_mul_f32_e32 v170, v170, v170
	v_mul_f32_e32 v171, v171, v171
	v_cvt_pk_bf16_f32 v178, v168, v169
	v_cvt_pk_bf16_f32 v179, v170, v171
	global_store_dwordx2 v197, v[178:179], s[56:57] sc0 sc1
	v_add_u32_e32 v197, 0x8000, v197
	ds_write_b32 v203, v52 offset:0
	ds_write_b32 v203, v53 offset:272
	ds_write_b32 v203, v54 offset:544
	ds_write_b32 v203, v55 offset:816
	ds_write_b32 v203, v56 offset:64
	ds_write_b32 v203, v57 offset:336
	ds_write_b32 v203, v58 offset:608
	ds_write_b32 v203, v59 offset:880
	ds_write_b32 v203, v60 offset:128
	ds_write_b32 v203, v61 offset:400
	ds_write_b32 v203, v62 offset:672
	ds_write_b32 v203, v63 offset:944
	ds_write_b32 v203, v64 offset:192
	ds_write_b32 v203, v65 offset:464
	ds_write_b32 v203, v66 offset:736
	ds_write_b32 v203, v67 offset:1008
	s_waitcnt lgkmcnt(0)
	ds_read_b128 v[156:159], v204 offset:0
	ds_read_b128 v[160:163], v204 offset:1088
	ds_read_b128 v[164:167], v204 offset:2176
	ds_read_b128 v[168:171], v204 offset:3264
	s_waitcnt lgkmcnt(3)
	v_max_f32_e32 v156, 0, v156
	v_max_f32_e32 v157, 0, v157
	v_max_f32_e32 v158, 0, v158
	v_max_f32_e32 v159, 0, v159
	v_mul_f32_e32 v156, v156, v156
	v_mul_f32_e32 v157, v157, v157
	v_mul_f32_e32 v158, v158, v158
	v_mul_f32_e32 v159, v159, v159
	v_cvt_pk_bf16_f32 v176, v156, v157
	v_cvt_pk_bf16_f32 v177, v158, v159
	global_store_dwordx2 v197, v[176:177], s[56:57] sc0 sc1
	v_add_u32_e32 v197, 0x8000, v197
	s_waitcnt lgkmcnt(2)
	v_max_f32_e32 v160, 0, v160
	v_max_f32_e32 v161, 0, v161
	v_max_f32_e32 v162, 0, v162
	v_max_f32_e32 v163, 0, v163
	v_mul_f32_e32 v160, v160, v160
	v_mul_f32_e32 v161, v161, v161
	v_mul_f32_e32 v162, v162, v162
	v_mul_f32_e32 v163, v163, v163
	v_cvt_pk_bf16_f32 v178, v160, v161
	v_cvt_pk_bf16_f32 v179, v162, v163
	global_store_dwordx2 v197, v[178:179], s[56:57] sc0 sc1
	v_add_u32_e32 v197, 0x8000, v197
	s_waitcnt lgkmcnt(1)
	v_max_f32_e32 v164, 0, v164
	v_max_f32_e32 v165, 0, v165
	v_max_f32_e32 v166, 0, v166
	v_max_f32_e32 v167, 0, v167
	v_mul_f32_e32 v164, v164, v164
	v_mul_f32_e32 v165, v165, v165
	v_mul_f32_e32 v166, v166, v166
	v_mul_f32_e32 v167, v167, v167
	v_cvt_pk_bf16_f32 v176, v164, v165
	v_cvt_pk_bf16_f32 v177, v166, v167
	global_store_dwordx2 v197, v[176:177], s[56:57] sc0 sc1
	v_add_u32_e32 v197, 0x8000, v197
	s_waitcnt lgkmcnt(0)
	v_max_f32_e32 v168, 0, v168
	v_max_f32_e32 v169, 0, v169
	v_max_f32_e32 v170, 0, v170
	v_max_f32_e32 v171, 0, v171
	v_mul_f32_e32 v168, v168, v168
	v_mul_f32_e32 v169, v169, v169
	v_mul_f32_e32 v170, v170, v170
	v_mul_f32_e32 v171, v171, v171
	v_cvt_pk_bf16_f32 v178, v168, v169
	v_cvt_pk_bf16_f32 v179, v170, v171
	global_store_dwordx2 v197, v[178:179], s[56:57] sc0 sc1
	v_add_u32_e32 v197, 0x8000, v197
	ds_write_b32 v203, v68 offset:0
	ds_write_b32 v203, v69 offset:272
	ds_write_b32 v203, v70 offset:544
	ds_write_b32 v203, v71 offset:816
	ds_write_b32 v203, v72 offset:64
	ds_write_b32 v203, v73 offset:336
	ds_write_b32 v203, v74 offset:608
	ds_write_b32 v203, v75 offset:880
	ds_write_b32 v203, v76 offset:128
	ds_write_b32 v203, v77 offset:400
	ds_write_b32 v203, v78 offset:672
	ds_write_b32 v203, v79 offset:944
	ds_write_b32 v203, v80 offset:192
	ds_write_b32 v203, v81 offset:464
	ds_write_b32 v203, v82 offset:736
	ds_write_b32 v203, v83 offset:1008
	s_waitcnt lgkmcnt(0)
	ds_read_b128 v[156:159], v204 offset:0
	ds_read_b128 v[160:163], v204 offset:1088
	ds_read_b128 v[164:167], v204 offset:2176
	ds_read_b128 v[168:171], v204 offset:3264
	s_waitcnt lgkmcnt(3)
	v_max_f32_e32 v156, 0, v156
	v_max_f32_e32 v157, 0, v157
	v_max_f32_e32 v158, 0, v158
	v_max_f32_e32 v159, 0, v159
	v_mul_f32_e32 v156, v156, v156
	v_mul_f32_e32 v157, v157, v157
	v_mul_f32_e32 v158, v158, v158
	v_mul_f32_e32 v159, v159, v159
	v_cvt_pk_bf16_f32 v176, v156, v157
	v_cvt_pk_bf16_f32 v177, v158, v159
	global_store_dwordx2 v197, v[176:177], s[56:57] sc0 sc1
	v_add_u32_e32 v197, 0x8000, v197
	s_waitcnt lgkmcnt(2)
	v_max_f32_e32 v160, 0, v160
	v_max_f32_e32 v161, 0, v161
	v_max_f32_e32 v162, 0, v162
	v_max_f32_e32 v163, 0, v163
	v_mul_f32_e32 v160, v160, v160
	v_mul_f32_e32 v161, v161, v161
	v_mul_f32_e32 v162, v162, v162
	v_mul_f32_e32 v163, v163, v163
	v_cvt_pk_bf16_f32 v178, v160, v161
	v_cvt_pk_bf16_f32 v179, v162, v163
	global_store_dwordx2 v197, v[178:179], s[56:57] sc0 sc1
	v_add_u32_e32 v197, 0x8000, v197
	s_waitcnt lgkmcnt(1)
	v_max_f32_e32 v164, 0, v164
	v_max_f32_e32 v165, 0, v165
	v_max_f32_e32 v166, 0, v166
	v_max_f32_e32 v167, 0, v167
	v_mul_f32_e32 v164, v164, v164
	v_mul_f32_e32 v165, v165, v165
	v_mul_f32_e32 v166, v166, v166
	v_mul_f32_e32 v167, v167, v167
	v_cvt_pk_bf16_f32 v176, v164, v165
	v_cvt_pk_bf16_f32 v177, v166, v167
	global_store_dwordx2 v197, v[176:177], s[56:57] sc0 sc1
	v_add_u32_e32 v197, 0x8000, v197
	s_waitcnt lgkmcnt(0)
	v_max_f32_e32 v168, 0, v168
	v_max_f32_e32 v169, 0, v169
	v_max_f32_e32 v170, 0, v170
	v_max_f32_e32 v171, 0, v171
	v_mul_f32_e32 v168, v168, v168
	v_mul_f32_e32 v169, v169, v169
	v_mul_f32_e32 v170, v170, v170
	v_mul_f32_e32 v171, v171, v171
	v_cvt_pk_bf16_f32 v178, v168, v169
	v_cvt_pk_bf16_f32 v179, v170, v171
	global_store_dwordx2 v197, v[178:179], s[56:57] sc0 sc1
	v_add_u32_e32 v197, 0x8000, v197
	ds_write_b32 v203, v84 offset:0
	ds_write_b32 v203, v85 offset:272
	ds_write_b32 v203, v86 offset:544
	ds_write_b32 v203, v87 offset:816
	ds_write_b32 v203, v88 offset:64
	ds_write_b32 v203, v89 offset:336
	ds_write_b32 v203, v90 offset:608
	ds_write_b32 v203, v91 offset:880
	ds_write_b32 v203, v92 offset:128
	ds_write_b32 v203, v93 offset:400
	ds_write_b32 v203, v94 offset:672
	ds_write_b32 v203, v95 offset:944
	ds_write_b32 v203, v96 offset:192
	ds_write_b32 v203, v97 offset:464
	ds_write_b32 v203, v98 offset:736
	ds_write_b32 v203, v99 offset:1008
	s_waitcnt lgkmcnt(0)
	ds_read_b128 v[156:159], v204 offset:0
	ds_read_b128 v[160:163], v204 offset:1088
	ds_read_b128 v[164:167], v204 offset:2176
	ds_read_b128 v[168:171], v204 offset:3264
	s_waitcnt lgkmcnt(3)
	v_max_f32_e32 v156, 0, v156
	v_max_f32_e32 v157, 0, v157
	v_max_f32_e32 v158, 0, v158
	v_max_f32_e32 v159, 0, v159
	v_mul_f32_e32 v156, v156, v156
	v_mul_f32_e32 v157, v157, v157
	v_mul_f32_e32 v158, v158, v158
	v_mul_f32_e32 v159, v159, v159
	v_cvt_pk_bf16_f32 v176, v156, v157
	v_cvt_pk_bf16_f32 v177, v158, v159
	global_store_dwordx2 v197, v[176:177], s[56:57] sc0 sc1
	v_add_u32_e32 v197, 0x8000, v197
	s_waitcnt lgkmcnt(2)
	v_max_f32_e32 v160, 0, v160
	v_max_f32_e32 v161, 0, v161
	v_max_f32_e32 v162, 0, v162
	v_max_f32_e32 v163, 0, v163
	v_mul_f32_e32 v160, v160, v160
	v_mul_f32_e32 v161, v161, v161
	v_mul_f32_e32 v162, v162, v162
	v_mul_f32_e32 v163, v163, v163
	v_cvt_pk_bf16_f32 v178, v160, v161
	v_cvt_pk_bf16_f32 v179, v162, v163
	global_store_dwordx2 v197, v[178:179], s[56:57] sc0 sc1
	v_add_u32_e32 v197, 0x8000, v197
	s_waitcnt lgkmcnt(1)
	v_max_f32_e32 v164, 0, v164
	v_max_f32_e32 v165, 0, v165
	v_max_f32_e32 v166, 0, v166
	v_max_f32_e32 v167, 0, v167
	v_mul_f32_e32 v164, v164, v164
	v_mul_f32_e32 v165, v165, v165
	v_mul_f32_e32 v166, v166, v166
	v_mul_f32_e32 v167, v167, v167
	v_cvt_pk_bf16_f32 v176, v164, v165
	v_cvt_pk_bf16_f32 v177, v166, v167
	global_store_dwordx2 v197, v[176:177], s[56:57] sc0 sc1
	v_add_u32_e32 v197, 0x8000, v197
	s_waitcnt lgkmcnt(0)
	v_max_f32_e32 v168, 0, v168
	v_max_f32_e32 v169, 0, v169
	v_max_f32_e32 v170, 0, v170
	v_max_f32_e32 v171, 0, v171
	v_mul_f32_e32 v168, v168, v168
	v_mul_f32_e32 v169, v169, v169
	v_mul_f32_e32 v170, v170, v170
	v_mul_f32_e32 v171, v171, v171
	v_cvt_pk_bf16_f32 v178, v168, v169
	v_cvt_pk_bf16_f32 v179, v170, v171
	global_store_dwordx2 v197, v[178:179], s[56:57] sc0 sc1
	v_add_u32_e32 v197, 0x8000, v197
	v_mov_b32_e32 v4, 0
	v_mov_b32_e32 v5, 0
	v_mov_b32_e32 v6, 0
	v_mov_b32_e32 v7, 0
	v_mov_b32_e32 v8, 0
	v_mov_b32_e32 v9, 0
	v_mov_b32_e32 v10, 0
	v_mov_b32_e32 v11, 0
	v_mov_b32_e32 v12, 0
	v_mov_b32_e32 v13, 0
	v_mov_b32_e32 v14, 0
	v_mov_b32_e32 v15, 0
	v_mov_b32_e32 v16, 0
	v_mov_b32_e32 v17, 0
	v_mov_b32_e32 v18, 0
	v_mov_b32_e32 v19, 0
	v_mov_b32_e32 v20, 0
	v_mov_b32_e32 v21, 0
	v_mov_b32_e32 v22, 0
	v_mov_b32_e32 v23, 0
	v_mov_b32_e32 v24, 0
	v_mov_b32_e32 v25, 0
	v_mov_b32_e32 v26, 0
	v_mov_b32_e32 v27, 0
	v_mov_b32_e32 v28, 0
	v_mov_b32_e32 v29, 0
	v_mov_b32_e32 v30, 0
	v_mov_b32_e32 v31, 0
	v_mov_b32_e32 v32, 0
	v_mov_b32_e32 v33, 0
	v_mov_b32_e32 v34, 0
	v_mov_b32_e32 v35, 0
	v_mov_b32_e32 v36, 0
	v_mov_b32_e32 v37, 0
	v_mov_b32_e32 v38, 0
	v_mov_b32_e32 v39, 0
	v_mov_b32_e32 v40, 0
	v_mov_b32_e32 v41, 0
	v_mov_b32_e32 v42, 0
	v_mov_b32_e32 v43, 0
	v_mov_b32_e32 v44, 0
	v_mov_b32_e32 v45, 0
	v_mov_b32_e32 v46, 0
	v_mov_b32_e32 v47, 0
	v_mov_b32_e32 v48, 0
	v_mov_b32_e32 v49, 0
	v_mov_b32_e32 v50, 0
	v_mov_b32_e32 v51, 0
	v_mov_b32_e32 v52, 0
	v_mov_b32_e32 v53, 0
	v_mov_b32_e32 v54, 0
	v_mov_b32_e32 v55, 0
	v_mov_b32_e32 v56, 0
	v_mov_b32_e32 v57, 0
	v_mov_b32_e32 v58, 0
	v_mov_b32_e32 v59, 0
	v_mov_b32_e32 v60, 0
	v_mov_b32_e32 v61, 0
	v_mov_b32_e32 v62, 0
	v_mov_b32_e32 v63, 0
	v_mov_b32_e32 v64, 0
	v_mov_b32_e32 v65, 0
	v_mov_b32_e32 v66, 0
	v_mov_b32_e32 v67, 0
	v_mov_b32_e32 v68, 0
	v_mov_b32_e32 v69, 0
	v_mov_b32_e32 v70, 0
	v_mov_b32_e32 v71, 0
	v_mov_b32_e32 v72, 0
	v_mov_b32_e32 v73, 0
	v_mov_b32_e32 v74, 0
	v_mov_b32_e32 v75, 0
	v_mov_b32_e32 v76, 0
	v_mov_b32_e32 v77, 0
	v_mov_b32_e32 v78, 0
	v_mov_b32_e32 v79, 0
	v_mov_b32_e32 v80, 0
	v_mov_b32_e32 v81, 0
	v_mov_b32_e32 v82, 0
	v_mov_b32_e32 v83, 0
	v_mov_b32_e32 v84, 0
	v_mov_b32_e32 v85, 0
	v_mov_b32_e32 v86, 0
	v_mov_b32_e32 v87, 0
	v_mov_b32_e32 v88, 0
	v_mov_b32_e32 v89, 0
	v_mov_b32_e32 v90, 0
	v_mov_b32_e32 v91, 0
	v_mov_b32_e32 v92, 0
	v_mov_b32_e32 v93, 0
	v_mov_b32_e32 v94, 0
	v_mov_b32_e32 v95, 0
	v_mov_b32_e32 v96, 0
	v_mov_b32_e32 v97, 0
	v_mov_b32_e32 v98, 0
	v_mov_b32_e32 v99, 0
	s_mov_b32 s34, 0
	s_add_u32 s35, s35, s52
	s_cmp_ge_u32 s31, s30
	s_cbranch_scc1 .Lgm_f1_exit

.Lgm_f2_cnt:
	s_add_u32 s30, s30, 64
	s_add_u32 s4, s4, s52
	s_cmp_lt_u32 s4, s54
	s_cbranch_scc1 .Lgm_f2_cnt
	s_add_u32 s48, s96, 0x3a24000
	s_addc_u32 s49, s97, 0
	s_mul_i32 s4, s36, 0x800000
	s_add_u32 s50, s96, 0x1d80000
	s_addc_u32 s51, s97, 0
	s_add_u32 s50, s50, s4
	s_addc_u32 s51, s51, 0
	v_and_b32_e32 v0, 63, v206
	v_lshrrev_b32_e32 v1, 6, v206
	s_mov_b32 s31, 0
	v_readfirstlane_b32 s42, v1
	s_nop 0
	s_cmp_ge_u32 s42, 4
	s_cbranch_scc1 .Lgm_f2_compute
	v_lshrrev_b32_e32 v3, 3, v0
	v_and_b32_e32 v4, 7, v0
	v_xor_b32_e32 v4, v4, v3
	v_lshl_add_u32 v3, v1, 3, v3
	v_lshlrev_b32_e32 v3, 13, v3
	v_lshl_add_u32 v180, v4, 4, v3
	v_add_u32_e32 v181, 0x40000, v180
	v_add_u32_e32 v182, 0x80000, v180
	v_add_u32_e32 v183, 0xc0000, v180
	v_add_u32_e32 v184, 0x100000, v180
	v_add_u32_e32 v185, 0x140000, v180
	s_lshl_b32 s42, s42, 10
	s_mov_b32 s38, s53
	s_mov_b32 s39, 0
	s_mov_b32 s41, s42
	s_and_b32 s4, s38, 31
	s_lshr_b32 s5, s38, 5
	s_mul_i32 s4, s4, 0x180000
	s_add_u32 s44, s48, s4
	s_addc_u32 s45, s49, 0
	s_mul_i32 s4, s5, 0x100000
	s_add_u32 s46, s50, s4
	s_addc_u32 s47, s51, 0
	s_add_u32 m0, s41, 0x0
	s_nop 0
	global_load_lds_dwordx4 v180, s[44:45]
	s_add_u32 m0, s41, 0x1000
	s_nop 0
	global_load_lds_dwordx4 v181, s[44:45]
	s_add_u32 m0, s41, 0x2000
	s_nop 0
	global_load_lds_dwordx4 v182, s[44:45]
	s_add_u32 m0, s41, 0x3000
	s_nop 0
	global_load_lds_dwordx4 v183, s[44:45]
	s_add_u32 m0, s41, 0x4000
	s_nop 0
	global_load_lds_dwordx4 v184, s[44:45]
	s_add_u32 m0, s41, 0x5000
	s_nop 0
	global_load_lds_dwordx4 v185, s[44:45]
	s_add_u32 m0, s41, 0x6000
	s_nop 0
	global_load_lds_dwordx4 v180, s[46:47]
	s_add_u32 m0, s41, 0x7000
	s_nop 0
	global_load_lds_dwordx4 v181, s[46:47]
	s_add_u32 m0, s41, 0x8000
	s_nop 0
	global_load_lds_dwordx4 v182, s[46:47]
	s_add_u32 m0, s41, 0x9000
	s_nop 0
	global_load_lds_dwordx4 v183, s[46:47]
	s_add_u32 s39, s39, 1
	s_add_u32 s44, s44, 0x80
	s_addc_u32 s45, s45, 0
	s_add_u32 s46, s46, 0x80
	s_addc_u32 s47, s47, 0
	s_cmp_lt_u32 s39, 64
	s_cbranch_scc1 .Lgm_f2_dadv1
	s_mov_b32 s39, 0
	s_add_u32 s4, s38, s52
	s_cmp_lt_u32 s4, s54
	s_cselect_b32 s38, s4, s38
	s_and_b32 s4, s38, 31
	s_lshr_b32 s5, s38, 5
	s_mul_i32 s4, s4, 0x180000
	s_add_u32 s44, s48, s4
	s_addc_u32 s45, s49, 0
	s_mul_i32 s4, s5, 0x100000
	s_add_u32 s46, s50, s4
	s_addc_u32 s47, s51, 0
.Lgm_f2_dadv1:
	s_add_u32 s41, s41, 0xa000
	s_sub_u32 s4, s41, 0x1e000
	s_cmp_ge_u32 s41, 0x1e000
	s_cselect_b32 s41, s4, s41
	s_add_u32 m0, s41, 0x0
	s_nop 0
	global_load_lds_dwordx4 v180, s[44:45]
	s_add_u32 m0, s41, 0x1000
	s_nop 0
	global_load_lds_dwordx4 v181, s[44:45]
	s_add_u32 m0, s41, 0x2000
	s_nop 0
	global_load_lds_dwordx4 v182, s[44:45]
	s_add_u32 m0, s41, 0x3000
	s_nop 0
	global_load_lds_dwordx4 v183, s[44:45]
	s_add_u32 m0, s41, 0x4000
	s_nop 0
	global_load_lds_dwordx4 v184, s[44:45]
	s_add_u32 m0, s41, 0x5000
	s_nop 0
	global_load_lds_dwordx4 v185, s[44:45]
	s_add_u32 m0, s41, 0x6000
	s_nop 0
	global_load_lds_dwordx4 v180, s[46:47]
	s_add_u32 m0, s41, 0x7000
	s_nop 0
	global_load_lds_dwordx4 v181, s[46:47]
	s_add_u32 m0, s41, 0x8000
	s_nop 0
	global_load_lds_dwordx4 v182, s[46:47]
	s_add_u32 m0, s41, 0x9000
	s_nop 0
	global_load_lds_dwordx4 v183, s[46:47]
	s_add_u32 s39, s39, 1
	s_add_u32 s44, s44, 0x80
	s_addc_u32 s45, s45, 0
	s_add_u32 s46, s46, 0x80
	s_addc_u32 s47, s47, 0
	s_cmp_lt_u32 s39, 64
	s_cbranch_scc1 .Lgm_f2_dadv2
	s_mov_b32 s39, 0
	s_add_u32 s4, s38, s52
	s_cmp_lt_u32 s4, s54
	s_cselect_b32 s38, s4, s38
	s_and_b32 s4, s38, 31
	s_lshr_b32 s5, s38, 5
	s_mul_i32 s4, s4, 0x180000
	s_add_u32 s44, s48, s4
	s_addc_u32 s45, s49, 0
	s_mul_i32 s4, s5, 0x100000
	s_add_u32 s46, s50, s4
	s_addc_u32 s47, s51, 0

.Lgm_f2_ld_loop:
	s_barrier
	s_add_u32 m0, s41, 0x0
	s_nop 0
	global_load_lds_dwordx4 v180, s[44:45]
	s_add_u32 m0, s41, 0x1000
	s_nop 0
	global_load_lds_dwordx4 v181, s[44:45]
	s_add_u32 m0, s41, 0x2000
	s_nop 0
	global_load_lds_dwordx4 v182, s[44:45]
	s_add_u32 m0, s41, 0x3000
	s_nop 0
	global_load_lds_dwordx4 v183, s[44:45]
	s_add_u32 m0, s41, 0x4000
	s_nop 0
	global_load_lds_dwordx4 v184, s[44:45]
	s_add_u32 m0, s41, 0x5000
	s_nop 0
	global_load_lds_dwordx4 v185, s[44:45]
	s_add_u32 m0, s41, 0x6000
	s_nop 0
	global_load_lds_dwordx4 v180, s[46:47]
	s_add_u32 m0, s41, 0x7000
	s_nop 0
	global_load_lds_dwordx4 v181, s[46:47]
	s_add_u32 m0, s41, 0x8000
	s_nop 0
	global_load_lds_dwordx4 v182, s[46:47]
	s_add_u32 m0, s41, 0x9000
	s_nop 0
	global_load_lds_dwordx4 v183, s[46:47]
	s_add_u32 s39, s39, 1
	s_add_u32 s44, s44, 0x80
	s_addc_u32 s45, s45, 0
	s_add_u32 s46, s46, 0x80
	s_addc_u32 s47, s47, 0
	s_cmp_lt_u32 s39, 64
	s_cbranch_scc1 .Lgm_f2_dadv3
	s_mov_b32 s39, 0
	s_add_u32 s4, s38, s52
	s_cmp_lt_u32 s4, s54
	s_cselect_b32 s38, s4, s38
	s_and_b32 s4, s38, 31
	s_lshr_b32 s5, s38, 5
	s_mul_i32 s4, s4, 0x180000
	s_add_u32 s44, s48, s4
	s_addc_u32 s45, s49, 0
	s_mul_i32 s4, s5, 0x100000
	s_add_u32 s46, s50, s4
	s_addc_u32 s47, s51, 0

.Lgm_f2_join:
	s_waitcnt lgkmcnt(13)
	v_mfma_f32_16x16x32_bf16 v[4:7], v[100:103], v[124:127], v[4:7]
	v_mfma_f32_16x16x32_bf16 v[20:23], v[104:107], v[124:127], v[20:23]
	v_mfma_f32_16x16x32_bf16 v[36:39], v[108:111], v[124:127], v[36:39]
	v_mfma_f32_16x16x32_bf16 v[52:55], v[112:115], v[124:127], v[52:55]
	v_mfma_f32_16x16x32_bf16 v[68:71], v[116:119], v[124:127], v[68:71]
	v_mfma_f32_16x16x32_bf16 v[84:87], v[120:123], v[124:127], v[84:87]
	s_waitcnt lgkmcnt(12)
	v_mfma_f32_16x16x32_bf16 v[8:11], v[100:103], v[128:131], v[8:11]
	v_mfma_f32_16x16x32_bf16 v[24:27], v[104:107], v[128:131], v[24:27]
	v_mfma_f32_16x16x32_bf16 v[40:43], v[108:111], v[128:131], v[40:43]
	v_mfma_f32_16x16x32_bf16 v[56:59], v[112:115], v[128:131], v[56:59]
	v_mfma_f32_16x16x32_bf16 v[72:75], v[116:119], v[128:131], v[72:75]
	v_mfma_f32_16x16x32_bf16 v[88:91], v[120:123], v[128:131], v[88:91]
	s_waitcnt lgkmcnt(11)
	v_mfma_f32_16x16x32_bf16 v[12:15], v[100:103], v[132:135], v[12:15]
	v_mfma_f32_16x16x32_bf16 v[28:31], v[104:107], v[132:135], v[28:31]
	v_mfma_f32_16x16x32_bf16 v[44:47], v[108:111], v[132:135], v[44:47]
	v_mfma_f32_16x16x32_bf16 v[60:63], v[112:115], v[132:135], v[60:63]
	v_mfma_f32_16x16x32_bf16 v[76:79], v[116:119], v[132:135], v[76:79]
	v_mfma_f32_16x16x32_bf16 v[92:95], v[120:123], v[132:135], v[92:95]
	s_waitcnt lgkmcnt(10)
	v_mfma_f32_16x16x32_bf16 v[16:19], v[100:103], v[136:139], v[16:19]
	v_mfma_f32_16x16x32_bf16 v[32:35], v[104:107], v[136:139], v[32:35]
	v_mfma_f32_16x16x32_bf16 v[48:51], v[108:111], v[136:139], v[48:51]
	v_mfma_f32_16x16x32_bf16 v[64:67], v[112:115], v[136:139], v[64:67]
	v_mfma_f32_16x16x32_bf16 v[80:83], v[116:119], v[136:139], v[80:83]
	v_mfma_f32_16x16x32_bf16 v[96:99], v[120:123], v[136:139], v[96:99]
	s_waitcnt lgkmcnt(0)
	s_add_u32 s34, s34, 1
	s_add_u32 s31, s31, 1
	s_cmp_lt_u32 s34, 64
	s_cbranch_scc1 .Lgm_f2_rot
	v_mfma_f32_16x16x32_bf16 v[4:7], v[140:143], v[164:167], v[4:7]
	v_mfma_f32_16x16x32_bf16 v[20:23], v[144:147], v[164:167], v[20:23]
	v_mfma_f32_16x16x32_bf16 v[36:39], v[148:151], v[164:167], v[36:39]
	v_mfma_f32_16x16x32_bf16 v[52:55], v[152:155], v[164:167], v[52:55]
	v_mfma_f32_16x16x32_bf16 v[68:71], v[156:159], v[164:167], v[68:71]
	v_mfma_f32_16x16x32_bf16 v[84:87], v[160:163], v[164:167], v[84:87]
	v_mfma_f32_16x16x32_bf16 v[8:11], v[140:143], v[168:171], v[8:11]
	v_mfma_f32_16x16x32_bf16 v[24:27], v[144:147], v[168:171], v[24:27]
	v_mfma_f32_16x16x32_bf16 v[40:43], v[148:151], v[168:171], v[40:43]
	v_mfma_f32_16x16x32_bf16 v[56:59], v[152:155], v[168:171], v[56:59]
	v_mfma_f32_16x16x32_bf16 v[72:75], v[156:159], v[168:171], v[72:75]
	v_mfma_f32_16x16x32_bf16 v[88:91], v[160:163], v[168:171], v[88:91]
	v_mfma_f32_16x16x32_bf16 v[12:15], v[140:143], v[172:175], v[12:15]
	v_mfma_f32_16x16x32_bf16 v[28:31], v[144:147], v[172:175], v[28:31]
	v_mfma_f32_16x16x32_bf16 v[44:47], v[148:151], v[172:175], v[44:47]
	v_mfma_f32_16x16x32_bf16 v[60:63], v[152:155], v[172:175], v[60:63]
	v_mfma_f32_16x16x32_bf16 v[76:79], v[156:159], v[172:175], v[76:79]
	v_mfma_f32_16x16x32_bf16 v[92:95], v[160:163], v[172:175], v[92:95]
	v_mfma_f32_16x16x32_bf16 v[16:19], v[140:143], v[176:179], v[16:19]
	v_mfma_f32_16x16x32_bf16 v[32:35], v[144:147], v[176:179], v[32:35]
	v_mfma_f32_16x16x32_bf16 v[48:51], v[148:151], v[176:179], v[48:51]
	v_mfma_f32_16x16x32_bf16 v[64:67], v[152:155], v[176:179], v[64:67]
	v_mfma_f32_16x16x32_bf16 v[80:83], v[156:159], v[176:179], v[80:83]
	v_mfma_f32_16x16x32_bf16 v[96:99], v[160:163], v[176:179], v[96:99]
	s_and_b32 s6, s35, 31
	s_lshr_b32 s7, s35, 5
	s_mul_i32 s6, s6, 192
	s_lshl_b32 s7, s7, 7
	s_nop 7
	s_mul_i32 s4, s6, 0x1000
	s_lshl_b32 s5, s7, 2
	s_add_u32 s4, s4, s5
	v_add_u32_e32 v197, s4, v205
	v_add_u32_e32 v192, s6, v190
	v_lshl_add_u32 v193, s7, 2, v191
	s_sub_i32 s4, s6, 0xc00
	s_max_i32 s4, s4, 0
	s_lshr_b32 s4, s4, 10
	s_add_i32 s5, s6, -2881
	s_max_i32 s5, s5, 0
	s_lshr_b32 s5, s5, 10
	s_movk_i32 s7, 0x1400
	s_cmp_eq_u32 s4, 0
	s_cselect_b32 s7, 0x1000, s7
	s_mul_i32 s4, s4, 0x6000
	s_mul_i32 s5, s5, 0x6000
	v_mov_b32_e32 v194, v197
	v_add_u32_e32 v195, 0, v192
	v_cmp_gt_u32_e32 vcc, 0x1000, v195
	v_mov_b32_e32 v0, s98
	v_mov_b32_e32 v1, s99
	v_mov_b32_e32 v3, s58
	v_cndmask_b32_e32 v0, v0, v3, vcc
	v_mov_b32_e32 v3, s59
	v_cndmask_b32_e32 v1, v1, v3, vcc
	v_add_co_u32_e32 v0, vcc, v0, v194
	s_nop 1
	v_addc_co_u32_e32 v1, vcc, 0, v1, vcc
	global_load_dwordx4 v[100:103], v[0:1], off
	v_add_u32_e32 v194, 0x4000, v194
	v_add_u32_e32 v195, 4, v192
	v_cmp_gt_u32_e32 vcc, 0x1000, v195
	v_mov_b32_e32 v0, s98
	v_mov_b32_e32 v1, s99
	v_mov_b32_e32 v3, s58
	v_cndmask_b32_e32 v0, v0, v3, vcc
	v_mov_b32_e32 v3, s59
	v_cndmask_b32_e32 v1, v1, v3, vcc
	v_add_co_u32_e32 v0, vcc, v0, v194
	s_nop 1
	v_addc_co_u32_e32 v1, vcc, 0, v1, vcc
	global_load_dwordx4 v[104:107], v[0:1], off
	v_add_u32_e32 v194, 0x4000, v194
	v_add_u32_e32 v195, 8, v192
	v_cmp_gt_u32_e32 vcc, 0x1000, v195
	v_mov_b32_e32 v0, s98
	v_mov_b32_e32 v1, s99
	v_mov_b32_e32 v3, s58
	v_cndmask_b32_e32 v0, v0, v3, vcc
	v_mov_b32_e32 v3, s59
	v_cndmask_b32_e32 v1, v1, v3, vcc
	v_add_co_u32_e32 v0, vcc, v0, v194
	s_nop 1
	v_addc_co_u32_e32 v1, vcc, 0, v1, vcc
	global_load_dwordx4 v[108:111], v[0:1], off
	v_add_u32_e32 v194, 0x4000, v194
	v_add_u32_e32 v195, 12, v192
	v_cmp_gt_u32_e32 vcc, 0x1000, v195
	v_mov_b32_e32 v0, s98
	v_mov_b32_e32 v1, s99
	v_mov_b32_e32 v3, s58
	v_cndmask_b32_e32 v0, v0, v3, vcc
	v_mov_b32_e32 v3, s59
	v_cndmask_b32_e32 v1, v1, v3, vcc
	v_add_co_u32_e32 v0, vcc, v0, v194
	s_nop 1
	v_addc_co_u32_e32 v1, vcc, 0, v1, vcc
	global_load_dwordx4 v[112:115], v[0:1], off
	v_add_u32_e32 v194, 0x4000, v194
	v_add_u32_e32 v195, 16, v192
	v_cmp_gt_u32_e32 vcc, 0x1000, v195
	v_mov_b32_e32 v0, s98
	v_mov_b32_e32 v1, s99
	v_mov_b32_e32 v3, s58
	v_cndmask_b32_e32 v0, v0, v3, vcc
	v_mov_b32_e32 v3, s59
	v_cndmask_b32_e32 v1, v1, v3, vcc
	v_add_co_u32_e32 v0, vcc, v0, v194
	s_nop 1
	v_addc_co_u32_e32 v1, vcc, 0, v1, vcc
	global_load_dwordx4 v[116:119], v[0:1], off
	v_add_u32_e32 v194, 0x4000, v194
	v_add_u32_e32 v195, 20, v192
	v_cmp_gt_u32_e32 vcc, 0x1000, v195
	v_mov_b32_e32 v0, s98
	v_mov_b32_e32 v1, s99
	v_mov_b32_e32 v3, s58
	v_cndmask_b32_e32 v0, v0, v3, vcc
	v_mov_b32_e32 v3, s59
	v_cndmask_b32_e32 v1, v1, v3, vcc
	v_add_co_u32_e32 v0, vcc, v0, v194
	s_nop 1
	v_addc_co_u32_e32 v1, vcc, 0, v1, vcc
	global_load_dwordx4 v[120:123], v[0:1], off
	v_add_u32_e32 v194, 0x4000, v194
	v_add_u32_e32 v195, 24, v192
	v_cmp_gt_u32_e32 vcc, 0x1000, v195
	v_mov_b32_e32 v0, s98
	v_mov_b32_e32 v1, s99
	v_mov_b32_e32 v3, s58
	v_cndmask_b32_e32 v0, v0, v3, vcc
	v_mov_b32_e32 v3, s59
	v_cndmask_b32_e32 v1, v1, v3, vcc
	v_add_co_u32_e32 v0, vcc, v0, v194
	s_nop 1
	v_addc_co_u32_e32 v1, vcc, 0, v1, vcc
	global_load_dwordx4 v[124:127], v[0:1], off
	v_add_u32_e32 v194, 0x4000, v194
	v_add_u32_e32 v195, 28, v192
	v_cmp_gt_u32_e32 vcc, 0x1000, v195
	v_mov_b32_e32 v0, s98
	v_mov_b32_e32 v1, s99
	v_mov_b32_e32 v3, s58
	v_cndmask_b32_e32 v0, v0, v3, vcc
	v_mov_b32_e32 v3, s59
	v_cndmask_b32_e32 v1, v1, v3, vcc
	v_add_co_u32_e32 v0, vcc, v0, v194
	s_nop 1
	v_addc_co_u32_e32 v1, vcc, 0, v1, vcc
	global_load_dwordx4 v[128:131], v[0:1], off
	v_add_u32_e32 v194, 0x4000, v194
	v_add_u32_e32 v195, 32, v192
	v_cmp_gt_u32_e32 vcc, 0x1000, v195
	v_mov_b32_e32 v0, s98
	v_mov_b32_e32 v1, s99
	v_mov_b32_e32 v3, s58
	v_cndmask_b32_e32 v0, v0, v3, vcc
	v_mov_b32_e32 v3, s59
	v_cndmask_b32_e32 v1, v1, v3, vcc
	v_add_co_u32_e32 v0, vcc, v0, v194
	s_nop 1
	v_addc_co_u32_e32 v1, vcc, 0, v1, vcc
	global_load_dwordx4 v[132:135], v[0:1], off
	v_add_u32_e32 v194, 0x4000, v194
	v_add_u32_e32 v195, 36, v192
	v_cmp_gt_u32_e32 vcc, 0x1000, v195
	v_mov_b32_e32 v0, s98
	v_mov_b32_e32 v1, s99
	v_mov_b32_e32 v3, s58
	v_cndmask_b32_e32 v0, v0, v3, vcc
	v_mov_b32_e32 v3, s59
	v_cndmask_b32_e32 v1, v1, v3, vcc
	v_add_co_u32_e32 v0, vcc, v0, v194
	s_nop 1
	v_addc_co_u32_e32 v1, vcc, 0, v1, vcc
	global_load_dwordx4 v[136:139], v[0:1], off
	v_add_u32_e32 v194, 0x4000, v194
	v_add_u32_e32 v195, 40, v192
	v_cmp_gt_u32_e32 vcc, 0x1000, v195
	v_mov_b32_e32 v0, s98
	v_mov_b32_e32 v1, s99
	v_mov_b32_e32 v3, s58
	v_cndmask_b32_e32 v0, v0, v3, vcc
	v_mov_b32_e32 v3, s59
	v_cndmask_b32_e32 v1, v1, v3, vcc
	v_add_co_u32_e32 v0, vcc, v0, v194
	s_nop 1
	v_addc_co_u32_e32 v1, vcc, 0, v1, vcc
	global_load_dwordx4 v[140:143], v[0:1], off
	v_add_u32_e32 v194, 0x4000, v194
	v_add_u32_e32 v195, 44, v192
	v_cmp_gt_u32_e32 vcc, 0x1000, v195
	v_mov_b32_e32 v0, s98
	v_mov_b32_e32 v1, s99
	v_mov_b32_e32 v3, s58
	v_cndmask_b32_e32 v0, v0, v3, vcc
	v_mov_b32_e32 v3, s59
	v_cndmask_b32_e32 v1, v1, v3, vcc
	v_add_co_u32_e32 v0, vcc, v0, v194
	s_nop 1
	v_addc_co_u32_e32 v1, vcc, 0, v1, vcc
	global_load_dwordx4 v[144:147], v[0:1], off
	v_add_u32_e32 v194, 0x4000, v194
	v_add_u32_e32 v195, s4, v193
	global_load_dwordx4 v[148:151], v195, s[100:101]
	v_add_u32_e32 v195, s5, v193
	global_load_dwordx4 v[152:155], v195, s[100:101]
	ds_write_b32 v203, v4 offset:0
	ds_write_b32 v203, v5 offset:272
	ds_write_b32 v203, v6 offset:544
	ds_write_b32 v203, v7 offset:816
	ds_write_b32 v203, v8 offset:64
	ds_write_b32 v203, v9 offset:336
	ds_write_b32 v203, v10 offset:608
	ds_write_b32 v203, v11 offset:880
	ds_write_b32 v203, v12 offset:128
	ds_write_b32 v203, v13 offset:400
	ds_write_b32 v203, v14 offset:672
	ds_write_b32 v203, v15 offset:944
	ds_write_b32 v203, v16 offset:192
	ds_write_b32 v203, v17 offset:464
	ds_write_b32 v203, v18 offset:736
	ds_write_b32 v203, v19 offset:1008
	s_waitcnt lgkmcnt(0)
	ds_read_b128 v[156:159], v204 offset:0
	ds_read_b128 v[160:163], v204 offset:1088
	ds_read_b128 v[164:167], v204 offset:2176
	ds_read_b128 v[168:171], v204 offset:3264
	s_waitcnt lgkmcnt(0)
	v_add_u32_e32 v195, 48, v192
	v_cmp_gt_u32_e32 vcc, 0x1000, v195
	v_mov_b32_e32 v0, s98
	v_mov_b32_e32 v1, s99
	v_mov_b32_e32 v3, s58
	v_cndmask_b32_e32 v0, v0, v3, vcc
	v_mov_b32_e32 v3, s59
	v_cndmask_b32_e32 v1, v1, v3, vcc
	v_add_co_u32_e32 v0, vcc, v0, v194
	s_nop 1
	v_addc_co_u32_e32 v1, vcc, 0, v1, vcc
	global_load_dwordx4 v[4:7], v[0:1], off
	v_add_u32_e32 v194, 0x4000, v194
	v_add_u32_e32 v195, 52, v192
	v_cmp_gt_u32_e32 vcc, 0x1000, v195
	v_mov_b32_e32 v0, s98
	v_mov_b32_e32 v1, s99
	v_mov_b32_e32 v3, s58
	v_cndmask_b32_e32 v0, v0, v3, vcc
	v_mov_b32_e32 v3, s59
	v_cndmask_b32_e32 v1, v1, v3, vcc
	v_add_co_u32_e32 v0, vcc, v0, v194
	s_nop 1
	v_addc_co_u32_e32 v1, vcc, 0, v1, vcc
	global_load_dwordx4 v[8:11], v[0:1], off
	v_add_u32_e32 v194, 0x4000, v194
	v_add_u32_e32 v195, 56, v192
	v_cmp_gt_u32_e32 vcc, 0x1000, v195
	v_mov_b32_e32 v0, s98
	v_mov_b32_e32 v1, s99
	v_mov_b32_e32 v3, s58
	v_cndmask_b32_e32 v0, v0, v3, vcc
	v_mov_b32_e32 v3, s59
	v_cndmask_b32_e32 v1, v1, v3, vcc
	v_add_co_u32_e32 v0, vcc, v0, v194
	s_nop 1
	v_addc_co_u32_e32 v1, vcc, 0, v1, vcc
	global_load_dwordx4 v[12:15], v[0:1], off
	v_add_u32_e32 v194, 0x4000, v194
	v_add_u32_e32 v195, 60, v192
	v_cmp_gt_u32_e32 vcc, 0x1000, v195
	v_mov_b32_e32 v0, s98
	v_mov_b32_e32 v1, s99
	v_mov_b32_e32 v3, s58
	v_cndmask_b32_e32 v0, v0, v3, vcc
	v_mov_b32_e32 v3, s59
	v_cndmask_b32_e32 v1, v1, v3, vcc
	v_add_co_u32_e32 v0, vcc, v0, v194
	s_nop 1
	v_addc_co_u32_e32 v1, vcc, 0, v1, vcc
	global_load_dwordx4 v[16:19], v[0:1], off
	v_add_u32_e32 v194, 0x4000, v194
	v_add_u32_e32 v195, 0, v192
	v_cmp_le_u32_e32 vcc, s7, v195
	s_waitcnt vmcnt(4)
	v_cndmask_b32_e32 v172, v148, v152, vcc
	v_cndmask_b32_e32 v173, v149, v153, vcc
	v_cndmask_b32_e32 v174, v150, v154, vcc
	v_cndmask_b32_e32 v175, v151, v155, vcc
	v_fmac_f32_e32 v100, v172, v156
	v_fmac_f32_e32 v101, v173, v157
	v_fmac_f32_e32 v102, v174, v158
	v_fmac_f32_e32 v103, v175, v159
	global_store_dwordx4 v197, v[100:103], s[56:57] sc0 sc1
	v_add_u32_e32 v197, 0x4000, v197
	v_add_u32_e32 v195, 4, v192
	v_cmp_le_u32_e32 vcc, s7, v195
	s_waitcnt vmcnt(5)
	s_waitcnt lgkmcnt(2)
	v_cndmask_b32_e32 v172, v148, v152, vcc
	v_cndmask_b32_e32 v173, v149, v153, vcc
	v_cndmask_b32_e32 v174, v150, v154, vcc
	v_cndmask_b32_e32 v175, v151, v155, vcc
	v_fmac_f32_e32 v104, v172, v160
	v_fmac_f32_e32 v105, v173, v161
	v_fmac_f32_e32 v106, v174, v162
	v_fmac_f32_e32 v107, v175, v163
	global_store_dwordx4 v197, v[104:107], s[56:57] sc0 sc1
	v_add_u32_e32 v197, 0x4000, v197
	v_add_u32_e32 v195, 8, v192
	v_cmp_le_u32_e32 vcc, s7, v195
	s_waitcnt vmcnt(6)
	s_waitcnt lgkmcnt(1)
	v_cndmask_b32_e32 v172, v148, v152, vcc
	v_cndmask_b32_e32 v173, v149, v153, vcc
	v_cndmask_b32_e32 v174, v150, v154, vcc
	v_cndmask_b32_e32 v175, v151, v155, vcc
	v_fmac_f32_e32 v108, v172, v164
	v_fmac_f32_e32 v109, v173, v165
	v_fmac_f32_e32 v110, v174, v166
	v_fmac_f32_e32 v111, v175, v167
	global_store_dwordx4 v197, v[108:111], s[56:57] sc0 sc1
	v_add_u32_e32 v197, 0x4000, v197
	v_add_u32_e32 v195, 12, v192
	v_cmp_le_u32_e32 vcc, s7, v195
	s_waitcnt vmcnt(7)
	s_waitcnt lgkmcnt(0)
	v_cndmask_b32_e32 v172, v148, v152, vcc
	v_cndmask_b32_e32 v173, v149, v153, vcc
	v_cndmask_b32_e32 v174, v150, v154, vcc
	v_cndmask_b32_e32 v175, v151, v155, vcc
	v_fmac_f32_e32 v112, v172, v168
	v_fmac_f32_e32 v113, v173, v169
	v_fmac_f32_e32 v114, v174, v170
	v_fmac_f32_e32 v115, v175, v171
	global_store_dwordx4 v197, v[112:115], s[56:57] sc0 sc1
	v_add_u32_e32 v197, 0x4000, v197
	ds_write_b32 v203, v20 offset:0
	ds_write_b32 v203, v21 offset:272
	ds_write_b32 v203, v22 offset:544
	ds_write_b32 v203, v23 offset:816
	ds_write_b32 v203, v24 offset:64
	ds_write_b32 v203, v25 offset:336
	ds_write_b32 v203, v26 offset:608
	ds_write_b32 v203, v27 offset:880
	ds_write_b32 v203, v28 offset:128
	ds_write_b32 v203, v29 offset:400
	ds_write_b32 v203, v30 offset:672
	ds_write_b32 v203, v31 offset:944
	ds_write_b32 v203, v32 offset:192
	ds_write_b32 v203, v33 offset:464
	ds_write_b32 v203, v34 offset:736
	ds_write_b32 v203, v35 offset:1008
	s_waitcnt lgkmcnt(0)
	ds_read_b128 v[156:159], v204 offset:0
	ds_read_b128 v[160:163], v204 offset:1088
	ds_read_b128 v[164:167], v204 offset:2176
	ds_read_b128 v[168:171], v204 offset:3264
	s_waitcnt lgkmcnt(0)
	v_add_u32_e32 v195, 64, v192
	v_cmp_gt_u32_e32 vcc, 0x1000, v195
	v_mov_b32_e32 v0, s98
	v_mov_b32_e32 v1, s99
	v_mov_b32_e32 v3, s58
	v_cndmask_b32_e32 v0, v0, v3, vcc
	v_mov_b32_e32 v3, s59
	v_cndmask_b32_e32 v1, v1, v3, vcc
	v_add_co_u32_e32 v0, vcc, v0, v194
	s_nop 1
	v_addc_co_u32_e32 v1, vcc, 0, v1, vcc
	global_load_dwordx4 v[20:23], v[0:1], off
	v_add_u32_e32 v194, 0x4000, v194
	v_add_u32_e32 v195, 68, v192
	v_cmp_gt_u32_e32 vcc, 0x1000, v195
	v_mov_b32_e32 v0, s98
	v_mov_b32_e32 v1, s99
	v_mov_b32_e32 v3, s58
	v_cndmask_b32_e32 v0, v0, v3, vcc
	v_mov_b32_e32 v3, s59
	v_cndmask_b32_e32 v1, v1, v3, vcc
	v_add_co_u32_e32 v0, vcc, v0, v194
	s_nop 1
	v_addc_co_u32_e32 v1, vcc, 0, v1, vcc
	global_load_dwordx4 v[24:27], v[0:1], off
	v_add_u32_e32 v194, 0x4000, v194
	v_add_u32_e32 v195, 72, v192
	v_cmp_gt_u32_e32 vcc, 0x1000, v195
	v_mov_b32_e32 v0, s98
	v_mov_b32_e32 v1, s99
	v_mov_b32_e32 v3, s58
	v_cndmask_b32_e32 v0, v0, v3, vcc
	v_mov_b32_e32 v3, s59
	v_cndmask_b32_e32 v1, v1, v3, vcc
	v_add_co_u32_e32 v0, vcc, v0, v194
	s_nop 1
	v_addc_co_u32_e32 v1, vcc, 0, v1, vcc
	global_load_dwordx4 v[28:31], v[0:1], off
	v_add_u32_e32 v194, 0x4000, v194
	v_add_u32_e32 v195, 76, v192
	v_cmp_gt_u32_e32 vcc, 0x1000, v195
	v_mov_b32_e32 v0, s98
	v_mov_b32_e32 v1, s99
	v_mov_b32_e32 v3, s58
	v_cndmask_b32_e32 v0, v0, v3, vcc
	v_mov_b32_e32 v3, s59
	v_cndmask_b32_e32 v1, v1, v3, vcc
	v_add_co_u32_e32 v0, vcc, v0, v194
	s_nop 1
	v_addc_co_u32_e32 v1, vcc, 0, v1, vcc
	global_load_dwordx4 v[32:35], v[0:1], off
	v_add_u32_e32 v194, 0x4000, v194
	v_add_u32_e32 v195, 16, v192
	v_cmp_le_u32_e32 vcc, s7, v195
	s_waitcnt vmcnt(12)
	v_cndmask_b32_e32 v172, v148, v152, vcc
	v_cndmask_b32_e32 v173, v149, v153, vcc
	v_cndmask_b32_e32 v174, v150, v154, vcc
	v_cndmask_b32_e32 v175, v151, v155, vcc
	v_fmac_f32_e32 v116, v172, v156
	v_fmac_f32_e32 v117, v173, v157
	v_fmac_f32_e32 v118, v174, v158
	v_fmac_f32_e32 v119, v175, v159
	global_store_dwordx4 v197, v[116:119], s[56:57] sc0 sc1
	v_add_u32_e32 v197, 0x4000, v197
	v_add_u32_e32 v195, 20, v192
	v_cmp_le_u32_e32 vcc, s7, v195
	s_waitcnt vmcnt(13)
	s_waitcnt lgkmcnt(2)
	v_cndmask_b32_e32 v172, v148, v152, vcc
	v_cndmask_b32_e32 v173, v149, v153, vcc
	v_cndmask_b32_e32 v174, v150, v154, vcc
	v_cndmask_b32_e32 v175, v151, v155, vcc
	v_fmac_f32_e32 v120, v172, v160
	v_fmac_f32_e32 v121, v173, v161
	v_fmac_f32_e32 v122, v174, v162
	v_fmac_f32_e32 v123, v175, v163
	global_store_dwordx4 v197, v[120:123], s[56:57] sc0 sc1
	v_add_u32_e32 v197, 0x4000, v197
	v_add_u32_e32 v195, 24, v192
	v_cmp_le_u32_e32 vcc, s7, v195
	s_waitcnt vmcnt(14)
	s_waitcnt lgkmcnt(1)
	v_cndmask_b32_e32 v172, v148, v152, vcc
	v_cndmask_b32_e32 v173, v149, v153, vcc
	v_cndmask_b32_e32 v174, v150, v154, vcc
	v_cndmask_b32_e32 v175, v151, v155, vcc
	v_fmac_f32_e32 v124, v172, v164
	v_fmac_f32_e32 v125, v173, v165
	v_fmac_f32_e32 v126, v174, v166
	v_fmac_f32_e32 v127, v175, v167
	global_store_dwordx4 v197, v[124:127], s[56:57] sc0 sc1
	v_add_u32_e32 v197, 0x4000, v197
	v_add_u32_e32 v195, 28, v192
	v_cmp_le_u32_e32 vcc, s7, v195
	s_waitcnt vmcnt(15)
	s_waitcnt lgkmcnt(0)
	v_cndmask_b32_e32 v172, v148, v152, vcc
	v_cndmask_b32_e32 v173, v149, v153, vcc
	v_cndmask_b32_e32 v174, v150, v154, vcc
	v_cndmask_b32_e32 v175, v151, v155, vcc
	v_fmac_f32_e32 v128, v172, v168
	v_fmac_f32_e32 v129, v173, v169
	v_fmac_f32_e32 v130, v174, v170
	v_fmac_f32_e32 v131, v175, v171
	global_store_dwordx4 v197, v[128:131], s[56:57] sc0 sc1
	v_add_u32_e32 v197, 0x4000, v197
	ds_write_b32 v203, v36 offset:0
	ds_write_b32 v203, v37 offset:272
	ds_write_b32 v203, v38 offset:544
	ds_write_b32 v203, v39 offset:816
	ds_write_b32 v203, v40 offset:64
	ds_write_b32 v203, v41 offset:336
	ds_write_b32 v203, v42 offset:608
	ds_write_b32 v203, v43 offset:880
	ds_write_b32 v203, v44 offset:128
	ds_write_b32 v203, v45 offset:400
	ds_write_b32 v203, v46 offset:672
	ds_write_b32 v203, v47 offset:944
	ds_write_b32 v203, v48 offset:192
	ds_write_b32 v203, v49 offset:464
	ds_write_b32 v203, v50 offset:736
	ds_write_b32 v203, v51 offset:1008
	s_waitcnt lgkmcnt(0)
	ds_read_b128 v[156:159], v204 offset:0
	ds_read_b128 v[160:163], v204 offset:1088
	ds_read_b128 v[164:167], v204 offset:2176
	ds_read_b128 v[168:171], v204 offset:3264
	s_waitcnt lgkmcnt(0)
	v_add_u32_e32 v195, 80, v192
	v_cmp_gt_u32_e32 vcc, 0x1000, v195
	v_mov_b32_e32 v0, s98
	v_mov_b32_e32 v1, s99
	v_mov_b32_e32 v3, s58
	v_cndmask_b32_e32 v0, v0, v3, vcc
	v_mov_b32_e32 v3, s59
	v_cndmask_b32_e32 v1, v1, v3, vcc
	v_add_co_u32_e32 v0, vcc, v0, v194
	s_nop 1
	v_addc_co_u32_e32 v1, vcc, 0, v1, vcc
	global_load_dwordx4 v[36:39], v[0:1], off
	v_add_u32_e32 v194, 0x4000, v194
	v_add_u32_e32 v195, 84, v192
	v_cmp_gt_u32_e32 vcc, 0x1000, v195
	v_mov_b32_e32 v0, s98
	v_mov_b32_e32 v1, s99
	v_mov_b32_e32 v3, s58
	v_cndmask_b32_e32 v0, v0, v3, vcc
	v_mov_b32_e32 v3, s59
	v_cndmask_b32_e32 v1, v1, v3, vcc
	v_add_co_u32_e32 v0, vcc, v0, v194
	s_nop 1
	v_addc_co_u32_e32 v1, vcc, 0, v1, vcc
	global_load_dwordx4 v[40:43], v[0:1], off
	v_add_u32_e32 v194, 0x4000, v194
	v_add_u32_e32 v195, 88, v192
	v_cmp_gt_u32_e32 vcc, 0x1000, v195
	v_mov_b32_e32 v0, s98
	v_mov_b32_e32 v1, s99
	v_mov_b32_e32 v3, s58
	v_cndmask_b32_e32 v0, v0, v3, vcc
	v_mov_b32_e32 v3, s59
	v_cndmask_b32_e32 v1, v1, v3, vcc
	v_add_co_u32_e32 v0, vcc, v0, v194
	s_nop 1
	v_addc_co_u32_e32 v1, vcc, 0, v1, vcc
	global_load_dwordx4 v[44:47], v[0:1], off
	v_add_u32_e32 v194, 0x4000, v194
	v_add_u32_e32 v195, 92, v192
	v_cmp_gt_u32_e32 vcc, 0x1000, v195
	v_mov_b32_e32 v0, s98
	v_mov_b32_e32 v1, s99
	v_mov_b32_e32 v3, s58
	v_cndmask_b32_e32 v0, v0, v3, vcc
	v_mov_b32_e32 v3, s59
	v_cndmask_b32_e32 v1, v1, v3, vcc
	v_add_co_u32_e32 v0, vcc, v0, v194
	s_nop 1
	v_addc_co_u32_e32 v1, vcc, 0, v1, vcc
	global_load_dwordx4 v[48:51], v[0:1], off
	v_add_u32_e32 v194, 0x4000, v194
	v_add_u32_e32 v195, 32, v192
	v_cmp_le_u32_e32 vcc, s7, v195
	s_waitcnt vmcnt(20)
	v_cndmask_b32_e32 v172, v148, v152, vcc
	v_cndmask_b32_e32 v173, v149, v153, vcc
	v_cndmask_b32_e32 v174, v150, v154, vcc
	v_cndmask_b32_e32 v175, v151, v155, vcc
	v_fmac_f32_e32 v132, v172, v156
	v_fmac_f32_e32 v133, v173, v157
	v_fmac_f32_e32 v134, v174, v158
	v_fmac_f32_e32 v135, v175, v159
	global_store_dwordx4 v197, v[132:135], s[56:57] sc0 sc1
	v_add_u32_e32 v197, 0x4000, v197
	v_add_u32_e32 v195, 36, v192
	v_cmp_le_u32_e32 vcc, s7, v195
	s_waitcnt vmcnt(21)
	s_waitcnt lgkmcnt(2)
	v_cndmask_b32_e32 v172, v148, v152, vcc
	v_cndmask_b32_e32 v173, v149, v153, vcc
	v_cndmask_b32_e32 v174, v150, v154, vcc
	v_cndmask_b32_e32 v175, v151, v155, vcc
	v_fmac_f32_e32 v136, v172, v160
	v_fmac_f32_e32 v137, v173, v161
	v_fmac_f32_e32 v138, v174, v162
	v_fmac_f32_e32 v139, v175, v163
	global_store_dwordx4 v197, v[136:139], s[56:57] sc0 sc1
	v_add_u32_e32 v197, 0x4000, v197
	v_add_u32_e32 v195, 40, v192
	v_cmp_le_u32_e32 vcc, s7, v195
	s_waitcnt vmcnt(22)
	s_waitcnt lgkmcnt(1)
	v_cndmask_b32_e32 v172, v148, v152, vcc
	v_cndmask_b32_e32 v173, v149, v153, vcc
	v_cndmask_b32_e32 v174, v150, v154, vcc
	v_cndmask_b32_e32 v175, v151, v155, vcc
	v_fmac_f32_e32 v140, v172, v164
	v_fmac_f32_e32 v141, v173, v165
	v_fmac_f32_e32 v142, v174, v166
	v_fmac_f32_e32 v143, v175, v167
	global_store_dwordx4 v197, v[140:143], s[56:57] sc0 sc1
	v_add_u32_e32 v197, 0x4000, v197
	v_add_u32_e32 v195, 44, v192
	v_cmp_le_u32_e32 vcc, s7, v195
	s_waitcnt vmcnt(23)
	s_waitcnt lgkmcnt(0)
	v_cndmask_b32_e32 v172, v148, v152, vcc
	v_cndmask_b32_e32 v173, v149, v153, vcc
	v_cndmask_b32_e32 v174, v150, v154, vcc
	v_cndmask_b32_e32 v175, v151, v155, vcc
	v_fmac_f32_e32 v144, v172, v168
	v_fmac_f32_e32 v145, v173, v169
	v_fmac_f32_e32 v146, v174, v170
	v_fmac_f32_e32 v147, v175, v171
	global_store_dwordx4 v197, v[144:147], s[56:57] sc0 sc1
	v_add_u32_e32 v197, 0x4000, v197
	ds_write_b32 v203, v52 offset:0
	ds_write_b32 v203, v53 offset:272
	ds_write_b32 v203, v54 offset:544
	ds_write_b32 v203, v55 offset:816
	ds_write_b32 v203, v56 offset:64
	ds_write_b32 v203, v57 offset:336
	ds_write_b32 v203, v58 offset:608
	ds_write_b32 v203, v59 offset:880
	ds_write_b32 v203, v60 offset:128
	ds_write_b32 v203, v61 offset:400
	ds_write_b32 v203, v62 offset:672
	ds_write_b32 v203, v63 offset:944
	ds_write_b32 v203, v64 offset:192
	ds_write_b32 v203, v65 offset:464
	ds_write_b32 v203, v66 offset:736
	ds_write_b32 v203, v67 offset:1008
	s_waitcnt lgkmcnt(0)
	ds_read_b128 v[156:159], v204 offset:0
	ds_read_b128 v[160:163], v204 offset:1088
	ds_read_b128 v[164:167], v204 offset:2176
	ds_read_b128 v[168:171], v204 offset:3264
	v_add_u32_e32 v195, 48, v192
	v_cmp_le_u32_e32 vcc, s7, v195
	s_waitcnt vmcnt(23)
	s_waitcnt lgkmcnt(3)
	v_cndmask_b32_e32 v172, v148, v152, vcc
	v_cndmask_b32_e32 v173, v149, v153, vcc
	v_cndmask_b32_e32 v174, v150, v154, vcc
	v_cndmask_b32_e32 v175, v151, v155, vcc
	v_fmac_f32_e32 v4, v172, v156
	v_fmac_f32_e32 v5, v173, v157
	v_fmac_f32_e32 v6, v174, v158
	v_fmac_f32_e32 v7, v175, v159
	global_store_dwordx4 v197, v[4:7], s[56:57] sc0 sc1
	v_add_u32_e32 v197, 0x4000, v197
	v_add_u32_e32 v195, 52, v192
	v_cmp_le_u32_e32 vcc, s7, v195
	s_waitcnt vmcnt(23)
	s_waitcnt lgkmcnt(2)
	v_cndmask_b32_e32 v172, v148, v152, vcc
	v_cndmask_b32_e32 v173, v149, v153, vcc
	v_cndmask_b32_e32 v174, v150, v154, vcc
	v_cndmask_b32_e32 v175, v151, v155, vcc
	v_fmac_f32_e32 v8, v172, v160
	v_fmac_f32_e32 v9, v173, v161
	v_fmac_f32_e32 v10, v174, v162
	v_fmac_f32_e32 v11, v175, v163
	global_store_dwordx4 v197, v[8:11], s[56:57] sc0 sc1
	v_add_u32_e32 v197, 0x4000, v197
	v_add_u32_e32 v195, 56, v192
	v_cmp_le_u32_e32 vcc, s7, v195
	s_waitcnt vmcnt(23)
	s_waitcnt lgkmcnt(1)
	v_cndmask_b32_e32 v172, v148, v152, vcc
	v_cndmask_b32_e32 v173, v149, v153, vcc
	v_cndmask_b32_e32 v174, v150, v154, vcc
	v_cndmask_b32_e32 v175, v151, v155, vcc
	v_fmac_f32_e32 v12, v172, v164
	v_fmac_f32_e32 v13, v173, v165
	v_fmac_f32_e32 v14, v174, v166
	v_fmac_f32_e32 v15, v175, v167
	global_store_dwordx4 v197, v[12:15], s[56:57] sc0 sc1
	v_add_u32_e32 v197, 0x4000, v197
	v_add_u32_e32 v195, 60, v192
	v_cmp_le_u32_e32 vcc, s7, v195
	s_waitcnt vmcnt(23)
	s_waitcnt lgkmcnt(0)
	v_cndmask_b32_e32 v172, v148, v152, vcc
	v_cndmask_b32_e32 v173, v149, v153, vcc
	v_cndmask_b32_e32 v174, v150, v154, vcc
	v_cndmask_b32_e32 v175, v151, v155, vcc
	v_fmac_f32_e32 v16, v172, v168
	v_fmac_f32_e32 v17, v173, v169
	v_fmac_f32_e32 v18, v174, v170
	v_fmac_f32_e32 v19, v175, v171
	global_store_dwordx4 v197, v[16:19], s[56:57] sc0 sc1
	v_add_u32_e32 v197, 0x4000, v197
	ds_write_b32 v203, v68 offset:0
	ds_write_b32 v203, v69 offset:272
	ds_write_b32 v203, v70 offset:544
	ds_write_b32 v203, v71 offset:816
	ds_write_b32 v203, v72 offset:64
	ds_write_b32 v203, v73 offset:336
	ds_write_b32 v203, v74 offset:608
	ds_write_b32 v203, v75 offset:880
	ds_write_b32 v203, v76 offset:128
	ds_write_b32 v203, v77 offset:400
	ds_write_b32 v203, v78 offset:672
	ds_write_b32 v203, v79 offset:944
	ds_write_b32 v203, v80 offset:192
	ds_write_b32 v203, v81 offset:464
	ds_write_b32 v203, v82 offset:736
	ds_write_b32 v203, v83 offset:1008
	s_waitcnt lgkmcnt(0)
	ds_read_b128 v[156:159], v204 offset:0
	ds_read_b128 v[160:163], v204 offset:1088
	ds_read_b128 v[164:167], v204 offset:2176
	ds_read_b128 v[168:171], v204 offset:3264
	v_add_u32_e32 v195, 64, v192
	v_cmp_le_u32_e32 vcc, s7, v195
	s_waitcnt vmcnt(19)
	s_waitcnt lgkmcnt(3)
	v_cndmask_b32_e32 v172, v148, v152, vcc
	v_cndmask_b32_e32 v173, v149, v153, vcc
	v_cndmask_b32_e32 v174, v150, v154, vcc
	v_cndmask_b32_e32 v175, v151, v155, vcc
	v_fmac_f32_e32 v20, v172, v156
	v_fmac_f32_e32 v21, v173, v157
	v_fmac_f32_e32 v22, v174, v158
	v_fmac_f32_e32 v23, v175, v159
	global_store_dwordx4 v197, v[20:23], s[56:57] sc0 sc1
	v_add_u32_e32 v197, 0x4000, v197
	v_add_u32_e32 v195, 68, v192
	v_cmp_le_u32_e32 vcc, s7, v195
	s_waitcnt vmcnt(19)
	s_waitcnt lgkmcnt(2)
	v_cndmask_b32_e32 v172, v148, v152, vcc
	v_cndmask_b32_e32 v173, v149, v153, vcc
	v_cndmask_b32_e32 v174, v150, v154, vcc
	v_cndmask_b32_e32 v175, v151, v155, vcc
	v_fmac_f32_e32 v24, v172, v160
	v_fmac_f32_e32 v25, v173, v161
	v_fmac_f32_e32 v26, v174, v162
	v_fmac_f32_e32 v27, v175, v163
	global_store_dwordx4 v197, v[24:27], s[56:57] sc0 sc1
	v_add_u32_e32 v197, 0x4000, v197
	v_add_u32_e32 v195, 72, v192
	v_cmp_le_u32_e32 vcc, s7, v195
	s_waitcnt vmcnt(19)
	s_waitcnt lgkmcnt(1)
	v_cndmask_b32_e32 v172, v148, v152, vcc
	v_cndmask_b32_e32 v173, v149, v153, vcc
	v_cndmask_b32_e32 v174, v150, v154, vcc
	v_cndmask_b32_e32 v175, v151, v155, vcc
	v_fmac_f32_e32 v28, v172, v164
	v_fmac_f32_e32 v29, v173, v165
	v_fmac_f32_e32 v30, v174, v166
	v_fmac_f32_e32 v31, v175, v167
	global_store_dwordx4 v197, v[28:31], s[56:57] sc0 sc1
	v_add_u32_e32 v197, 0x4000, v197
	v_add_u32_e32 v195, 76, v192
	v_cmp_le_u32_e32 vcc, s7, v195
	s_waitcnt vmcnt(19)
	s_waitcnt lgkmcnt(0)
	v_cndmask_b32_e32 v172, v148, v152, vcc
	v_cndmask_b32_e32 v173, v149, v153, vcc
	v_cndmask_b32_e32 v174, v150, v154, vcc
	v_cndmask_b32_e32 v175, v151, v155, vcc
	v_fmac_f32_e32 v32, v172, v168
	v_fmac_f32_e32 v33, v173, v169
	v_fmac_f32_e32 v34, v174, v170
	v_fmac_f32_e32 v35, v175, v171
	global_store_dwordx4 v197, v[32:35], s[56:57] sc0 sc1
	v_add_u32_e32 v197, 0x4000, v197
	ds_write_b32 v203, v84 offset:0
	ds_write_b32 v203, v85 offset:272
	ds_write_b32 v203, v86 offset:544
	ds_write_b32 v203, v87 offset:816
	ds_write_b32 v203, v88 offset:64
	ds_write_b32 v203, v89 offset:336
	ds_write_b32 v203, v90 offset:608
	ds_write_b32 v203, v91 offset:880
	ds_write_b32 v203, v92 offset:128
	ds_write_b32 v203, v93 offset:400
	ds_write_b32 v203, v94 offset:672
	ds_write_b32 v203, v95 offset:944
	ds_write_b32 v203, v96 offset:192
	ds_write_b32 v203, v97 offset:464
	ds_write_b32 v203, v98 offset:736
	ds_write_b32 v203, v99 offset:1008
	s_waitcnt lgkmcnt(0)
	ds_read_b128 v[156:159], v204 offset:0
	ds_read_b128 v[160:163], v204 offset:1088
	ds_read_b128 v[164:167], v204 offset:2176
	ds_read_b128 v[168:171], v204 offset:3264
	v_add_u32_e32 v195, 80, v192
	v_cmp_le_u32_e32 vcc, s7, v195
	s_waitcnt vmcnt(15)
	s_waitcnt lgkmcnt(3)
	v_cndmask_b32_e32 v172, v148, v152, vcc
	v_cndmask_b32_e32 v173, v149, v153, vcc
	v_cndmask_b32_e32 v174, v150, v154, vcc
	v_cndmask_b32_e32 v175, v151, v155, vcc
	v_fmac_f32_e32 v36, v172, v156
	v_fmac_f32_e32 v37, v173, v157
	v_fmac_f32_e32 v38, v174, v158
	v_fmac_f32_e32 v39, v175, v159
	global_store_dwordx4 v197, v[36:39], s[56:57] sc0 sc1
	v_add_u32_e32 v197, 0x4000, v197
	v_add_u32_e32 v195, 84, v192
	v_cmp_le_u32_e32 vcc, s7, v195
	s_waitcnt vmcnt(15)
	s_waitcnt lgkmcnt(2)
	v_cndmask_b32_e32 v172, v148, v152, vcc
	v_cndmask_b32_e32 v173, v149, v153, vcc
	v_cndmask_b32_e32 v174, v150, v154, vcc
	v_cndmask_b32_e32 v175, v151, v155, vcc
	v_fmac_f32_e32 v40, v172, v160
	v_fmac_f32_e32 v41, v173, v161
	v_fmac_f32_e32 v42, v174, v162
	v_fmac_f32_e32 v43, v175, v163
	global_store_dwordx4 v197, v[40:43], s[56:57] sc0 sc1
	v_add_u32_e32 v197, 0x4000, v197
	v_add_u32_e32 v195, 88, v192
	v_cmp_le_u32_e32 vcc, s7, v195
	s_waitcnt vmcnt(15)
	s_waitcnt lgkmcnt(1)
	v_cndmask_b32_e32 v172, v148, v152, vcc
	v_cndmask_b32_e32 v173, v149, v153, vcc
	v_cndmask_b32_e32 v174, v150, v154, vcc
	v_cndmask_b32_e32 v175, v151, v155, vcc
	v_fmac_f32_e32 v44, v172, v164
	v_fmac_f32_e32 v45, v173, v165
	v_fmac_f32_e32 v46, v174, v166
	v_fmac_f32_e32 v47, v175, v167
	global_store_dwordx4 v197, v[44:47], s[56:57] sc0 sc1
	v_add_u32_e32 v197, 0x4000, v197
	v_add_u32_e32 v195, 92, v192
	v_cmp_le_u32_e32 vcc, s7, v195
	s_waitcnt vmcnt(15)
	s_waitcnt lgkmcnt(0)
	v_cndmask_b32_e32 v172, v148, v152, vcc
	v_cndmask_b32_e32 v173, v149, v153, vcc
	v_cndmask_b32_e32 v174, v150, v154, vcc
	v_cndmask_b32_e32 v175, v151, v155, vcc
	v_fmac_f32_e32 v48, v172, v168
	v_fmac_f32_e32 v49, v173, v169
	v_fmac_f32_e32 v50, v174, v170
	v_fmac_f32_e32 v51, v175, v171
	global_store_dwordx4 v197, v[48:51], s[56:57] sc0 sc1
	v_add_u32_e32 v197, 0x4000, v197
	v_mov_b32_e32 v4, 0
	v_mov_b32_e32 v5, 0
	v_mov_b32_e32 v6, 0
	v_mov_b32_e32 v7, 0
	v_mov_b32_e32 v8, 0
	v_mov_b32_e32 v9, 0
	v_mov_b32_e32 v10, 0
	v_mov_b32_e32 v11, 0
	v_mov_b32_e32 v12, 0
	v_mov_b32_e32 v13, 0
	v_mov_b32_e32 v14, 0
	v_mov_b32_e32 v15, 0
	v_mov_b32_e32 v16, 0
	v_mov_b32_e32 v17, 0
	v_mov_b32_e32 v18, 0
	v_mov_b32_e32 v19, 0
	v_mov_b32_e32 v20, 0
	v_mov_b32_e32 v21, 0
	v_mov_b32_e32 v22, 0
	v_mov_b32_e32 v23, 0
	v_mov_b32_e32 v24, 0
	v_mov_b32_e32 v25, 0
	v_mov_b32_e32 v26, 0
	v_mov_b32_e32 v27, 0
	v_mov_b32_e32 v28, 0
	v_mov_b32_e32 v29, 0
	v_mov_b32_e32 v30, 0
	v_mov_b32_e32 v31, 0
	v_mov_b32_e32 v32, 0
	v_mov_b32_e32 v33, 0
	v_mov_b32_e32 v34, 0
	v_mov_b32_e32 v35, 0
	v_mov_b32_e32 v36, 0
	v_mov_b32_e32 v37, 0
	v_mov_b32_e32 v38, 0
	v_mov_b32_e32 v39, 0
	v_mov_b32_e32 v40, 0
	v_mov_b32_e32 v41, 0
	v_mov_b32_e32 v42, 0
	v_mov_b32_e32 v43, 0
	v_mov_b32_e32 v44, 0
	v_mov_b32_e32 v45, 0
	v_mov_b32_e32 v46, 0
	v_mov_b32_e32 v47, 0
	v_mov_b32_e32 v48, 0
	v_mov_b32_e32 v49, 0
	v_mov_b32_e32 v50, 0
	v_mov_b32_e32 v51, 0
	v_mov_b32_e32 v52, 0
	v_mov_b32_e32 v53, 0
	v_mov_b32_e32 v54, 0
	v_mov_b32_e32 v55, 0
	v_mov_b32_e32 v56, 0
	v_mov_b32_e32 v57, 0
	v_mov_b32_e32 v58, 0
	v_mov_b32_e32 v59, 0
	v_mov_b32_e32 v60, 0
	v_mov_b32_e32 v61, 0
	v_mov_b32_e32 v62, 0
	v_mov_b32_e32 v63, 0
	v_mov_b32_e32 v64, 0
	v_mov_b32_e32 v65, 0
	v_mov_b32_e32 v66, 0
	v_mov_b32_e32 v67, 0
	v_mov_b32_e32 v68, 0
	v_mov_b32_e32 v69, 0
	v_mov_b32_e32 v70, 0
	v_mov_b32_e32 v71, 0
	v_mov_b32_e32 v72, 0
	v_mov_b32_e32 v73, 0
	v_mov_b32_e32 v74, 0
	v_mov_b32_e32 v75, 0
	v_mov_b32_e32 v76, 0
	v_mov_b32_e32 v77, 0
	v_mov_b32_e32 v78, 0
	v_mov_b32_e32 v79, 0
	v_mov_b32_e32 v80, 0
	v_mov_b32_e32 v81, 0
	v_mov_b32_e32 v82, 0
	v_mov_b32_e32 v83, 0
	v_mov_b32_e32 v84, 0
	v_mov_b32_e32 v85, 0
	v_mov_b32_e32 v86, 0
	v_mov_b32_e32 v87, 0
	v_mov_b32_e32 v88, 0
	v_mov_b32_e32 v89, 0
	v_mov_b32_e32 v90, 0
	v_mov_b32_e32 v91, 0
	v_mov_b32_e32 v92, 0
	v_mov_b32_e32 v93, 0
	v_mov_b32_e32 v94, 0
	v_mov_b32_e32 v95, 0
	v_mov_b32_e32 v96, 0
	v_mov_b32_e32 v97, 0
	v_mov_b32_e32 v98, 0
	v_mov_b32_e32 v99, 0
	s_mov_b32 s34, 0
	s_add_u32 s35, s35, s52
	s_cmp_ge_u32 s31, s30
	s_cbranch_scc1 .Lgm_f2_exit

.Lgm_wo_cnt:
	s_add_u32 s30, s30, 16
	s_add_u32 s4, s4, s52
	s_cmp_lt_u32 s4, s54
	s_cbranch_scc1 .Lgm_wo_cnt
	s_add_u32 s48, s96, 0x7084000
	s_addc_u32 s49, s97, 0
	s_mul_i32 s4, s36, 0x200000
	s_add_u32 s50, s96, 0x980000
	s_addc_u32 s51, s97, 0
	s_add_u32 s50, s50, s4
	s_addc_u32 s51, s51, 0
	v_and_b32_e32 v0, 63, v206
	v_lshrrev_b32_e32 v1, 6, v206
	s_mov_b32 s31, 0
	v_readfirstlane_b32 s42, v1
	s_nop 0
	s_cmp_ge_u32 s42, 4
	s_cbranch_scc1 .Lgm_wo_compute
	v_lshrrev_b32_e32 v3, 3, v0
	v_and_b32_e32 v4, 7, v0
	v_xor_b32_e32 v4, v4, v3
	v_lshl_add_u32 v3, v1, 3, v3
	v_lshlrev_b32_e32 v3, 11, v3
	v_lshl_add_u32 v180, v4, 4, v3
	v_add_u32_e32 v181, 0x10000, v180
	v_add_u32_e32 v182, 0x20000, v180
	v_add_u32_e32 v183, 0x30000, v180
	v_add_u32_e32 v184, 0x40000, v180
	v_add_u32_e32 v185, 0x50000, v180
	s_lshl_b32 s42, s42, 10
	s_mov_b32 s38, s53
	s_mov_b32 s39, 0
	s_mov_b32 s41, s42
	s_and_b32 s4, s38, 31
	s_lshr_b32 s5, s38, 5
	s_mul_i32 s4, s4, 0x60000
	s_add_u32 s44, s48, s4
	s_addc_u32 s45, s49, 0
	s_mul_i32 s4, s5, 0x40000
	s_add_u32 s46, s50, s4
	s_addc_u32 s47, s51, 0
	s_add_u32 m0, s41, 0x0
	s_nop 0
	global_load_lds_dwordx4 v180, s[44:45]
	s_add_u32 m0, s41, 0x1000
	s_nop 0
	global_load_lds_dwordx4 v181, s[44:45]
	s_add_u32 m0, s41, 0x2000
	s_nop 0
	global_load_lds_dwordx4 v182, s[44:45]
	s_add_u32 m0, s41, 0x3000
	s_nop 0
	global_load_lds_dwordx4 v183, s[44:45]
	s_add_u32 m0, s41, 0x4000
	s_nop 0
	global_load_lds_dwordx4 v184, s[44:45]
	s_add_u32 m0, s41, 0x5000
	s_nop 0
	global_load_lds_dwordx4 v185, s[44:45]
	s_add_u32 m0, s41, 0x6000
	s_nop 0
	global_load_lds_dwordx4 v180, s[46:47]
	s_add_u32 m0, s41, 0x7000
	s_nop 0
	global_load_lds_dwordx4 v181, s[46:47]
	s_add_u32 m0, s41, 0x8000
	s_nop 0
	global_load_lds_dwordx4 v182, s[46:47]
	s_add_u32 m0, s41, 0x9000
	s_nop 0
	global_load_lds_dwordx4 v183, s[46:47]
	s_add_u32 s39, s39, 1
	s_add_u32 s44, s44, 0x80
	s_addc_u32 s45, s45, 0
	s_add_u32 s46, s46, 0x80
	s_addc_u32 s47, s47, 0
	s_cmp_lt_u32 s39, 16
	s_cbranch_scc1 .Lgm_wo_dadv1
	s_mov_b32 s39, 0
	s_add_u32 s4, s38, s52
	s_cmp_lt_u32 s4, s54
	s_cselect_b32 s38, s4, s38
	s_and_b32 s4, s38, 31
	s_lshr_b32 s5, s38, 5
	s_mul_i32 s4, s4, 0x60000
	s_add_u32 s44, s48, s4
	s_addc_u32 s45, s49, 0
	s_mul_i32 s4, s5, 0x40000
	s_add_u32 s46, s50, s4
	s_addc_u32 s47, s51, 0

.Lgm_wo_join:
	s_waitcnt lgkmcnt(13)
	v_mfma_f32_16x16x32_bf16 v[4:7], v[100:103], v[124:127], v[4:7]
	v_mfma_f32_16x16x32_bf16 v[20:23], v[104:107], v[124:127], v[20:23]
	v_mfma_f32_16x16x32_bf16 v[36:39], v[108:111], v[124:127], v[36:39]
	v_mfma_f32_16x16x32_bf16 v[52:55], v[112:115], v[124:127], v[52:55]
	v_mfma_f32_16x16x32_bf16 v[68:71], v[116:119], v[124:127], v[68:71]
	v_mfma_f32_16x16x32_bf16 v[84:87], v[120:123], v[124:127], v[84:87]
	s_waitcnt lgkmcnt(12)
	v_mfma_f32_16x16x32_bf16 v[8:11], v[100:103], v[128:131], v[8:11]
	v_mfma_f32_16x16x32_bf16 v[24:27], v[104:107], v[128:131], v[24:27]
	v_mfma_f32_16x16x32_bf16 v[40:43], v[108:111], v[128:131], v[40:43]
	v_mfma_f32_16x16x32_bf16 v[56:59], v[112:115], v[128:131], v[56:59]
	v_mfma_f32_16x16x32_bf16 v[72:75], v[116:119], v[128:131], v[72:75]
	v_mfma_f32_16x16x32_bf16 v[88:91], v[120:123], v[128:131], v[88:91]
	s_waitcnt lgkmcnt(11)
	v_mfma_f32_16x16x32_bf16 v[12:15], v[100:103], v[132:135], v[12:15]
	v_mfma_f32_16x16x32_bf16 v[28:31], v[104:107], v[132:135], v[28:31]
	v_mfma_f32_16x16x32_bf16 v[44:47], v[108:111], v[132:135], v[44:47]
	v_mfma_f32_16x16x32_bf16 v[60:63], v[112:115], v[132:135], v[60:63]
	v_mfma_f32_16x16x32_bf16 v[76:79], v[116:119], v[132:135], v[76:79]
	v_mfma_f32_16x16x32_bf16 v[92:95], v[120:123], v[132:135], v[92:95]
	s_waitcnt lgkmcnt(10)
	v_mfma_f32_16x16x32_bf16 v[16:19], v[100:103], v[136:139], v[16:19]
	v_mfma_f32_16x16x32_bf16 v[32:35], v[104:107], v[136:139], v[32:35]
	v_mfma_f32_16x16x32_bf16 v[48:51], v[108:111], v[136:139], v[48:51]
	v_mfma_f32_16x16x32_bf16 v[64:67], v[112:115], v[136:139], v[64:67]
	v_mfma_f32_16x16x32_bf16 v[80:83], v[116:119], v[136:139], v[80:83]
	v_mfma_f32_16x16x32_bf16 v[96:99], v[120:123], v[136:139], v[96:99]
	s_waitcnt lgkmcnt(0)
	s_add_u32 s34, s34, 1
	s_add_u32 s31, s31, 1
	s_cmp_lt_u32 s34, 16
	s_cbranch_scc1 .Lgm_wo_rot
	v_mfma_f32_16x16x32_bf16 v[4:7], v[140:143], v[164:167], v[4:7]
	v_mfma_f32_16x16x32_bf16 v[20:23], v[144:147], v[164:167], v[20:23]
	v_mfma_f32_16x16x32_bf16 v[36:39], v[148:151], v[164:167], v[36:39]
	v_mfma_f32_16x16x32_bf16 v[52:55], v[152:155], v[164:167], v[52:55]
	v_mfma_f32_16x16x32_bf16 v[68:71], v[156:159], v[164:167], v[68:71]
	v_mfma_f32_16x16x32_bf16 v[84:87], v[160:163], v[164:167], v[84:87]
	v_mfma_f32_16x16x32_bf16 v[8:11], v[140:143], v[168:171], v[8:11]
	v_mfma_f32_16x16x32_bf16 v[24:27], v[144:147], v[168:171], v[24:27]
	v_mfma_f32_16x16x32_bf16 v[40:43], v[148:151], v[168:171], v[40:43]
	v_mfma_f32_16x16x32_bf16 v[56:59], v[152:155], v[168:171], v[56:59]
	v_mfma_f32_16x16x32_bf16 v[72:75], v[156:159], v[168:171], v[72:75]
	v_mfma_f32_16x16x32_bf16 v[88:91], v[160:163], v[168:171], v[88:91]
	v_mfma_f32_16x16x32_bf16 v[12:15], v[140:143], v[172:175], v[12:15]
	v_mfma_f32_16x16x32_bf16 v[28:31], v[144:147], v[172:175], v[28:31]
	v_mfma_f32_16x16x32_bf16 v[44:47], v[148:151], v[172:175], v[44:47]
	v_mfma_f32_16x16x32_bf16 v[60:63], v[152:155], v[172:175], v[60:63]
	v_mfma_f32_16x16x32_bf16 v[76:79], v[156:159], v[172:175], v[76:79]
	v_mfma_f32_16x16x32_bf16 v[92:95], v[160:163], v[172:175], v[92:95]
	v_mfma_f32_16x16x32_bf16 v[16:19], v[140:143], v[176:179], v[16:19]
	v_mfma_f32_16x16x32_bf16 v[32:35], v[144:147], v[176:179], v[32:35]
	v_mfma_f32_16x16x32_bf16 v[48:51], v[148:151], v[176:179], v[48:51]
	v_mfma_f32_16x16x32_bf16 v[64:67], v[152:155], v[176:179], v[64:67]
	v_mfma_f32_16x16x32_bf16 v[80:83], v[156:159], v[176:179], v[80:83]
	v_mfma_f32_16x16x32_bf16 v[96:99], v[160:163], v[176:179], v[96:99]
	s_and_b32 s6, s35, 31
	s_lshr_b32 s7, s35, 5
	s_mul_i32 s6, s6, 192
	s_lshl_b32 s7, s7, 7
	s_nop 7
	s_mul_i32 s4, s6, 0x1000
	s_lshl_b32 s5, s7, 2
	s_add_u32 s4, s4, s5
	v_add_u32_e32 v197, s4, v205
	v_add_u32_e32 v192, s6, v190
	v_lshl_add_u32 v193, s7, 2, v191
	s_sub_i32 s4, s6, 0xc00
	s_max_i32 s4, s4, 0
	s_lshr_b32 s4, s4, 10
	s_add_i32 s5, s6, -2881
	s_max_i32 s5, s5, 0
	s_lshr_b32 s5, s5, 10
	s_movk_i32 s7, 0x1400
	s_cmp_eq_u32 s4, 0
	s_cselect_b32 s7, 0x1000, s7
	s_mul_i32 s4, s4, 0x6000
	s_mul_i32 s5, s5, 0x6000
	v_mov_b32_e32 v194, v197
	v_add_u32_e32 v195, 0, v192
	v_cmp_gt_u32_e32 vcc, 0x1000, v195
	v_mov_b32_e32 v0, s98
	v_mov_b32_e32 v1, s99
	v_mov_b32_e32 v3, s58
	v_cndmask_b32_e32 v0, v0, v3, vcc
	v_mov_b32_e32 v3, s59
	v_cndmask_b32_e32 v1, v1, v3, vcc
	v_add_co_u32_e32 v0, vcc, v0, v194
	s_nop 1
	v_addc_co_u32_e32 v1, vcc, 0, v1, vcc
	global_load_dwordx4 v[100:103], v[0:1], off
	v_add_u32_e32 v194, 0x4000, v194
	v_add_u32_e32 v195, 4, v192
	v_cmp_gt_u32_e32 vcc, 0x1000, v195
	v_mov_b32_e32 v0, s98
	v_mov_b32_e32 v1, s99
	v_mov_b32_e32 v3, s58
	v_cndmask_b32_e32 v0, v0, v3, vcc
	v_mov_b32_e32 v3, s59
	v_cndmask_b32_e32 v1, v1, v3, vcc
	v_add_co_u32_e32 v0, vcc, v0, v194
	s_nop 1
	v_addc_co_u32_e32 v1, vcc, 0, v1, vcc
	global_load_dwordx4 v[104:107], v[0:1], off
	v_add_u32_e32 v194, 0x4000, v194
	v_add_u32_e32 v195, 8, v192
	v_cmp_gt_u32_e32 vcc, 0x1000, v195
	v_mov_b32_e32 v0, s98
	v_mov_b32_e32 v1, s99
	v_mov_b32_e32 v3, s58
	v_cndmask_b32_e32 v0, v0, v3, vcc
	v_mov_b32_e32 v3, s59
	v_cndmask_b32_e32 v1, v1, v3, vcc
	v_add_co_u32_e32 v0, vcc, v0, v194
	s_nop 1
	v_addc_co_u32_e32 v1, vcc, 0, v1, vcc
	global_load_dwordx4 v[108:111], v[0:1], off
	v_add_u32_e32 v194, 0x4000, v194
	v_add_u32_e32 v195, 12, v192
	v_cmp_gt_u32_e32 vcc, 0x1000, v195
	v_mov_b32_e32 v0, s98
	v_mov_b32_e32 v1, s99
	v_mov_b32_e32 v3, s58
	v_cndmask_b32_e32 v0, v0, v3, vcc
	v_mov_b32_e32 v3, s59
	v_cndmask_b32_e32 v1, v1, v3, vcc
	v_add_co_u32_e32 v0, vcc, v0, v194
	s_nop 1
	v_addc_co_u32_e32 v1, vcc, 0, v1, vcc
	global_load_dwordx4 v[112:115], v[0:1], off
	v_add_u32_e32 v194, 0x4000, v194
	v_add_u32_e32 v195, 16, v192
	v_cmp_gt_u32_e32 vcc, 0x1000, v195
	v_mov_b32_e32 v0, s98
	v_mov_b32_e32 v1, s99
	v_mov_b32_e32 v3, s58
	v_cndmask_b32_e32 v0, v0, v3, vcc
	v_mov_b32_e32 v3, s59
	v_cndmask_b32_e32 v1, v1, v3, vcc
	v_add_co_u32_e32 v0, vcc, v0, v194
	s_nop 1
	v_addc_co_u32_e32 v1, vcc, 0, v1, vcc
	global_load_dwordx4 v[116:119], v[0:1], off
	v_add_u32_e32 v194, 0x4000, v194
	v_add_u32_e32 v195, 20, v192
	v_cmp_gt_u32_e32 vcc, 0x1000, v195
	v_mov_b32_e32 v0, s98
	v_mov_b32_e32 v1, s99
	v_mov_b32_e32 v3, s58
	v_cndmask_b32_e32 v0, v0, v3, vcc
	v_mov_b32_e32 v3, s59
	v_cndmask_b32_e32 v1, v1, v3, vcc
	v_add_co_u32_e32 v0, vcc, v0, v194
	s_nop 1
	v_addc_co_u32_e32 v1, vcc, 0, v1, vcc
	global_load_dwordx4 v[120:123], v[0:1], off
	v_add_u32_e32 v194, 0x4000, v194
	v_add_u32_e32 v195, 24, v192
	v_cmp_gt_u32_e32 vcc, 0x1000, v195
	v_mov_b32_e32 v0, s98
	v_mov_b32_e32 v1, s99
	v_mov_b32_e32 v3, s58
	v_cndmask_b32_e32 v0, v0, v3, vcc
	v_mov_b32_e32 v3, s59
	v_cndmask_b32_e32 v1, v1, v3, vcc
	v_add_co_u32_e32 v0, vcc, v0, v194
	s_nop 1
	v_addc_co_u32_e32 v1, vcc, 0, v1, vcc
	global_load_dwordx4 v[124:127], v[0:1], off
	v_add_u32_e32 v194, 0x4000, v194
	v_add_u32_e32 v195, 28, v192
	v_cmp_gt_u32_e32 vcc, 0x1000, v195
	v_mov_b32_e32 v0, s98
	v_mov_b32_e32 v1, s99
	v_mov_b32_e32 v3, s58
	v_cndmask_b32_e32 v0, v0, v3, vcc
	v_mov_b32_e32 v3, s59
	v_cndmask_b32_e32 v1, v1, v3, vcc
	v_add_co_u32_e32 v0, vcc, v0, v194
	s_nop 1
	v_addc_co_u32_e32 v1, vcc, 0, v1, vcc
	global_load_dwordx4 v[128:131], v[0:1], off
	v_add_u32_e32 v194, 0x4000, v194
	v_add_u32_e32 v195, 32, v192
	v_cmp_gt_u32_e32 vcc, 0x1000, v195
	v_mov_b32_e32 v0, s98
	v_mov_b32_e32 v1, s99
	v_mov_b32_e32 v3, s58
	v_cndmask_b32_e32 v0, v0, v3, vcc
	v_mov_b32_e32 v3, s59
	v_cndmask_b32_e32 v1, v1, v3, vcc
	v_add_co_u32_e32 v0, vcc, v0, v194
	s_nop 1
	v_addc_co_u32_e32 v1, vcc, 0, v1, vcc
	global_load_dwordx4 v[132:135], v[0:1], off
	v_add_u32_e32 v194, 0x4000, v194
	v_add_u32_e32 v195, 36, v192
	v_cmp_gt_u32_e32 vcc, 0x1000, v195
	v_mov_b32_e32 v0, s98
	v_mov_b32_e32 v1, s99
	v_mov_b32_e32 v3, s58
	v_cndmask_b32_e32 v0, v0, v3, vcc
	v_mov_b32_e32 v3, s59
	v_cndmask_b32_e32 v1, v1, v3, vcc
	v_add_co_u32_e32 v0, vcc, v0, v194
	s_nop 1
	v_addc_co_u32_e32 v1, vcc, 0, v1, vcc
	global_load_dwordx4 v[136:139], v[0:1], off
	v_add_u32_e32 v194, 0x4000, v194
	v_add_u32_e32 v195, 40, v192
	v_cmp_gt_u32_e32 vcc, 0x1000, v195
	v_mov_b32_e32 v0, s98
	v_mov_b32_e32 v1, s99
	v_mov_b32_e32 v3, s58
	v_cndmask_b32_e32 v0, v0, v3, vcc
	v_mov_b32_e32 v3, s59
	v_cndmask_b32_e32 v1, v1, v3, vcc
	v_add_co_u32_e32 v0, vcc, v0, v194
	s_nop 1
	v_addc_co_u32_e32 v1, vcc, 0, v1, vcc
	global_load_dwordx4 v[140:143], v[0:1], off
	v_add_u32_e32 v194, 0x4000, v194
	v_add_u32_e32 v195, 44, v192
	v_cmp_gt_u32_e32 vcc, 0x1000, v195
	v_mov_b32_e32 v0, s98
	v_mov_b32_e32 v1, s99
	v_mov_b32_e32 v3, s58
	v_cndmask_b32_e32 v0, v0, v3, vcc
	v_mov_b32_e32 v3, s59
	v_cndmask_b32_e32 v1, v1, v3, vcc
	v_add_co_u32_e32 v0, vcc, v0, v194
	s_nop 1
	v_addc_co_u32_e32 v1, vcc, 0, v1, vcc
	global_load_dwordx4 v[144:147], v[0:1], off
	v_add_u32_e32 v194, 0x4000, v194
	v_add_u32_e32 v195, s4, v193
	global_load_dwordx4 v[148:151], v195, s[100:101]
	v_add_u32_e32 v195, s5, v193
	global_load_dwordx4 v[152:155], v195, s[100:101]
	ds_write_b32 v203, v4 offset:0
	ds_write_b32 v203, v5 offset:272
	ds_write_b32 v203, v6 offset:544
	ds_write_b32 v203, v7 offset:816
	ds_write_b32 v203, v8 offset:64
	ds_write_b32 v203, v9 offset:336
	ds_write_b32 v203, v10 offset:608
	ds_write_b32 v203, v11 offset:880
	ds_write_b32 v203, v12 offset:128
	ds_write_b32 v203, v13 offset:400
	ds_write_b32 v203, v14 offset:672
	ds_write_b32 v203, v15 offset:944
	ds_write_b32 v203, v16 offset:192
	ds_write_b32 v203, v17 offset:464
	ds_write_b32 v203, v18 offset:736
	ds_write_b32 v203, v19 offset:1008
	s_waitcnt lgkmcnt(0)
	ds_read_b128 v[156:159], v204 offset:0
	ds_read_b128 v[160:163], v204 offset:1088
	ds_read_b128 v[164:167], v204 offset:2176
	ds_read_b128 v[168:171], v204 offset:3264
	s_waitcnt lgkmcnt(0)
	v_add_u32_e32 v195, 48, v192
	v_cmp_gt_u32_e32 vcc, 0x1000, v195
	v_mov_b32_e32 v0, s98
	v_mov_b32_e32 v1, s99
	v_mov_b32_e32 v3, s58
	v_cndmask_b32_e32 v0, v0, v3, vcc
	v_mov_b32_e32 v3, s59
	v_cndmask_b32_e32 v1, v1, v3, vcc
	v_add_co_u32_e32 v0, vcc, v0, v194
	s_nop 1
	v_addc_co_u32_e32 v1, vcc, 0, v1, vcc
	global_load_dwordx4 v[4:7], v[0:1], off
	v_add_u32_e32 v194, 0x4000, v194
	v_add_u32_e32 v195, 52, v192
	v_cmp_gt_u32_e32 vcc, 0x1000, v195
	v_mov_b32_e32 v0, s98
	v_mov_b32_e32 v1, s99
	v_mov_b32_e32 v3, s58
	v_cndmask_b32_e32 v0, v0, v3, vcc
	v_mov_b32_e32 v3, s59
	v_cndmask_b32_e32 v1, v1, v3, vcc
	v_add_co_u32_e32 v0, vcc, v0, v194
	s_nop 1
	v_addc_co_u32_e32 v1, vcc, 0, v1, vcc
	global_load_dwordx4 v[8:11], v[0:1], off
	v_add_u32_e32 v194, 0x4000, v194
	v_add_u32_e32 v195, 56, v192
	v_cmp_gt_u32_e32 vcc, 0x1000, v195
	v_mov_b32_e32 v0, s98
	v_mov_b32_e32 v1, s99
	v_mov_b32_e32 v3, s58
	v_cndmask_b32_e32 v0, v0, v3, vcc
	v_mov_b32_e32 v3, s59
	v_cndmask_b32_e32 v1, v1, v3, vcc
	v_add_co_u32_e32 v0, vcc, v0, v194
	s_nop 1
	v_addc_co_u32_e32 v1, vcc, 0, v1, vcc
	global_load_dwordx4 v[12:15], v[0:1], off
	v_add_u32_e32 v194, 0x4000, v194
	v_add_u32_e32 v195, 60, v192
	v_cmp_gt_u32_e32 vcc, 0x1000, v195
	v_mov_b32_e32 v0, s98
	v_mov_b32_e32 v1, s99
	v_mov_b32_e32 v3, s58
	v_cndmask_b32_e32 v0, v0, v3, vcc
	v_mov_b32_e32 v3, s59
	v_cndmask_b32_e32 v1, v1, v3, vcc
	v_add_co_u32_e32 v0, vcc, v0, v194
	s_nop 1
	v_addc_co_u32_e32 v1, vcc, 0, v1, vcc
	global_load_dwordx4 v[16:19], v[0:1], off
	v_add_u32_e32 v194, 0x4000, v194
	v_add_u32_e32 v195, 0, v192
	v_cmp_le_u32_e32 vcc, s7, v195
	s_waitcnt vmcnt(4)
	v_cndmask_b32_e32 v172, v148, v152, vcc
	v_cndmask_b32_e32 v173, v149, v153, vcc
	v_cndmask_b32_e32 v174, v150, v154, vcc
	v_cndmask_b32_e32 v175, v151, v155, vcc
	v_fmac_f32_e32 v100, v172, v156
	v_fmac_f32_e32 v101, v173, v157
	v_fmac_f32_e32 v102, v174, v158
	v_fmac_f32_e32 v103, v175, v159
	global_store_dwordx4 v197, v[100:103], s[56:57] sc0 sc1
	v_add_u32_e32 v197, 0x4000, v197
	v_add_u32_e32 v195, 4, v192
	v_cmp_le_u32_e32 vcc, s7, v195
	s_waitcnt vmcnt(5)
	s_waitcnt lgkmcnt(2)
	v_cndmask_b32_e32 v172, v148, v152, vcc
	v_cndmask_b32_e32 v173, v149, v153, vcc
	v_cndmask_b32_e32 v174, v150, v154, vcc
	v_cndmask_b32_e32 v175, v151, v155, vcc
	v_fmac_f32_e32 v104, v172, v160
	v_fmac_f32_e32 v105, v173, v161
	v_fmac_f32_e32 v106, v174, v162
	v_fmac_f32_e32 v107, v175, v163
	global_store_dwordx4 v197, v[104:107], s[56:57] sc0 sc1
	v_add_u32_e32 v197, 0x4000, v197
	v_add_u32_e32 v195, 8, v192
	v_cmp_le_u32_e32 vcc, s7, v195
	s_waitcnt vmcnt(6)
	s_waitcnt lgkmcnt(1)
	v_cndmask_b32_e32 v172, v148, v152, vcc
	v_cndmask_b32_e32 v173, v149, v153, vcc
	v_cndmask_b32_e32 v174, v150, v154, vcc
	v_cndmask_b32_e32 v175, v151, v155, vcc
	v_fmac_f32_e32 v108, v172, v164
	v_fmac_f32_e32 v109, v173, v165
	v_fmac_f32_e32 v110, v174, v166
	v_fmac_f32_e32 v111, v175, v167
	global_store_dwordx4 v197, v[108:111], s[56:57] sc0 sc1
	v_add_u32_e32 v197, 0x4000, v197
	v_add_u32_e32 v195, 12, v192
	v_cmp_le_u32_e32 vcc, s7, v195
	s_waitcnt vmcnt(7)
	s_waitcnt lgkmcnt(0)
	v_cndmask_b32_e32 v172, v148, v152, vcc
	v_cndmask_b32_e32 v173, v149, v153, vcc
	v_cndmask_b32_e32 v174, v150, v154, vcc
	v_cndmask_b32_e32 v175, v151, v155, vcc
	v_fmac_f32_e32 v112, v172, v168
	v_fmac_f32_e32 v113, v173, v169
	v_fmac_f32_e32 v114, v174, v170
	v_fmac_f32_e32 v115, v175, v171
	global_store_dwordx4 v197, v[112:115], s[56:57] sc0 sc1
	v_add_u32_e32 v197, 0x4000, v197
	ds_write_b32 v203, v20 offset:0
	ds_write_b32 v203, v21 offset:272
	ds_write_b32 v203, v22 offset:544
	ds_write_b32 v203, v23 offset:816
	ds_write_b32 v203, v24 offset:64
	ds_write_b32 v203, v25 offset:336
	ds_write_b32 v203, v26 offset:608
	ds_write_b32 v203, v27 offset:880
	ds_write_b32 v203, v28 offset:128
	ds_write_b32 v203, v29 offset:400
	ds_write_b32 v203, v30 offset:672
	ds_write_b32 v203, v31 offset:944
	ds_write_b32 v203, v32 offset:192
	ds_write_b32 v203, v33 offset:464
	ds_write_b32 v203, v34 offset:736
	ds_write_b32 v203, v35 offset:1008
	s_waitcnt lgkmcnt(0)
	ds_read_b128 v[156:159], v204 offset:0
	ds_read_b128 v[160:163], v204 offset:1088
	ds_read_b128 v[164:167], v204 offset:2176
	ds_read_b128 v[168:171], v204 offset:3264
	s_waitcnt lgkmcnt(0)
	v_add_u32_e32 v195, 64, v192
	v_cmp_gt_u32_e32 vcc, 0x1000, v195
	v_mov_b32_e32 v0, s98
	v_mov_b32_e32 v1, s99
	v_mov_b32_e32 v3, s58
	v_cndmask_b32_e32 v0, v0, v3, vcc
	v_mov_b32_e32 v3, s59
	v_cndmask_b32_e32 v1, v1, v3, vcc
	v_add_co_u32_e32 v0, vcc, v0, v194
	s_nop 1
	v_addc_co_u32_e32 v1, vcc, 0, v1, vcc
	global_load_dwordx4 v[20:23], v[0:1], off
	v_add_u32_e32 v194, 0x4000, v194
	v_add_u32_e32 v195, 68, v192
	v_cmp_gt_u32_e32 vcc, 0x1000, v195
	v_mov_b32_e32 v0, s98
	v_mov_b32_e32 v1, s99
	v_mov_b32_e32 v3, s58
	v_cndmask_b32_e32 v0, v0, v3, vcc
	v_mov_b32_e32 v3, s59
	v_cndmask_b32_e32 v1, v1, v3, vcc
	v_add_co_u32_e32 v0, vcc, v0, v194
	s_nop 1
	v_addc_co_u32_e32 v1, vcc, 0, v1, vcc
	global_load_dwordx4 v[24:27], v[0:1], off
	v_add_u32_e32 v194, 0x4000, v194
	v_add_u32_e32 v195, 72, v192
	v_cmp_gt_u32_e32 vcc, 0x1000, v195
	v_mov_b32_e32 v0, s98
	v_mov_b32_e32 v1, s99
	v_mov_b32_e32 v3, s58
	v_cndmask_b32_e32 v0, v0, v3, vcc
	v_mov_b32_e32 v3, s59
	v_cndmask_b32_e32 v1, v1, v3, vcc
	v_add_co_u32_e32 v0, vcc, v0, v194
	s_nop 1
	v_addc_co_u32_e32 v1, vcc, 0, v1, vcc
	global_load_dwordx4 v[28:31], v[0:1], off
	v_add_u32_e32 v194, 0x4000, v194
	v_add_u32_e32 v195, 76, v192
	v_cmp_gt_u32_e32 vcc, 0x1000, v195
	v_mov_b32_e32 v0, s98
	v_mov_b32_e32 v1, s99
	v_mov_b32_e32 v3, s58
	v_cndmask_b32_e32 v0, v0, v3, vcc
	v_mov_b32_e32 v3, s59
	v_cndmask_b32_e32 v1, v1, v3, vcc
	v_add_co_u32_e32 v0, vcc, v0, v194
	s_nop 1
	v_addc_co_u32_e32 v1, vcc, 0, v1, vcc
	global_load_dwordx4 v[32:35], v[0:1], off
	v_add_u32_e32 v194, 0x4000, v194
	v_add_u32_e32 v195, 16, v192
	v_cmp_le_u32_e32 vcc, s7, v195
	s_waitcnt vmcnt(12)
	v_cndmask_b32_e32 v172, v148, v152, vcc
	v_cndmask_b32_e32 v173, v149, v153, vcc
	v_cndmask_b32_e32 v174, v150, v154, vcc
	v_cndmask_b32_e32 v175, v151, v155, vcc
	v_fmac_f32_e32 v116, v172, v156
	v_fmac_f32_e32 v117, v173, v157
	v_fmac_f32_e32 v118, v174, v158
	v_fmac_f32_e32 v119, v175, v159
	global_store_dwordx4 v197, v[116:119], s[56:57] sc0 sc1
	v_add_u32_e32 v197, 0x4000, v197
	v_add_u32_e32 v195, 20, v192
	v_cmp_le_u32_e32 vcc, s7, v195
	s_waitcnt vmcnt(13)
	s_waitcnt lgkmcnt(2)
	v_cndmask_b32_e32 v172, v148, v152, vcc
	v_cndmask_b32_e32 v173, v149, v153, vcc
	v_cndmask_b32_e32 v174, v150, v154, vcc
	v_cndmask_b32_e32 v175, v151, v155, vcc
	v_fmac_f32_e32 v120, v172, v160
	v_fmac_f32_e32 v121, v173, v161
	v_fmac_f32_e32 v122, v174, v162
	v_fmac_f32_e32 v123, v175, v163
	global_store_dwordx4 v197, v[120:123], s[56:57] sc0 sc1
	v_add_u32_e32 v197, 0x4000, v197
	v_add_u32_e32 v195, 24, v192
	v_cmp_le_u32_e32 vcc, s7, v195
	s_waitcnt vmcnt(14)
	s_waitcnt lgkmcnt(1)
	v_cndmask_b32_e32 v172, v148, v152, vcc
	v_cndmask_b32_e32 v173, v149, v153, vcc
	v_cndmask_b32_e32 v174, v150, v154, vcc
	v_cndmask_b32_e32 v175, v151, v155, vcc
	v_fmac_f32_e32 v124, v172, v164
	v_fmac_f32_e32 v125, v173, v165
	v_fmac_f32_e32 v126, v174, v166
	v_fmac_f32_e32 v127, v175, v167
	global_store_dwordx4 v197, v[124:127], s[56:57] sc0 sc1
	v_add_u32_e32 v197, 0x4000, v197
	v_add_u32_e32 v195, 28, v192
	v_cmp_le_u32_e32 vcc, s7, v195
	s_waitcnt vmcnt(15)
	s_waitcnt lgkmcnt(0)
	v_cndmask_b32_e32 v172, v148, v152, vcc
	v_cndmask_b32_e32 v173, v149, v153, vcc
	v_cndmask_b32_e32 v174, v150, v154, vcc
	v_cndmask_b32_e32 v175, v151, v155, vcc
	v_fmac_f32_e32 v128, v172, v168
	v_fmac_f32_e32 v129, v173, v169
	v_fmac_f32_e32 v130, v174, v170
	v_fmac_f32_e32 v131, v175, v171
	global_store_dwordx4 v197, v[128:131], s[56:57] sc0 sc1
	v_add_u32_e32 v197, 0x4000, v197
	ds_write_b32 v203, v36 offset:0
	ds_write_b32 v203, v37 offset:272
	ds_write_b32 v203, v38 offset:544
	ds_write_b32 v203, v39 offset:816
	ds_write_b32 v203, v40 offset:64
	ds_write_b32 v203, v41 offset:336
	ds_write_b32 v203, v42 offset:608
	ds_write_b32 v203, v43 offset:880
	ds_write_b32 v203, v44 offset:128
	ds_write_b32 v203, v45 offset:400
	ds_write_b32 v203, v46 offset:672
	ds_write_b32 v203, v47 offset:944
	ds_write_b32 v203, v48 offset:192
	ds_write_b32 v203, v49 offset:464
	ds_write_b32 v203, v50 offset:736
	ds_write_b32 v203, v51 offset:1008
	s_waitcnt lgkmcnt(0)
	ds_read_b128 v[156:159], v204 offset:0
	ds_read_b128 v[160:163], v204 offset:1088
	ds_read_b128 v[164:167], v204 offset:2176
	ds_read_b128 v[168:171], v204 offset:3264
	s_waitcnt lgkmcnt(0)
	v_add_u32_e32 v195, 80, v192
	v_cmp_gt_u32_e32 vcc, 0x1000, v195
	v_mov_b32_e32 v0, s98
	v_mov_b32_e32 v1, s99
	v_mov_b32_e32 v3, s58
	v_cndmask_b32_e32 v0, v0, v3, vcc
	v_mov_b32_e32 v3, s59
	v_cndmask_b32_e32 v1, v1, v3, vcc
	v_add_co_u32_e32 v0, vcc, v0, v194
	s_nop 1
	v_addc_co_u32_e32 v1, vcc, 0, v1, vcc
	global_load_dwordx4 v[36:39], v[0:1], off
	v_add_u32_e32 v194, 0x4000, v194
	v_add_u32_e32 v195, 84, v192
	v_cmp_gt_u32_e32 vcc, 0x1000, v195
	v_mov_b32_e32 v0, s98
	v_mov_b32_e32 v1, s99
	v_mov_b32_e32 v3, s58
	v_cndmask_b32_e32 v0, v0, v3, vcc
	v_mov_b32_e32 v3, s59
	v_cndmask_b32_e32 v1, v1, v3, vcc
	v_add_co_u32_e32 v0, vcc, v0, v194
	s_nop 1
	v_addc_co_u32_e32 v1, vcc, 0, v1, vcc
	global_load_dwordx4 v[40:43], v[0:1], off
	v_add_u32_e32 v194, 0x4000, v194
	v_add_u32_e32 v195, 88, v192
	v_cmp_gt_u32_e32 vcc, 0x1000, v195
	v_mov_b32_e32 v0, s98
	v_mov_b32_e32 v1, s99
	v_mov_b32_e32 v3, s58
	v_cndmask_b32_e32 v0, v0, v3, vcc
	v_mov_b32_e32 v3, s59
	v_cndmask_b32_e32 v1, v1, v3, vcc
	v_add_co_u32_e32 v0, vcc, v0, v194
	s_nop 1
	v_addc_co_u32_e32 v1, vcc, 0, v1, vcc
	global_load_dwordx4 v[44:47], v[0:1], off
	v_add_u32_e32 v194, 0x4000, v194
	v_add_u32_e32 v195, 92, v192
	v_cmp_gt_u32_e32 vcc, 0x1000, v195
	v_mov_b32_e32 v0, s98
	v_mov_b32_e32 v1, s99
	v_mov_b32_e32 v3, s58
	v_cndmask_b32_e32 v0, v0, v3, vcc
	v_mov_b32_e32 v3, s59
	v_cndmask_b32_e32 v1, v1, v3, vcc
	v_add_co_u32_e32 v0, vcc, v0, v194
	s_nop 1
	v_addc_co_u32_e32 v1, vcc, 0, v1, vcc
	global_load_dwordx4 v[48:51], v[0:1], off
	v_add_u32_e32 v194, 0x4000, v194
	v_add_u32_e32 v195, 32, v192
	v_cmp_le_u32_e32 vcc, s7, v195
	s_waitcnt vmcnt(20)
	v_cndmask_b32_e32 v172, v148, v152, vcc
	v_cndmask_b32_e32 v173, v149, v153, vcc
	v_cndmask_b32_e32 v174, v150, v154, vcc
	v_cndmask_b32_e32 v175, v151, v155, vcc
	v_fmac_f32_e32 v132, v172, v156
	v_fmac_f32_e32 v133, v173, v157
	v_fmac_f32_e32 v134, v174, v158
	v_fmac_f32_e32 v135, v175, v159
	global_store_dwordx4 v197, v[132:135], s[56:57] sc0 sc1
	v_add_u32_e32 v197, 0x4000, v197
	v_add_u32_e32 v195, 36, v192
	v_cmp_le_u32_e32 vcc, s7, v195
	s_waitcnt vmcnt(21)
	s_waitcnt lgkmcnt(2)
	v_cndmask_b32_e32 v172, v148, v152, vcc
	v_cndmask_b32_e32 v173, v149, v153, vcc
	v_cndmask_b32_e32 v174, v150, v154, vcc
	v_cndmask_b32_e32 v175, v151, v155, vcc
	v_fmac_f32_e32 v136, v172, v160
	v_fmac_f32_e32 v137, v173, v161
	v_fmac_f32_e32 v138, v174, v162
	v_fmac_f32_e32 v139, v175, v163
	global_store_dwordx4 v197, v[136:139], s[56:57] sc0 sc1
	v_add_u32_e32 v197, 0x4000, v197
	v_add_u32_e32 v195, 40, v192
	v_cmp_le_u32_e32 vcc, s7, v195
	s_waitcnt vmcnt(22)
	s_waitcnt lgkmcnt(1)
	v_cndmask_b32_e32 v172, v148, v152, vcc
	v_cndmask_b32_e32 v173, v149, v153, vcc
	v_cndmask_b32_e32 v174, v150, v154, vcc
	v_cndmask_b32_e32 v175, v151, v155, vcc
	v_fmac_f32_e32 v140, v172, v164
	v_fmac_f32_e32 v141, v173, v165
	v_fmac_f32_e32 v142, v174, v166
	v_fmac_f32_e32 v143, v175, v167
	global_store_dwordx4 v197, v[140:143], s[56:57] sc0 sc1
	v_add_u32_e32 v197, 0x4000, v197
	v_add_u32_e32 v195, 44, v192
	v_cmp_le_u32_e32 vcc, s7, v195
	s_waitcnt vmcnt(23)
	s_waitcnt lgkmcnt(0)
	v_cndmask_b32_e32 v172, v148, v152, vcc
	v_cndmask_b32_e32 v173, v149, v153, vcc
	v_cndmask_b32_e32 v174, v150, v154, vcc
	v_cndmask_b32_e32 v175, v151, v155, vcc
	v_fmac_f32_e32 v144, v172, v168
	v_fmac_f32_e32 v145, v173, v169
	v_fmac_f32_e32 v146, v174, v170
	v_fmac_f32_e32 v147, v175, v171
	global_store_dwordx4 v197, v[144:147], s[56:57] sc0 sc1
	v_add_u32_e32 v197, 0x4000, v197
	ds_write_b32 v203, v52 offset:0
	ds_write_b32 v203, v53 offset:272
	ds_write_b32 v203, v54 offset:544
	ds_write_b32 v203, v55 offset:816
	ds_write_b32 v203, v56 offset:64
	ds_write_b32 v203, v57 offset:336
	ds_write_b32 v203, v58 offset:608
	ds_write_b32 v203, v59 offset:880
	ds_write_b32 v203, v60 offset:128
	ds_write_b32 v203, v61 offset:400
	ds_write_b32 v203, v62 offset:672
	ds_write_b32 v203, v63 offset:944
	ds_write_b32 v203, v64 offset:192
	ds_write_b32 v203, v65 offset:464
	ds_write_b32 v203, v66 offset:736
	ds_write_b32 v203, v67 offset:1008
	s_waitcnt lgkmcnt(0)
	ds_read_b128 v[156:159], v204 offset:0
	ds_read_b128 v[160:163], v204 offset:1088
	ds_read_b128 v[164:167], v204 offset:2176
	ds_read_b128 v[168:171], v204 offset:3264
	v_add_u32_e32 v195, 48, v192
	v_cmp_le_u32_e32 vcc, s7, v195
	s_waitcnt vmcnt(23)
	s_waitcnt lgkmcnt(3)
	v_cndmask_b32_e32 v172, v148, v152, vcc
	v_cndmask_b32_e32 v173, v149, v153, vcc
	v_cndmask_b32_e32 v174, v150, v154, vcc
	v_cndmask_b32_e32 v175, v151, v155, vcc
	v_fmac_f32_e32 v4, v172, v156
	v_fmac_f32_e32 v5, v173, v157
	v_fmac_f32_e32 v6, v174, v158
	v_fmac_f32_e32 v7, v175, v159
	global_store_dwordx4 v197, v[4:7], s[56:57] sc0 sc1
	v_add_u32_e32 v197, 0x4000, v197
	v_add_u32_e32 v195, 52, v192
	v_cmp_le_u32_e32 vcc, s7, v195
	s_waitcnt vmcnt(23)
	s_waitcnt lgkmcnt(2)
	v_cndmask_b32_e32 v172, v148, v152, vcc
	v_cndmask_b32_e32 v173, v149, v153, vcc
	v_cndmask_b32_e32 v174, v150, v154, vcc
	v_cndmask_b32_e32 v175, v151, v155, vcc
	v_fmac_f32_e32 v8, v172, v160
	v_fmac_f32_e32 v9, v173, v161
	v_fmac_f32_e32 v10, v174, v162
	v_fmac_f32_e32 v11, v175, v163
	global_store_dwordx4 v197, v[8:11], s[56:57] sc0 sc1
	v_add_u32_e32 v197, 0x4000, v197
	v_add_u32_e32 v195, 56, v192
	v_cmp_le_u32_e32 vcc, s7, v195
	s_waitcnt vmcnt(23)
	s_waitcnt lgkmcnt(1)
	v_cndmask_b32_e32 v172, v148, v152, vcc
	v_cndmask_b32_e32 v173, v149, v153, vcc
	v_cndmask_b32_e32 v174, v150, v154, vcc
	v_cndmask_b32_e32 v175, v151, v155, vcc
	v_fmac_f32_e32 v12, v172, v164
	v_fmac_f32_e32 v13, v173, v165
	v_fmac_f32_e32 v14, v174, v166
	v_fmac_f32_e32 v15, v175, v167
	global_store_dwordx4 v197, v[12:15], s[56:57] sc0 sc1
	v_add_u32_e32 v197, 0x4000, v197
	v_add_u32_e32 v195, 60, v192
	v_cmp_le_u32_e32 vcc, s7, v195
	s_waitcnt vmcnt(23)
	s_waitcnt lgkmcnt(0)
	v_cndmask_b32_e32 v172, v148, v152, vcc
	v_cndmask_b32_e32 v173, v149, v153, vcc
	v_cndmask_b32_e32 v174, v150, v154, vcc
	v_cndmask_b32_e32 v175, v151, v155, vcc
	v_fmac_f32_e32 v16, v172, v168
	v_fmac_f32_e32 v17, v173, v169
	v_fmac_f32_e32 v18, v174, v170
	v_fmac_f32_e32 v19, v175, v171
	global_store_dwordx4 v197, v[16:19], s[56:57] sc0 sc1
	v_add_u32_e32 v197, 0x4000, v197
	ds_write_b32 v203, v68 offset:0
	ds_write_b32 v203, v69 offset:272
	ds_write_b32 v203, v70 offset:544
	ds_write_b32 v203, v71 offset:816
	ds_write_b32 v203, v72 offset:64
	ds_write_b32 v203, v73 offset:336
	ds_write_b32 v203, v74 offset:608
	ds_write_b32 v203, v75 offset:880
	ds_write_b32 v203, v76 offset:128
	ds_write_b32 v203, v77 offset:400
	ds_write_b32 v203, v78 offset:672
	ds_write_b32 v203, v79 offset:944
	ds_write_b32 v203, v80 offset:192
	ds_write_b32 v203, v81 offset:464
	ds_write_b32 v203, v82 offset:736
	ds_write_b32 v203, v83 offset:1008
	s_waitcnt lgkmcnt(0)
	ds_read_b128 v[156:159], v204 offset:0
	ds_read_b128 v[160:163], v204 offset:1088
	ds_read_b128 v[164:167], v204 offset:2176
	ds_read_b128 v[168:171], v204 offset:3264
	v_add_u32_e32 v195, 64, v192
	v_cmp_le_u32_e32 vcc, s7, v195
	s_waitcnt vmcnt(19)
	s_waitcnt lgkmcnt(3)
	v_cndmask_b32_e32 v172, v148, v152, vcc
	v_cndmask_b32_e32 v173, v149, v153, vcc
	v_cndmask_b32_e32 v174, v150, v154, vcc
	v_cndmask_b32_e32 v175, v151, v155, vcc
	v_fmac_f32_e32 v20, v172, v156
	v_fmac_f32_e32 v21, v173, v157
	v_fmac_f32_e32 v22, v174, v158
	v_fmac_f32_e32 v23, v175, v159
	global_store_dwordx4 v197, v[20:23], s[56:57] sc0 sc1
	v_add_u32_e32 v197, 0x4000, v197
	v_add_u32_e32 v195, 68, v192
	v_cmp_le_u32_e32 vcc, s7, v195
	s_waitcnt vmcnt(19)
	s_waitcnt lgkmcnt(2)
	v_cndmask_b32_e32 v172, v148, v152, vcc
	v_cndmask_b32_e32 v173, v149, v153, vcc
	v_cndmask_b32_e32 v174, v150, v154, vcc
	v_cndmask_b32_e32 v175, v151, v155, vcc
	v_fmac_f32_e32 v24, v172, v160
	v_fmac_f32_e32 v25, v173, v161
	v_fmac_f32_e32 v26, v174, v162
	v_fmac_f32_e32 v27, v175, v163
	global_store_dwordx4 v197, v[24:27], s[56:57] sc0 sc1
	v_add_u32_e32 v197, 0x4000, v197
	v_add_u32_e32 v195, 72, v192
	v_cmp_le_u32_e32 vcc, s7, v195
	s_waitcnt vmcnt(19)
	s_waitcnt lgkmcnt(1)
	v_cndmask_b32_e32 v172, v148, v152, vcc
	v_cndmask_b32_e32 v173, v149, v153, vcc
	v_cndmask_b32_e32 v174, v150, v154, vcc
	v_cndmask_b32_e32 v175, v151, v155, vcc
	v_fmac_f32_e32 v28, v172, v164
	v_fmac_f32_e32 v29, v173, v165
	v_fmac_f32_e32 v30, v174, v166
	v_fmac_f32_e32 v31, v175, v167
	global_store_dwordx4 v197, v[28:31], s[56:57] sc0 sc1
	v_add_u32_e32 v197, 0x4000, v197
	v_add_u32_e32 v195, 76, v192
	v_cmp_le_u32_e32 vcc, s7, v195
	s_waitcnt vmcnt(19)
	s_waitcnt lgkmcnt(0)
	v_cndmask_b32_e32 v172, v148, v152, vcc
	v_cndmask_b32_e32 v173, v149, v153, vcc
	v_cndmask_b32_e32 v174, v150, v154, vcc
	v_cndmask_b32_e32 v175, v151, v155, vcc
	v_fmac_f32_e32 v32, v172, v168
	v_fmac_f32_e32 v33, v173, v169
	v_fmac_f32_e32 v34, v174, v170
	v_fmac_f32_e32 v35, v175, v171
	global_store_dwordx4 v197, v[32:35], s[56:57] sc0 sc1
	v_add_u32_e32 v197, 0x4000, v197
	ds_write_b32 v203, v84 offset:0
	ds_write_b32 v203, v85 offset:272
	ds_write_b32 v203, v86 offset:544
	ds_write_b32 v203, v87 offset:816
	ds_write_b32 v203, v88 offset:64
	ds_write_b32 v203, v89 offset:336
	ds_write_b32 v203, v90 offset:608
	ds_write_b32 v203, v91 offset:880
	ds_write_b32 v203, v92 offset:128
	ds_write_b32 v203, v93 offset:400
	ds_write_b32 v203, v94 offset:672
	ds_write_b32 v203, v95 offset:944
	ds_write_b32 v203, v96 offset:192
	ds_write_b32 v203, v97 offset:464
	ds_write_b32 v203, v98 offset:736
	ds_write_b32 v203, v99 offset:1008
	s_waitcnt lgkmcnt(0)
	ds_read_b128 v[156:159], v204 offset:0
	ds_read_b128 v[160:163], v204 offset:1088
	ds_read_b128 v[164:167], v204 offset:2176
	ds_read_b128 v[168:171], v204 offset:3264
	v_add_u32_e32 v195, 80, v192
	v_cmp_le_u32_e32 vcc, s7, v195
	s_waitcnt vmcnt(15)
	s_waitcnt lgkmcnt(3)
	v_cndmask_b32_e32 v172, v148, v152, vcc
	v_cndmask_b32_e32 v173, v149, v153, vcc
	v_cndmask_b32_e32 v174, v150, v154, vcc
	v_cndmask_b32_e32 v175, v151, v155, vcc
	v_fmac_f32_e32 v36, v172, v156
	v_fmac_f32_e32 v37, v173, v157
	v_fmac_f32_e32 v38, v174, v158
	v_fmac_f32_e32 v39, v175, v159
	global_store_dwordx4 v197, v[36:39], s[56:57] sc0 sc1
	v_add_u32_e32 v197, 0x4000, v197
	v_add_u32_e32 v195, 84, v192
	v_cmp_le_u32_e32 vcc, s7, v195
	s_waitcnt vmcnt(15)
	s_waitcnt lgkmcnt(2)
	v_cndmask_b32_e32 v172, v148, v152, vcc
	v_cndmask_b32_e32 v173, v149, v153, vcc
	v_cndmask_b32_e32 v174, v150, v154, vcc
	v_cndmask_b32_e32 v175, v151, v155, vcc
	v_fmac_f32_e32 v40, v172, v160
	v_fmac_f32_e32 v41, v173, v161
	v_fmac_f32_e32 v42, v174, v162
	v_fmac_f32_e32 v43, v175, v163
	global_store_dwordx4 v197, v[40:43], s[56:57] sc0 sc1
	v_add_u32_e32 v197, 0x4000, v197
	v_add_u32_e32 v195, 88, v192
	v_cmp_le_u32_e32 vcc, s7, v195
	s_waitcnt vmcnt(15)
	s_waitcnt lgkmcnt(1)
	v_cndmask_b32_e32 v172, v148, v152, vcc
	v_cndmask_b32_e32 v173, v149, v153, vcc
	v_cndmask_b32_e32 v174, v150, v154, vcc
	v_cndmask_b32_e32 v175, v151, v155, vcc
	v_fmac_f32_e32 v44, v172, v164
	v_fmac_f32_e32 v45, v173, v165
	v_fmac_f32_e32 v46, v174, v166
	v_fmac_f32_e32 v47, v175, v167
	global_store_dwordx4 v197, v[44:47], s[56:57] sc0 sc1
	v_add_u32_e32 v197, 0x4000, v197
	v_add_u32_e32 v195, 92, v192
	v_cmp_le_u32_e32 vcc, s7, v195
	s_waitcnt vmcnt(15)
	s_waitcnt lgkmcnt(0)
	v_cndmask_b32_e32 v172, v148, v152, vcc
	v_cndmask_b32_e32 v173, v149, v153, vcc
	v_cndmask_b32_e32 v174, v150, v154, vcc
	v_cndmask_b32_e32 v175, v151, v155, vcc
	v_fmac_f32_e32 v48, v172, v168
	v_fmac_f32_e32 v49, v173, v169
	v_fmac_f32_e32 v50, v174, v170
	v_fmac_f32_e32 v51, v175, v171
	global_store_dwordx4 v197, v[48:51], s[56:57] sc0 sc1
	v_add_u32_e32 v197, 0x4000, v197
	v_mov_b32_e32 v4, 0
	v_mov_b32_e32 v5, 0
	v_mov_b32_e32 v6, 0
	v_mov_b32_e32 v7, 0
	v_mov_b32_e32 v8, 0
	v_mov_b32_e32 v9, 0
	v_mov_b32_e32 v10, 0
	v_mov_b32_e32 v11, 0
	v_mov_b32_e32 v12, 0
	v_mov_b32_e32 v13, 0
	v_mov_b32_e32 v14, 0
	v_mov_b32_e32 v15, 0
	v_mov_b32_e32 v16, 0
	v_mov_b32_e32 v17, 0
	v_mov_b32_e32 v18, 0
	v_mov_b32_e32 v19, 0
	v_mov_b32_e32 v20, 0
	v_mov_b32_e32 v21, 0
	v_mov_b32_e32 v22, 0
	v_mov_b32_e32 v23, 0
	v_mov_b32_e32 v24, 0
	v_mov_b32_e32 v25, 0
	v_mov_b32_e32 v26, 0
	v_mov_b32_e32 v27, 0
	v_mov_b32_e32 v28, 0
	v_mov_b32_e32 v29, 0
	v_mov_b32_e32 v30, 0
	v_mov_b32_e32 v31, 0
	v_mov_b32_e32 v32, 0
	v_mov_b32_e32 v33, 0
	v_mov_b32_e32 v34, 0
	v_mov_b32_e32 v35, 0
	v_mov_b32_e32 v36, 0
	v_mov_b32_e32 v37, 0
	v_mov_b32_e32 v38, 0
	v_mov_b32_e32 v39, 0
	v_mov_b32_e32 v40, 0
	v_mov_b32_e32 v41, 0
	v_mov_b32_e32 v42, 0
	v_mov_b32_e32 v43, 0
	v_mov_b32_e32 v44, 0
	v_mov_b32_e32 v45, 0
	v_mov_b32_e32 v46, 0
	v_mov_b32_e32 v47, 0
	v_mov_b32_e32 v48, 0
	v_mov_b32_e32 v49, 0
	v_mov_b32_e32 v50, 0
	v_mov_b32_e32 v51, 0
	v_mov_b32_e32 v52, 0
	v_mov_b32_e32 v53, 0
	v_mov_b32_e32 v54, 0
	v_mov_b32_e32 v55, 0
	v_mov_b32_e32 v56, 0
	v_mov_b32_e32 v57, 0
	v_mov_b32_e32 v58, 0
	v_mov_b32_e32 v59, 0
	v_mov_b32_e32 v60, 0
	v_mov_b32_e32 v61, 0
	v_mov_b32_e32 v62, 0
	v_mov_b32_e32 v63, 0
	v_mov_b32_e32 v64, 0
	v_mov_b32_e32 v65, 0
	v_mov_b32_e32 v66, 0
	v_mov_b32_e32 v67, 0
	v_mov_b32_e32 v68, 0
	v_mov_b32_e32 v69, 0
	v_mov_b32_e32 v70, 0
	v_mov_b32_e32 v71, 0
	v_mov_b32_e32 v72, 0
	v_mov_b32_e32 v73, 0
	v_mov_b32_e32 v74, 0
	v_mov_b32_e32 v75, 0
	v_mov_b32_e32 v76, 0
	v_mov_b32_e32 v77, 0
	v_mov_b32_e32 v78, 0
	v_mov_b32_e32 v79, 0
	v_mov_b32_e32 v80, 0
	v_mov_b32_e32 v81, 0
	v_mov_b32_e32 v82, 0
	v_mov_b32_e32 v83, 0
	v_mov_b32_e32 v84, 0
	v_mov_b32_e32 v85, 0
	v_mov_b32_e32 v86, 0
	v_mov_b32_e32 v87, 0
	v_mov_b32_e32 v88, 0
	v_mov_b32_e32 v89, 0
	v_mov_b32_e32 v90, 0
	v_mov_b32_e32 v91, 0
	v_mov_b32_e32 v92, 0
	v_mov_b32_e32 v93, 0
	v_mov_b32_e32 v94, 0
	v_mov_b32_e32 v95, 0
	v_mov_b32_e32 v96, 0
	v_mov_b32_e32 v97, 0
	v_mov_b32_e32 v98, 0
	v_mov_b32_e32 v99, 0
	s_mov_b32 s34, 0
	s_add_u32 s35, s35, s52
	s_cmp_ge_u32 s31, s30
	s_cbranch_scc1 .Lgm_wo_exit

.Lgm_wi_cnt:
	s_add_u32 s30, s30, 16
	s_add_u32 s4, s4, s52
	s_cmp_lt_u32 s4, s54
	s_cbranch_scc1 .Lgm_wi_cnt
	s_add_u32 s48, s96, 0x2e24000
	s_addc_u32 s49, s97, 0
	s_mul_i32 s4, s36, 0x4c0000
	s_add_u32 s50, s96, 0x0
	s_addc_u32 s51, s97, 0
	s_add_u32 s50, s50, s4
	s_addc_u32 s51, s51, 0
	v_and_b32_e32 v0, 63, v206
	v_lshrrev_b32_e32 v1, 6, v206
	s_mov_b32 s31, 0
	v_readfirstlane_b32 s42, v1
	s_nop 0
	s_cmp_ge_u32 s42, 4
	s_cbranch_scc1 .Lgm_wi_compute
	v_lshrrev_b32_e32 v3, 3, v0
	v_and_b32_e32 v4, 7, v0
	v_xor_b32_e32 v4, v4, v3
	v_lshl_add_u32 v3, v1, 3, v3
	v_lshlrev_b32_e32 v3, 11, v3
	v_lshl_add_u32 v180, v4, 4, v3
	v_add_u32_e32 v181, 0x10000, v180
	v_add_u32_e32 v182, 0x20000, v180
	v_add_u32_e32 v183, 0x30000, v180
	v_add_u32_e32 v184, 0x40000, v180
	v_add_u32_e32 v185, 0x50000, v180
	s_lshl_b32 s42, s42, 10
	s_mov_b32 s38, s53
	s_mov_b32 s39, 0
	s_mov_b32 s41, s42
	s_and_b32 s4, s38, 31
	s_lshr_b32 s5, s38, 5
	s_mul_i32 s4, s4, 0x60000
	s_add_u32 s44, s48, s4
	s_addc_u32 s45, s49, 0
	s_mul_i32 s4, s5, 0x40000
	s_add_u32 s46, s50, s4
	s_addc_u32 s47, s51, 0
	s_add_u32 m0, s41, 0x0
	s_nop 0
	global_load_lds_dwordx4 v180, s[44:45]
	s_add_u32 m0, s41, 0x1000
	s_nop 0
	global_load_lds_dwordx4 v181, s[44:45]
	s_add_u32 m0, s41, 0x2000
	s_nop 0
	global_load_lds_dwordx4 v182, s[44:45]
	s_add_u32 m0, s41, 0x3000
	s_nop 0
	global_load_lds_dwordx4 v183, s[44:45]
	s_add_u32 m0, s41, 0x4000
	s_nop 0
	global_load_lds_dwordx4 v184, s[44:45]
	s_add_u32 m0, s41, 0x5000
	s_nop 0
	global_load_lds_dwordx4 v185, s[44:45]
	s_add_u32 m0, s41, 0x6000
	s_nop 0
	global_load_lds_dwordx4 v180, s[46:47]
	s_add_u32 m0, s41, 0x7000
	s_nop 0
	global_load_lds_dwordx4 v181, s[46:47]
	s_add_u32 m0, s41, 0x8000
	s_nop 0
	global_load_lds_dwordx4 v182, s[46:47]
	s_add_u32 m0, s41, 0x9000
	s_nop 0
	global_load_lds_dwordx4 v183, s[46:47]
	s_add_u32 s39, s39, 1
	s_add_u32 s44, s44, 0x80
	s_addc_u32 s45, s45, 0
	s_add_u32 s46, s46, 0x80
	s_addc_u32 s47, s47, 0
	s_cmp_lt_u32 s39, 16
	s_cbranch_scc1 .Lgm_wi_dadv1
	s_mov_b32 s39, 0
	s_add_u32 s4, s38, s52
	s_cmp_lt_u32 s4, s54
	s_cselect_b32 s38, s4, s38
	s_and_b32 s4, s38, 31
	s_lshr_b32 s5, s38, 5
	s_mul_i32 s4, s4, 0x60000
	s_add_u32 s44, s48, s4
	s_addc_u32 s45, s49, 0
	s_mul_i32 s4, s5, 0x40000
	s_add_u32 s46, s50, s4
	s_addc_u32 s47, s51, 0

.Lgm_wi_join:
	s_waitcnt lgkmcnt(13)
	v_mfma_f32_16x16x32_bf16 v[4:7], v[100:103], v[124:127], v[4:7]
	v_mfma_f32_16x16x32_bf16 v[20:23], v[104:107], v[124:127], v[20:23]
	v_mfma_f32_16x16x32_bf16 v[36:39], v[108:111], v[124:127], v[36:39]
	v_mfma_f32_16x16x32_bf16 v[52:55], v[112:115], v[124:127], v[52:55]
	v_mfma_f32_16x16x32_bf16 v[68:71], v[116:119], v[124:127], v[68:71]
	v_mfma_f32_16x16x32_bf16 v[84:87], v[120:123], v[124:127], v[84:87]
	s_waitcnt lgkmcnt(12)
	v_mfma_f32_16x16x32_bf16 v[8:11], v[100:103], v[128:131], v[8:11]
	v_mfma_f32_16x16x32_bf16 v[24:27], v[104:107], v[128:131], v[24:27]
	v_mfma_f32_16x16x32_bf16 v[40:43], v[108:111], v[128:131], v[40:43]
	v_mfma_f32_16x16x32_bf16 v[56:59], v[112:115], v[128:131], v[56:59]
	v_mfma_f32_16x16x32_bf16 v[72:75], v[116:119], v[128:131], v[72:75]
	v_mfma_f32_16x16x32_bf16 v[88:91], v[120:123], v[128:131], v[88:91]
	s_waitcnt lgkmcnt(11)
	v_mfma_f32_16x16x32_bf16 v[12:15], v[100:103], v[132:135], v[12:15]
	v_mfma_f32_16x16x32_bf16 v[28:31], v[104:107], v[132:135], v[28:31]
	v_mfma_f32_16x16x32_bf16 v[44:47], v[108:111], v[132:135], v[44:47]
	v_mfma_f32_16x16x32_bf16 v[60:63], v[112:115], v[132:135], v[60:63]
	v_mfma_f32_16x16x32_bf16 v[76:79], v[116:119], v[132:135], v[76:79]
	v_mfma_f32_16x16x32_bf16 v[92:95], v[120:123], v[132:135], v[92:95]
	s_waitcnt lgkmcnt(10)
	v_mfma_f32_16x16x32_bf16 v[16:19], v[100:103], v[136:139], v[16:19]
	v_mfma_f32_16x16x32_bf16 v[32:35], v[104:107], v[136:139], v[32:35]
	v_mfma_f32_16x16x32_bf16 v[48:51], v[108:111], v[136:139], v[48:51]
	v_mfma_f32_16x16x32_bf16 v[64:67], v[112:115], v[136:139], v[64:67]
	v_mfma_f32_16x16x32_bf16 v[80:83], v[116:119], v[136:139], v[80:83]
	v_mfma_f32_16x16x32_bf16 v[96:99], v[120:123], v[136:139], v[96:99]
	s_waitcnt lgkmcnt(0)
	s_add_u32 s34, s34, 1
	s_add_u32 s31, s31, 1
	s_cmp_lt_u32 s34, 16
	s_cbranch_scc1 .Lgm_wi_rot
	v_mfma_f32_16x16x32_bf16 v[4:7], v[140:143], v[164:167], v[4:7]
	v_mfma_f32_16x16x32_bf16 v[20:23], v[144:147], v[164:167], v[20:23]
	v_mfma_f32_16x16x32_bf16 v[36:39], v[148:151], v[164:167], v[36:39]
	v_mfma_f32_16x16x32_bf16 v[52:55], v[152:155], v[164:167], v[52:55]
	v_mfma_f32_16x16x32_bf16 v[68:71], v[156:159], v[164:167], v[68:71]
	v_mfma_f32_16x16x32_bf16 v[84:87], v[160:163], v[164:167], v[84:87]
	v_mfma_f32_16x16x32_bf16 v[8:11], v[140:143], v[168:171], v[8:11]
	v_mfma_f32_16x16x32_bf16 v[24:27], v[144:147], v[168:171], v[24:27]
	v_mfma_f32_16x16x32_bf16 v[40:43], v[148:151], v[168:171], v[40:43]
	v_mfma_f32_16x16x32_bf16 v[56:59], v[152:155], v[168:171], v[56:59]
	v_mfma_f32_16x16x32_bf16 v[72:75], v[156:159], v[168:171], v[72:75]
	v_mfma_f32_16x16x32_bf16 v[88:91], v[160:163], v[168:171], v[88:91]
	v_mfma_f32_16x16x32_bf16 v[12:15], v[140:143], v[172:175], v[12:15]
	v_mfma_f32_16x16x32_bf16 v[28:31], v[144:147], v[172:175], v[28:31]
	v_mfma_f32_16x16x32_bf16 v[44:47], v[148:151], v[172:175], v[44:47]
	v_mfma_f32_16x16x32_bf16 v[60:63], v[152:155], v[172:175], v[60:63]
	v_mfma_f32_16x16x32_bf16 v[76:79], v[156:159], v[172:175], v[76:79]
	v_mfma_f32_16x16x32_bf16 v[92:95], v[160:163], v[172:175], v[92:95]
	v_mfma_f32_16x16x32_bf16 v[16:19], v[140:143], v[176:179], v[16:19]
	v_mfma_f32_16x16x32_bf16 v[32:35], v[144:147], v[176:179], v[32:35]
	v_mfma_f32_16x16x32_bf16 v[48:51], v[148:151], v[176:179], v[48:51]
	v_mfma_f32_16x16x32_bf16 v[64:67], v[152:155], v[176:179], v[64:67]
	v_mfma_f32_16x16x32_bf16 v[80:83], v[156:159], v[176:179], v[80:83]
	v_mfma_f32_16x16x32_bf16 v[96:99], v[160:163], v[176:179], v[96:99]
	s_and_b32 s6, s35, 31
	s_lshr_b32 s7, s35, 5
	s_mul_i32 s6, s6, 192
	s_lshl_b32 s7, s7, 7
	s_nop 7
	s_mul_i32 s4, s6, 0x2440
	s_lshl_b32 s5, s7, 2
	s_add_u32 s4, s4, s5
	v_add_u32_e32 v197, s4, v205
	v_add_u32_e32 v192, s7, v193
	s_mov_b32 s4, 0x910
	v_cmp_gt_u32_e32 vcc, s4, v192
	s_mov_b64 s[4:5], exec
	ds_write_b32 v203, v4 offset:0
	ds_write_b32 v203, v5 offset:272
	ds_write_b32 v203, v6 offset:544
	ds_write_b32 v203, v7 offset:816
	ds_write_b32 v203, v8 offset:64
	ds_write_b32 v203, v9 offset:336
	ds_write_b32 v203, v10 offset:608
	ds_write_b32 v203, v11 offset:880
	ds_write_b32 v203, v12 offset:128
	ds_write_b32 v203, v13 offset:400
	ds_write_b32 v203, v14 offset:672
	ds_write_b32 v203, v15 offset:944
	ds_write_b32 v203, v16 offset:192
	ds_write_b32 v203, v17 offset:464
	ds_write_b32 v203, v18 offset:736
	ds_write_b32 v203, v19 offset:1008
	s_waitcnt lgkmcnt(0)
	ds_read_b128 v[156:159], v204 offset:0
	ds_read_b128 v[160:163], v204 offset:1088
	ds_read_b128 v[164:167], v204 offset:2176
	ds_read_b128 v[168:171], v204 offset:3264
	s_waitcnt lgkmcnt(0)
	s_and_b64 exec, s[4:5], vcc
	global_store_dwordx4 v197, v[156:159], s[56:57] sc0 sc1
	v_add_u32_e32 v197, 0x9100, v197
	global_store_dwordx4 v197, v[160:163], s[56:57] sc0 sc1
	v_add_u32_e32 v197, 0x9100, v197
	global_store_dwordx4 v197, v[164:167], s[56:57] sc0 sc1
	v_add_u32_e32 v197, 0x9100, v197
	global_store_dwordx4 v197, v[168:171], s[56:57] sc0 sc1
	v_add_u32_e32 v197, 0x9100, v197
	s_mov_b64 exec, s[4:5]
	s_nop 1
	ds_write_b32 v203, v20 offset:0
	ds_write_b32 v203, v21 offset:272
	ds_write_b32 v203, v22 offset:544
	ds_write_b32 v203, v23 offset:816
	ds_write_b32 v203, v24 offset:64
	ds_write_b32 v203, v25 offset:336
	ds_write_b32 v203, v26 offset:608
	ds_write_b32 v203, v27 offset:880
	ds_write_b32 v203, v28 offset:128
	ds_write_b32 v203, v29 offset:400
	ds_write_b32 v203, v30 offset:672
	ds_write_b32 v203, v31 offset:944
	ds_write_b32 v203, v32 offset:192
	ds_write_b32 v203, v33 offset:464
	ds_write_b32 v203, v34 offset:736
	ds_write_b32 v203, v35 offset:1008
	s_waitcnt lgkmcnt(0)
	ds_read_b128 v[156:159], v204 offset:0
	ds_read_b128 v[160:163], v204 offset:1088
	ds_read_b128 v[164:167], v204 offset:2176
	ds_read_b128 v[168:171], v204 offset:3264
	s_waitcnt lgkmcnt(0)
	s_and_b64 exec, s[4:5], vcc
	global_store_dwordx4 v197, v[156:159], s[56:57] sc0 sc1
	v_add_u32_e32 v197, 0x9100, v197
	global_store_dwordx4 v197, v[160:163], s[56:57] sc0 sc1
	v_add_u32_e32 v197, 0x9100, v197
	global_store_dwordx4 v197, v[164:167], s[56:57] sc0 sc1
	v_add_u32_e32 v197, 0x9100, v197
	global_store_dwordx4 v197, v[168:171], s[56:57] sc0 sc1
	v_add_u32_e32 v197, 0x9100, v197
	s_mov_b64 exec, s[4:5]
	s_nop 1
	ds_write_b32 v203, v36 offset:0
	ds_write_b32 v203, v37 offset:272
	ds_write_b32 v203, v38 offset:544
	ds_write_b32 v203, v39 offset:816
	ds_write_b32 v203, v40 offset:64
	ds_write_b32 v203, v41 offset:336
	ds_write_b32 v203, v42 offset:608
	ds_write_b32 v203, v43 offset:880
	ds_write_b32 v203, v44 offset:128
	ds_write_b32 v203, v45 offset:400
	ds_write_b32 v203, v46 offset:672
	ds_write_b32 v203, v47 offset:944
	ds_write_b32 v203, v48 offset:192
	ds_write_b32 v203, v49 offset:464
	ds_write_b32 v203, v50 offset:736
	ds_write_b32 v203, v51 offset:1008
	s_waitcnt lgkmcnt(0)
	ds_read_b128 v[156:159], v204 offset:0
	ds_read_b128 v[160:163], v204 offset:1088
	ds_read_b128 v[164:167], v204 offset:2176
	ds_read_b128 v[168:171], v204 offset:3264
	s_waitcnt lgkmcnt(0)
	s_and_b64 exec, s[4:5], vcc
	global_store_dwordx4 v197, v[156:159], s[56:57] sc0 sc1
	v_add_u32_e32 v197, 0x9100, v197
	global_store_dwordx4 v197, v[160:163], s[56:57] sc0 sc1
	v_add_u32_e32 v197, 0x9100, v197
	global_store_dwordx4 v197, v[164:167], s[56:57] sc0 sc1
	v_add_u32_e32 v197, 0x9100, v197
	global_store_dwordx4 v197, v[168:171], s[56:57] sc0 sc1
	v_add_u32_e32 v197, 0x9100, v197
	s_mov_b64 exec, s[4:5]
	s_nop 1
	ds_write_b32 v203, v52 offset:0
	ds_write_b32 v203, v53 offset:272
	ds_write_b32 v203, v54 offset:544
	ds_write_b32 v203, v55 offset:816
	ds_write_b32 v203, v56 offset:64
	ds_write_b32 v203, v57 offset:336
	ds_write_b32 v203, v58 offset:608
	ds_write_b32 v203, v59 offset:880
	ds_write_b32 v203, v60 offset:128
	ds_write_b32 v203, v61 offset:400
	ds_write_b32 v203, v62 offset:672
	ds_write_b32 v203, v63 offset:944
	ds_write_b32 v203, v64 offset:192
	ds_write_b32 v203, v65 offset:464
	ds_write_b32 v203, v66 offset:736
	ds_write_b32 v203, v67 offset:1008
	s_waitcnt lgkmcnt(0)
	ds_read_b128 v[156:159], v204 offset:0
	ds_read_b128 v[160:163], v204 offset:1088
	ds_read_b128 v[164:167], v204 offset:2176
	ds_read_b128 v[168:171], v204 offset:3264
	s_waitcnt lgkmcnt(0)
	s_and_b64 exec, s[4:5], vcc
	global_store_dwordx4 v197, v[156:159], s[56:57] sc0 sc1
	v_add_u32_e32 v197, 0x9100, v197
	global_store_dwordx4 v197, v[160:163], s[56:57] sc0 sc1
	v_add_u32_e32 v197, 0x9100, v197
	global_store_dwordx4 v197, v[164:167], s[56:57] sc0 sc1
	v_add_u32_e32 v197, 0x9100, v197
	global_store_dwordx4 v197, v[168:171], s[56:57] sc0 sc1
	v_add_u32_e32 v197, 0x9100, v197
	s_mov_b64 exec, s[4:5]
	s_nop 1
	ds_write_b32 v203, v68 offset:0
	ds_write_b32 v203, v69 offset:272
	ds_write_b32 v203, v70 offset:544
	ds_write_b32 v203, v71 offset:816
	ds_write_b32 v203, v72 offset:64
	ds_write_b32 v203, v73 offset:336
	ds_write_b32 v203, v74 offset:608
	ds_write_b32 v203, v75 offset:880
	ds_write_b32 v203, v76 offset:128
	ds_write_b32 v203, v77 offset:400
	ds_write_b32 v203, v78 offset:672
	ds_write_b32 v203, v79 offset:944
	ds_write_b32 v203, v80 offset:192
	ds_write_b32 v203, v81 offset:464
	ds_write_b32 v203, v82 offset:736
	ds_write_b32 v203, v83 offset:1008
	s_waitcnt lgkmcnt(0)
	ds_read_b128 v[156:159], v204 offset:0
	ds_read_b128 v[160:163], v204 offset:1088
	ds_read_b128 v[164:167], v204 offset:2176
	ds_read_b128 v[168:171], v204 offset:3264
	s_waitcnt lgkmcnt(0)
	s_and_b64 exec, s[4:5], vcc
	global_store_dwordx4 v197, v[156:159], s[56:57] sc0 sc1
	v_add_u32_e32 v197, 0x9100, v197
	global_store_dwordx4 v197, v[160:163], s[56:57] sc0 sc1
	v_add_u32_e32 v197, 0x9100, v197
	global_store_dwordx4 v197, v[164:167], s[56:57] sc0 sc1
	v_add_u32_e32 v197, 0x9100, v197
	global_store_dwordx4 v197, v[168:171], s[56:57] sc0 sc1
	v_add_u32_e32 v197, 0x9100, v197
	s_mov_b64 exec, s[4:5]
	s_nop 1
	ds_write_b32 v203, v84 offset:0
	ds_write_b32 v203, v85 offset:272
	ds_write_b32 v203, v86 offset:544
	ds_write_b32 v203, v87 offset:816
	ds_write_b32 v203, v88 offset:64
	ds_write_b32 v203, v89 offset:336
	ds_write_b32 v203, v90 offset:608
	ds_write_b32 v203, v91 offset:880
	ds_write_b32 v203, v92 offset:128
	ds_write_b32 v203, v93 offset:400
	ds_write_b32 v203, v94 offset:672
	ds_write_b32 v203, v95 offset:944
	ds_write_b32 v203, v96 offset:192
	ds_write_b32 v203, v97 offset:464
	ds_write_b32 v203, v98 offset:736
	ds_write_b32 v203, v99 offset:1008
	s_waitcnt lgkmcnt(0)
	ds_read_b128 v[156:159], v204 offset:0
	ds_read_b128 v[160:163], v204 offset:1088
	ds_read_b128 v[164:167], v204 offset:2176
	ds_read_b128 v[168:171], v204 offset:3264
	s_waitcnt lgkmcnt(0)
	s_and_b64 exec, s[4:5], vcc
	global_store_dwordx4 v197, v[156:159], s[56:57] sc0 sc1
	v_add_u32_e32 v197, 0x9100, v197
	global_store_dwordx4 v197, v[160:163], s[56:57] sc0 sc1
	v_add_u32_e32 v197, 0x9100, v197
	global_store_dwordx4 v197, v[164:167], s[56:57] sc0 sc1
	v_add_u32_e32 v197, 0x9100, v197
	global_store_dwordx4 v197, v[168:171], s[56:57] sc0 sc1
	v_add_u32_e32 v197, 0x9100, v197
	s_mov_b64 exec, s[4:5]
	s_nop 1
	v_mov_b32_e32 v4, 0
	v_mov_b32_e32 v5, 0
	v_mov_b32_e32 v6, 0
	v_mov_b32_e32 v7, 0
	v_mov_b32_e32 v8, 0
	v_mov_b32_e32 v9, 0
	v_mov_b32_e32 v10, 0
	v_mov_b32_e32 v11, 0
	v_mov_b32_e32 v12, 0
	v_mov_b32_e32 v13, 0
	v_mov_b32_e32 v14, 0
	v_mov_b32_e32 v15, 0
	v_mov_b32_e32 v16, 0
	v_mov_b32_e32 v17, 0
	v_mov_b32_e32 v18, 0
	v_mov_b32_e32 v19, 0
	v_mov_b32_e32 v20, 0
	v_mov_b32_e32 v21, 0
	v_mov_b32_e32 v22, 0
	v_mov_b32_e32 v23, 0
	v_mov_b32_e32 v24, 0
	v_mov_b32_e32 v25, 0
	v_mov_b32_e32 v26, 0
	v_mov_b32_e32 v27, 0
	v_mov_b32_e32 v28, 0
	v_mov_b32_e32 v29, 0
	v_mov_b32_e32 v30, 0
	v_mov_b32_e32 v31, 0
	v_mov_b32_e32 v32, 0
	v_mov_b32_e32 v33, 0
	v_mov_b32_e32 v34, 0
	v_mov_b32_e32 v35, 0
	v_mov_b32_e32 v36, 0
	v_mov_b32_e32 v37, 0
	v_mov_b32_e32 v38, 0
	v_mov_b32_e32 v39, 0
	v_mov_b32_e32 v40, 0
	v_mov_b32_e32 v41, 0
	v_mov_b32_e32 v42, 0
	v_mov_b32_e32 v43, 0
	v_mov_b32_e32 v44, 0
	v_mov_b32_e32 v45, 0
	v_mov_b32_e32 v46, 0
	v_mov_b32_e32 v47, 0
	v_mov_b32_e32 v48, 0
	v_mov_b32_e32 v49, 0
	v_mov_b32_e32 v50, 0
	v_mov_b32_e32 v51, 0
	v_mov_b32_e32 v52, 0
	v_mov_b32_e32 v53, 0
	v_mov_b32_e32 v54, 0
	v_mov_b32_e32 v55, 0
	v_mov_b32_e32 v56, 0
	v_mov_b32_e32 v57, 0
	v_mov_b32_e32 v58, 0
	v_mov_b32_e32 v59, 0
	v_mov_b32_e32 v60, 0
	v_mov_b32_e32 v61, 0
	v_mov_b32_e32 v62, 0
	v_mov_b32_e32 v63, 0
	v_mov_b32_e32 v64, 0
	v_mov_b32_e32 v65, 0
	v_mov_b32_e32 v66, 0
	v_mov_b32_e32 v67, 0
	v_mov_b32_e32 v68, 0
	v_mov_b32_e32 v69, 0
	v_mov_b32_e32 v70, 0
	v_mov_b32_e32 v71, 0
	v_mov_b32_e32 v72, 0
	v_mov_b32_e32 v73, 0
	v_mov_b32_e32 v74, 0
	v_mov_b32_e32 v75, 0
	v_mov_b32_e32 v76, 0
	v_mov_b32_e32 v77, 0
	v_mov_b32_e32 v78, 0
	v_mov_b32_e32 v79, 0
	v_mov_b32_e32 v80, 0
	v_mov_b32_e32 v81, 0
	v_mov_b32_e32 v82, 0
	v_mov_b32_e32 v83, 0
	v_mov_b32_e32 v84, 0
	v_mov_b32_e32 v85, 0
	v_mov_b32_e32 v86, 0
	v_mov_b32_e32 v87, 0
	v_mov_b32_e32 v88, 0
	v_mov_b32_e32 v89, 0
	v_mov_b32_e32 v90, 0
	v_mov_b32_e32 v91, 0
	v_mov_b32_e32 v92, 0
	v_mov_b32_e32 v93, 0
	v_mov_b32_e32 v94, 0
	v_mov_b32_e32 v95, 0
	v_mov_b32_e32 v96, 0
	v_mov_b32_e32 v97, 0
	v_mov_b32_e32 v98, 0
	v_mov_b32_e32 v99, 0
	s_mov_b32 s34, 0
	s_add_u32 s35, s35, s52
	s_cmp_ge_u32 s31, s30
	s_cbranch_scc1 .Lgm_wi_exit

.Lgm_glu_cnt:
	s_add_u32 s30, s30, 4
	s_add_u32 s4, s4, s52
	s_cmp_lt_u32 s4, s54
	s_cbranch_scc1 .Lgm_glu_cnt
	s_add_u32 s48, s96, 0xcea4000
	s_addc_u32 s49, s97, 0
	s_mul_i32 s4, s36, 0x20000
	s_add_u32 s50, s96, 0x2d80000
	s_addc_u32 s51, s97, 0
	s_add_u32 s50, s50, s4
	s_addc_u32 s51, s51, 0
	v_and_b32_e32 v0, 63, v206
	v_lshrrev_b32_e32 v1, 6, v206
	s_mov_b32 s31, 0
	v_readfirstlane_b32 s42, v1
	s_nop 0
	s_cmp_ge_u32 s42, 4
	s_cbranch_scc1 .Lgm_glu_compute
	v_lshrrev_b32_e32 v3, 3, v0
	v_and_b32_e32 v4, 7, v0
	v_xor_b32_e32 v4, v4, v3
	v_lshl_add_u32 v3, v1, 3, v3
	v_lshlrev_b32_e32 v3, 9, v3
	v_lshl_add_u32 v180, v4, 4, v3
	v_add_u32_e32 v181, 0x4000, v180
	v_add_u32_e32 v182, 0x8000, v180
	v_add_u32_e32 v183, 0xc000, v180
	v_add_u32_e32 v184, 0x10000, v180
	v_add_u32_e32 v185, 0x14000, v180
	s_lshl_b32 s42, s42, 10
	s_mov_b32 s38, s53
	s_mov_b32 s39, 0
	s_mov_b32 s41, s42
	s_and_b32 s4, s38, 31
	s_lshr_b32 s5, s38, 5
	s_mul_i32 s4, s4, 0x18000
	s_add_u32 s44, s48, s4
	s_addc_u32 s45, s49, 0
	s_mul_i32 s4, s5, 0x10000
	s_add_u32 s46, s50, s4
	s_addc_u32 s47, s51, 0
	s_add_u32 m0, s41, 0x0
	s_nop 0
	global_load_lds_dwordx4 v180, s[44:45]
	s_add_u32 m0, s41, 0x1000
	s_nop 0
	global_load_lds_dwordx4 v181, s[44:45]
	s_add_u32 m0, s41, 0x2000
	s_nop 0
	global_load_lds_dwordx4 v182, s[44:45]
	s_add_u32 m0, s41, 0x3000
	s_nop 0
	global_load_lds_dwordx4 v183, s[44:45]
	s_add_u32 m0, s41, 0x4000
	s_nop 0
	global_load_lds_dwordx4 v184, s[44:45]
	s_add_u32 m0, s41, 0x5000
	s_nop 0
	global_load_lds_dwordx4 v185, s[44:45]
	s_add_u32 m0, s41, 0x6000
	s_nop 0
	global_load_lds_dwordx4 v180, s[46:47]
	s_add_u32 m0, s41, 0x7000
	s_nop 0
	global_load_lds_dwordx4 v181, s[46:47]
	s_add_u32 m0, s41, 0x8000
	s_nop 0
	global_load_lds_dwordx4 v182, s[46:47]
	s_add_u32 m0, s41, 0x9000
	s_nop 0
	global_load_lds_dwordx4 v183, s[46:47]
	s_add_u32 s39, s39, 1
	s_add_u32 s44, s44, 0x80
	s_addc_u32 s45, s45, 0
	s_add_u32 s46, s46, 0x80
	s_addc_u32 s47, s47, 0
	s_cmp_lt_u32 s39, 4
	s_cbranch_scc1 .Lgm_glu_dadv1
	s_mov_b32 s39, 0
	s_add_u32 s4, s38, s52
	s_cmp_lt_u32 s4, s54
	s_cselect_b32 s38, s4, s38
	s_and_b32 s4, s38, 31
	s_lshr_b32 s5, s38, 5
	s_mul_i32 s4, s4, 0x18000
	s_add_u32 s44, s48, s4
	s_addc_u32 s45, s49, 0
	s_mul_i32 s4, s5, 0x10000
	s_add_u32 s46, s50, s4
	s_addc_u32 s47, s51, 0
.Lgm_glu_dadv1:
	s_add_u32 s41, s41, 0xa000
	s_sub_u32 s4, s41, 0x1e000
	s_cmp_ge_u32 s41, 0x1e000
	s_cselect_b32 s41, s4, s41
	s_add_u32 m0, s41, 0x0
	s_nop 0
	global_load_lds_dwordx4 v180, s[44:45]
	s_add_u32 m0, s41, 0x1000
	s_nop 0
	global_load_lds_dwordx4 v181, s[44:45]
	s_add_u32 m0, s41, 0x2000
	s_nop 0
	global_load_lds_dwordx4 v182, s[44:45]
	s_add_u32 m0, s41, 0x3000
	s_nop 0
	global_load_lds_dwordx4 v183, s[44:45]
	s_add_u32 m0, s41, 0x4000
	s_nop 0
	global_load_lds_dwordx4 v184, s[44:45]
	s_add_u32 m0, s41, 0x5000
	s_nop 0
	global_load_lds_dwordx4 v185, s[44:45]
	s_add_u32 m0, s41, 0x6000
	s_nop 0
	global_load_lds_dwordx4 v180, s[46:47]
	s_add_u32 m0, s41, 0x7000
	s_nop 0
	global_load_lds_dwordx4 v181, s[46:47]
	s_add_u32 m0, s41, 0x8000
	s_nop 0
	global_load_lds_dwordx4 v182, s[46:47]
	s_add_u32 m0, s41, 0x9000
	s_nop 0
	global_load_lds_dwordx4 v183, s[46:47]
	s_add_u32 s39, s39, 1
	s_add_u32 s44, s44, 0x80
	s_addc_u32 s45, s45, 0
	s_add_u32 s46, s46, 0x80
	s_addc_u32 s47, s47, 0
	s_cmp_lt_u32 s39, 4
	s_cbranch_scc1 .Lgm_glu_dadv2
	s_mov_b32 s39, 0
	s_add_u32 s4, s38, s52
	s_cmp_lt_u32 s4, s54
	s_cselect_b32 s38, s4, s38
	s_and_b32 s4, s38, 31
	s_lshr_b32 s5, s38, 5
	s_mul_i32 s4, s4, 0x18000
	s_add_u32 s44, s48, s4
	s_addc_u32 s45, s49, 0
	s_mul_i32 s4, s5, 0x10000
	s_add_u32 s46, s50, s4
	s_addc_u32 s47, s51, 0

.Lgm_glu_ld_loop:
	s_barrier
	s_add_u32 m0, s41, 0x0
	s_nop 0
	global_load_lds_dwordx4 v180, s[44:45]
	s_add_u32 m0, s41, 0x1000
	s_nop 0
	global_load_lds_dwordx4 v181, s[44:45]
	s_add_u32 m0, s41, 0x2000
	s_nop 0
	global_load_lds_dwordx4 v182, s[44:45]
	s_add_u32 m0, s41, 0x3000
	s_nop 0
	global_load_lds_dwordx4 v183, s[44:45]
	s_add_u32 m0, s41, 0x4000
	s_nop 0
	global_load_lds_dwordx4 v184, s[44:45]
	s_add_u32 m0, s41, 0x5000
	s_nop 0
	global_load_lds_dwordx4 v185, s[44:45]
	s_add_u32 m0, s41, 0x6000
	s_nop 0
	global_load_lds_dwordx4 v180, s[46:47]
	s_add_u32 m0, s41, 0x7000
	s_nop 0
	global_load_lds_dwordx4 v181, s[46:47]
	s_add_u32 m0, s41, 0x8000
	s_nop 0
	global_load_lds_dwordx4 v182, s[46:47]
	s_add_u32 m0, s41, 0x9000
	s_nop 0
	global_load_lds_dwordx4 v183, s[46:47]
	s_add_u32 s39, s39, 1
	s_add_u32 s44, s44, 0x80
	s_addc_u32 s45, s45, 0
	s_add_u32 s46, s46, 0x80
	s_addc_u32 s47, s47, 0
	s_cmp_lt_u32 s39, 4
	s_cbranch_scc1 .Lgm_glu_dadv3
	s_mov_b32 s39, 0
	s_add_u32 s4, s38, s52
	s_cmp_lt_u32 s4, s54
	s_cselect_b32 s38, s4, s38
	s_and_b32 s4, s38, 31
	s_lshr_b32 s5, s38, 5
	s_mul_i32 s4, s4, 0x18000
	s_add_u32 s44, s48, s4
	s_addc_u32 s45, s49, 0
	s_mul_i32 s4, s5, 0x10000
	s_add_u32 s46, s50, s4
	s_addc_u32 s47, s51, 0

.Lgm_glu_join:
	s_waitcnt lgkmcnt(13)
	v_mfma_f32_16x16x32_bf16 v[4:7], v[100:103], v[124:127], v[4:7]
	v_mfma_f32_16x16x32_bf16 v[20:23], v[104:107], v[124:127], v[20:23]
	v_mfma_f32_16x16x32_bf16 v[36:39], v[108:111], v[124:127], v[36:39]
	v_mfma_f32_16x16x32_bf16 v[52:55], v[112:115], v[124:127], v[52:55]
	v_mfma_f32_16x16x32_bf16 v[68:71], v[116:119], v[124:127], v[68:71]
	v_mfma_f32_16x16x32_bf16 v[84:87], v[120:123], v[124:127], v[84:87]
	s_waitcnt lgkmcnt(12)
	v_mfma_f32_16x16x32_bf16 v[8:11], v[100:103], v[128:131], v[8:11]
	v_mfma_f32_16x16x32_bf16 v[24:27], v[104:107], v[128:131], v[24:27]
	v_mfma_f32_16x16x32_bf16 v[40:43], v[108:111], v[128:131], v[40:43]
	v_mfma_f32_16x16x32_bf16 v[56:59], v[112:115], v[128:131], v[56:59]
	v_mfma_f32_16x16x32_bf16 v[72:75], v[116:119], v[128:131], v[72:75]
	v_mfma_f32_16x16x32_bf16 v[88:91], v[120:123], v[128:131], v[88:91]
	s_waitcnt lgkmcnt(11)
	v_mfma_f32_16x16x32_bf16 v[12:15], v[100:103], v[132:135], v[12:15]
	v_mfma_f32_16x16x32_bf16 v[28:31], v[104:107], v[132:135], v[28:31]
	v_mfma_f32_16x16x32_bf16 v[44:47], v[108:111], v[132:135], v[44:47]
	v_mfma_f32_16x16x32_bf16 v[60:63], v[112:115], v[132:135], v[60:63]
	v_mfma_f32_16x16x32_bf16 v[76:79], v[116:119], v[132:135], v[76:79]
	v_mfma_f32_16x16x32_bf16 v[92:95], v[120:123], v[132:135], v[92:95]
	s_waitcnt lgkmcnt(10)
	v_mfma_f32_16x16x32_bf16 v[16:19], v[100:103], v[136:139], v[16:19]
	v_mfma_f32_16x16x32_bf16 v[32:35], v[104:107], v[136:139], v[32:35]
	v_mfma_f32_16x16x32_bf16 v[48:51], v[108:111], v[136:139], v[48:51]
	v_mfma_f32_16x16x32_bf16 v[64:67], v[112:115], v[136:139], v[64:67]
	v_mfma_f32_16x16x32_bf16 v[80:83], v[116:119], v[136:139], v[80:83]
	v_mfma_f32_16x16x32_bf16 v[96:99], v[120:123], v[136:139], v[96:99]
	s_waitcnt lgkmcnt(0)
	s_add_u32 s34, s34, 1
	s_add_u32 s31, s31, 1
	s_cmp_lt_u32 s34, 4
	s_cbranch_scc1 .Lgm_glu_rot
	v_mfma_f32_16x16x32_bf16 v[4:7], v[140:143], v[164:167], v[4:7]
	v_mfma_f32_16x16x32_bf16 v[20:23], v[144:147], v[164:167], v[20:23]
	v_mfma_f32_16x16x32_bf16 v[36:39], v[148:151], v[164:167], v[36:39]
	v_mfma_f32_16x16x32_bf16 v[52:55], v[152:155], v[164:167], v[52:55]
	v_mfma_f32_16x16x32_bf16 v[68:71], v[156:159], v[164:167], v[68:71]
	v_mfma_f32_16x16x32_bf16 v[84:87], v[160:163], v[164:167], v[84:87]
	v_mfma_f32_16x16x32_bf16 v[8:11], v[140:143], v[168:171], v[8:11]
	v_mfma_f32_16x16x32_bf16 v[24:27], v[144:147], v[168:171], v[24:27]
	v_mfma_f32_16x16x32_bf16 v[40:43], v[148:151], v[168:171], v[40:43]
	v_mfma_f32_16x16x32_bf16 v[56:59], v[152:155], v[168:171], v[56:59]
	v_mfma_f32_16x16x32_bf16 v[72:75], v[156:159], v[168:171], v[72:75]
	v_mfma_f32_16x16x32_bf16 v[88:91], v[160:163], v[168:171], v[88:91]
	v_mfma_f32_16x16x32_bf16 v[12:15], v[140:143], v[172:175], v[12:15]
	v_mfma_f32_16x16x32_bf16 v[28:31], v[144:147], v[172:175], v[28:31]
	v_mfma_f32_16x16x32_bf16 v[44:47], v[148:151], v[172:175], v[44:47]
	v_mfma_f32_16x16x32_bf16 v[60:63], v[152:155], v[172:175], v[60:63]
	v_mfma_f32_16x16x32_bf16 v[76:79], v[156:159], v[172:175], v[76:79]
	v_mfma_f32_16x16x32_bf16 v[92:95], v[160:163], v[172:175], v[92:95]
	v_mfma_f32_16x16x32_bf16 v[16:19], v[140:143], v[176:179], v[16:19]
	v_mfma_f32_16x16x32_bf16 v[32:35], v[144:147], v[176:179], v[32:35]
	v_mfma_f32_16x16x32_bf16 v[48:51], v[148:151], v[176:179], v[48:51]
	v_mfma_f32_16x16x32_bf16 v[64:67], v[152:155], v[176:179], v[64:67]
	v_mfma_f32_16x16x32_bf16 v[80:83], v[156:159], v[176:179], v[80:83]
	v_mfma_f32_16x16x32_bf16 v[96:99], v[160:163], v[176:179], v[96:99]
	s_and_b32 s6, s35, 31
	s_lshr_b32 s7, s35, 5
	s_mul_i32 s6, s6, 192
	s_lshl_b32 s7, s7, 7
	s_nop 7
	s_mul_i32 s4, s6, 0x800
	s_lshl_b32 s5, s7, 1
	s_add_u32 s4, s4, s5
	v_add_u32_e32 v197, s4, v205
	v_lshl_add_u32 v195, s7, 2, v191
	global_load_dwordx4 v[148:151], v195, s[100:101]
	s_lshl_b32 s4, s6, 9
	s_add_u32 s4, s4, s5
	v_lshlrev_b32_e32 v194, 9, v190
	v_lshl_add_u32 v194, v193, 1, v194
	v_add_u32_e32 v194, s4, v194
	global_load_dwordx2 v[100:101], v194, s[98:99]
	v_add_u32_e32 v194, 0x800, v194
	global_load_dwordx2 v[102:103], v194, s[98:99]
	v_add_u32_e32 v194, 0x800, v194
	global_load_dwordx2 v[104:105], v194, s[98:99]
	v_add_u32_e32 v194, 0x800, v194
	global_load_dwordx2 v[106:107], v194, s[98:99]
	v_add_u32_e32 v194, 0x800, v194
	global_load_dwordx2 v[108:109], v194, s[98:99]
	v_add_u32_e32 v194, 0x800, v194
	global_load_dwordx2 v[110:111], v194, s[98:99]
	v_add_u32_e32 v194, 0x800, v194
	global_load_dwordx2 v[112:113], v194, s[98:99]
	v_add_u32_e32 v194, 0x800, v194
	global_load_dwordx2 v[114:115], v194, s[98:99]
	v_add_u32_e32 v194, 0x800, v194
	global_load_dwordx2 v[116:117], v194, s[98:99]
	v_add_u32_e32 v194, 0x800, v194
	global_load_dwordx2 v[118:119], v194, s[98:99]
	v_add_u32_e32 v194, 0x800, v194
	global_load_dwordx2 v[120:121], v194, s[98:99]
	v_add_u32_e32 v194, 0x800, v194
	global_load_dwordx2 v[122:123], v194, s[98:99]
	v_add_u32_e32 v194, 0x800, v194
	global_load_dwordx2 v[124:125], v194, s[98:99]
	v_add_u32_e32 v194, 0x800, v194
	global_load_dwordx2 v[126:127], v194, s[98:99]
	v_add_u32_e32 v194, 0x800, v194
	global_load_dwordx2 v[128:129], v194, s[98:99]
	v_add_u32_e32 v194, 0x800, v194
	global_load_dwordx2 v[130:131], v194, s[98:99]
	v_add_u32_e32 v194, 0x800, v194
	global_load_dwordx2 v[132:133], v194, s[98:99]
	v_add_u32_e32 v194, 0x800, v194
	global_load_dwordx2 v[134:135], v194, s[98:99]
	v_add_u32_e32 v194, 0x800, v194
	global_load_dwordx2 v[136:137], v194, s[98:99]
	v_add_u32_e32 v194, 0x800, v194
	global_load_dwordx2 v[138:139], v194, s[98:99]
	v_add_u32_e32 v194, 0x800, v194
	global_load_dwordx2 v[140:141], v194, s[98:99]
	v_add_u32_e32 v194, 0x800, v194
	global_load_dwordx2 v[142:143], v194, s[98:99]
	v_add_u32_e32 v194, 0x800, v194
	global_load_dwordx2 v[144:145], v194, s[98:99]
	v_add_u32_e32 v194, 0x800, v194
	global_load_dwordx2 v[146:147], v194, s[98:99]
	s_mov_b32 s4, 0

.LBB0_668:
	s_and_b64 vcc, exec, s[38:39]
	s_cbranch_vccz .LBB0_674
	s_branch .LBB0_674

.LBB0_692:
	v_readlane_b32 s4, v236, 39
	v_readlane_b32 s5, v236, 40
	s_barrier
	s_and_saveexec_b64 s[38:39], s[4:5]
	s_cbranch_execz .LBB0_645
	s_mov_b64 s[48:49], exec
	v_mbcnt_lo_u32_b32 v0, s48, 0
	v_mbcnt_hi_u32_b32 v0, s49, v0
	v_cmp_eq_u32_e32 vcc, 0, v0
	s_and_saveexec_b64 s[46:47], vcc
	s_cbranch_execz .LBB0_644
	s_bcnt1_i32_b64 s35, s[48:49]
	v_readlane_b32 s4, v235, 56
	v_mov_b32_e32 v1, s35
	v_readlane_b32 s5, v235, 57
	s_nop 4
	global_atomic_add v1, v2, v1, s[4:5] sc0
	s_branch .LBB0_644
.LBB0_704:
	s_mov_b64 s[38:39], 0
	s_movk_i32 s62, 0xfff
	s_movk_i32 s60, 0x17ff
